# MFMA issue order inside each 8-MFMA group changed to A-operand-major with serpentine B (operand reuse between consecutive MFMAs), 7 GEMM loops, on top of v13
# baseline (speedup 1.0000x reference)
; #define PG8_STAGE(bufoff, gbase, voff) do { _Pragma("unroll") for (int _i = 0; _i < 2; ++_i) \
;         __builtin_amdgcn_global_load_lds((const unsigned*)((const char*)(gbase) + (voff)[_i]), (LAS unsigned*)(lds + (bufoff) + ldsw + _i * 8192), 16, 0, 0); } while (0)
; #define PG8_LDA(dst, b, h) do { _Pragma("unroll") for (int m = 0; m < 4; ++m) _Pragma("unroll") for (int k = 0; k < 2; ++k) dst[m][k] = *(const LAS bf16x8*)(lds + PG8_SA(b, h) + aoff + m * 2048 + k * 1024); } while (0)
; #define PG8_LDB(dst, b, h) do { _Pragma("unroll") for (int n = 0; n < 2; ++n) _Pragma("unroll") for (int k = 0; k < 2; ++k) dst[n][k] = *(const LAS bf16x8*)(lds + PG8_SB(b, h) + boff + n * 2048 + k * 1024); } while (0)
; #define PG8_MMA(ai, bj, At, Bt) do { __builtin_amdgcn_s_setprio(1); _Pragma("unroll") for (int m = 0; m < 4; ++m) _Pragma("unroll") for (int n = 0; n < 2; ++n) _Pragma("unroll") for (int k = 0; k < 2; ++k) \
;         acc[ai][bj][m][n] = __builtin_amdgcn_mfma_f32_16x16x32_bf16(Bt[n][k], At[m][k], acc[ai][bj][m][n], 0, 0, 0); __builtin_amdgcn_s_setprio(0); } while (0)
; #define PG8_WAIT_V(n) asm volatile("s_waitcnt vmcnt(" #n ")" ::: "memory")
; #define PG8_WAIT_L(n) asm volatile("s_waitcnt lgkmcnt(" #n ")" ::: "memory")
; #define PG8_BAR __builtin_amdgcn_s_barrier()
; #define PG8_SCHED __builtin_amdgcn_sched_barrier(0)
; template <class Epi, bool ALIGN_EPI>
; __device__ __forceinline__ void gemm_phase(LAS unsigned char* lds, const Gemm g, const StaticOrder& S, const Epi& E) {
;     ...
;             const bool last = (t == nt - 2);
;             const char* a1 = cA + (size_t)(t + 1) * kstep;
;             const char* a2 = last ? nA : cA + (size_t)(t + 2) * kstep; const char* b2 = last ? nB : cB + (size_t)(t + 2) * kstep;
;             const char* a3 = a2 + kstep; const char* b3 = b2 + kstep;
;             PG8_LDB(B0, 0, 0); PG8_LDB(B1, 0, 1); PG8_SCHED; PG8_LDA(At, 0, 0); PG8_STAGE(PG8_SA(1, 1), a1 + hstepA, voffA);
;             PG8_WAIT_V(8); PG8_WAIT_L(0); PG8_BAR; PG8_MMA(0, 0, At, B0); PG8_MMA(0, 1, At, B1); PG8_BAR; PG8_SCHED;
;             PG8_LDA(At, 0, 1); PG8_STAGE(PG8_SB(0, 0), b2, voffB); PG8_STAGE(PG8_SB(0, 1), b2 + hstepB, voffB); PG8_STAGE(PG8_SA(0, 0), a2, voffA);
;             PG8_WAIT_V(8); PG8_WAIT_L(0); PG8_BAR; PG8_MMA(1, 0, At, B0); PG8_MMA(1, 1, At, B1); PG8_BAR; PG8_SCHED;
.LBB0_121:
	ds_read_b128 v[144:147], v152
	ds_read_b128 v[156:159], v152 offset:1024
	ds_read_b128 v[160:163], v152 offset:2048
	ds_read_b128 v[168:171], v152 offset:3072
	ds_read_b128 v[172:175], v153
	ds_read_b128 v[176:179], v153 offset:1024
	ds_read_b128 v[180:183], v153 offset:2048
	ds_read_b128 v[184:187], v153 offset:3072
	s_add_u32 s26, s24, 0xfff80080
	s_addc_u32 s27, s25, -1
	s_cmp_eq_u32 s55, 28
	s_cselect_b32 s29, s17, s27
	s_cselect_b32 s28, s51, s26
	s_cselect_b32 s27, s15, s54
	s_cselect_b32 s26, s52, s53
	v_lshl_add_u64 v[164:165], s[24:25], 0, v[138:139]
	s_add_i32 m0, s23, 0xc000
	ds_read_b128 v[188:191], v154
	ds_read_b128 v[192:195], v154 offset:1024
	ds_read_b128 v[196:199], v154 offset:2048
	ds_read_b128 v[200:203], v154 offset:3072
	ds_read_b128 v[204:207], v154 offset:4096
	ds_read_b128 v[208:211], v154 offset:5120
	ds_read_b128 v[212:215], v154 offset:6144
	ds_read_b128 v[216:219], v154 offset:7168
	global_load_lds_dwordx4 v[164:165], off
	v_lshl_add_u64 v[164:165], s[24:25], 0, v[136:137]
	s_add_i32 m0, s23, 0xe000
	s_nop 0
	global_load_lds_dwordx4 v[164:165], off
	s_waitcnt vmcnt(8)
	s_waitcnt lgkmcnt(0)
	s_setprio 1
	s_barrier
	v_mfma_f32_16x16x32_bf16 v[124:127], v[144:147], v[188:191], v[124:127]
	v_mfma_f32_16x16x32_bf16 v[108:111], v[144:147], v[196:199], v[108:111]
	v_mfma_f32_16x16x32_bf16 v[92:95], v[144:147], v[204:207], v[92:95]
	v_mfma_f32_16x16x32_bf16 v[76:79], v[144:147], v[212:215], v[76:79]
	v_mfma_f32_16x16x32_bf16 v[72:75], v[160:163], v[212:215], v[72:75]
	v_mfma_f32_16x16x32_bf16 v[88:91], v[160:163], v[204:207], v[88:91]
	v_mfma_f32_16x16x32_bf16 v[104:107], v[160:163], v[196:199], v[104:107]
	v_mfma_f32_16x16x32_bf16 v[120:123], v[160:163], v[188:191], v[120:123]
	v_mfma_f32_16x16x32_bf16 v[124:127], v[156:159], v[192:195], v[124:127]
	v_mfma_f32_16x16x32_bf16 v[108:111], v[156:159], v[200:203], v[108:111]
	v_mfma_f32_16x16x32_bf16 v[92:95], v[156:159], v[208:211], v[92:95]
	v_mfma_f32_16x16x32_bf16 v[76:79], v[156:159], v[216:219], v[76:79]
	v_mfma_f32_16x16x32_bf16 v[72:75], v[168:171], v[216:219], v[72:75]
	v_mfma_f32_16x16x32_bf16 v[88:91], v[168:171], v[208:211], v[88:91]
	v_mfma_f32_16x16x32_bf16 v[104:107], v[168:171], v[200:203], v[104:107]
	v_mfma_f32_16x16x32_bf16 v[120:123], v[168:171], v[192:195], v[120:123]
	s_setprio 0
	s_setprio 1
	v_mfma_f32_16x16x32_bf16 v[116:119], v[172:175], v[188:191], v[116:119]
	v_mfma_f32_16x16x32_bf16 v[100:103], v[172:175], v[196:199], v[100:103]
	v_mfma_f32_16x16x32_bf16 v[84:87], v[172:175], v[204:207], v[84:87]
	v_mfma_f32_16x16x32_bf16 v[68:71], v[172:175], v[212:215], v[68:71]
	v_mfma_f32_16x16x32_bf16 v[64:67], v[180:183], v[212:215], v[64:67]
	v_mfma_f32_16x16x32_bf16 v[80:83], v[180:183], v[204:207], v[80:83]
	v_mfma_f32_16x16x32_bf16 v[96:99], v[180:183], v[196:199], v[96:99]
	v_mfma_f32_16x16x32_bf16 v[112:115], v[180:183], v[188:191], v[112:115]
	v_mfma_f32_16x16x32_bf16 v[116:119], v[176:179], v[192:195], v[116:119]
	v_mfma_f32_16x16x32_bf16 v[100:103], v[176:179], v[200:203], v[100:103]
	v_mfma_f32_16x16x32_bf16 v[84:87], v[176:179], v[208:211], v[84:87]
	v_mfma_f32_16x16x32_bf16 v[68:71], v[176:179], v[216:219], v[68:71]
	v_mfma_f32_16x16x32_bf16 v[64:67], v[184:187], v[216:219], v[64:67]
	v_mfma_f32_16x16x32_bf16 v[80:83], v[184:187], v[208:211], v[80:83]
	v_mfma_f32_16x16x32_bf16 v[96:99], v[184:187], v[200:203], v[96:99]
	v_mfma_f32_16x16x32_bf16 v[112:115], v[184:187], v[192:195], v[112:115]
	s_barrier
	s_setprio 0
	s_add_i32 s56, s46, s35
	v_lshl_add_u64 v[164:165], s[26:27], 0, v[132:133]
	s_mov_b32 m0, s56
	ds_read_b128 v[188:191], v154 offset:16384
	ds_read_b128 v[192:195], v154 offset:17408
	ds_read_b128 v[196:199], v154 offset:18432
	ds_read_b128 v[200:203], v154 offset:19456
	ds_read_b128 v[204:207], v154 offset:20480
	ds_read_b128 v[208:211], v154 offset:21504
	ds_read_b128 v[212:215], v154 offset:22528
	ds_read_b128 v[216:219], v154 offset:23552
	global_load_lds_dwordx4 v[164:165], off
	s_add_i32 m0, s56, 0x2000
	s_add_u32 s56, s26, 0x80000
	v_lshl_add_u64 v[220:221], s[26:27], 0, v[128:129]
	s_addc_u32 s57, s27, 0
	s_add_i32 s58, s47, s35
	global_load_lds_dwordx4 v[220:221], off
	v_lshl_add_u64 v[222:223], s[56:57], 0, v[132:133]
	s_mov_b32 m0, s58
	v_lshl_add_u64 v[224:225], s[28:29], 0, v[130:131]
	global_load_lds_dwordx4 v[222:223], off
	v_lshl_add_u64 v[222:223], s[56:57], 0, v[128:129]
	s_add_i32 m0, s58, 0x2000
	s_nop 0
	global_load_lds_dwordx4 v[222:223], off
	v_lshl_add_u64 v[222:223], s[28:29], 0, v[134:135]
	s_mov_b32 m0, s23
	s_nop 0
	global_load_lds_dwordx4 v[222:223], off
	s_mov_b32 m0, s38
	s_nop 0
	global_load_lds_dwordx4 v[224:225], off
	s_waitcnt vmcnt(8)
	s_waitcnt lgkmcnt(0)
	s_setprio 1
	s_barrier
; #define PG8_STAGE(bufoff, gbase, voff) do { _Pragma("unroll") for (int _i = 0; _i < 2; ++_i) \
;         __builtin_amdgcn_global_load_lds((const unsigned*)((const char*)(gbase) + (voff)[_i]), (LAS unsigned*)(lds + (bufoff) + ldsw + _i * 8192), 16, 0, 0); } while (0)
; #define PG8_LDA(dst, b, h) do { _Pragma("unroll") for (int m = 0; m < 4; ++m) _Pragma("unroll") for (int k = 0; k < 2; ++k) dst[m][k] = *(const LAS bf16x8*)(lds + PG8_SA(b, h) + aoff + m * 2048 + k * 1024); } while (0)
; #define PG8_LDB(dst, b, h) do { _Pragma("unroll") for (int n = 0; n < 2; ++n) _Pragma("unroll") for (int k = 0; k < 2; ++k) dst[n][k] = *(const LAS bf16x8*)(lds + PG8_SB(b, h) + boff + n * 2048 + k * 1024); } while (0)
; #define PG8_MMA(ai, bj, At, Bt) do { __builtin_amdgcn_s_setprio(1); _Pragma("unroll") for (int m = 0; m < 4; ++m) _Pragma("unroll") for (int n = 0; n < 2; ++n) _Pragma("unroll") for (int k = 0; k < 2; ++k) \
;         acc[ai][bj][m][n] = __builtin_amdgcn_mfma_f32_16x16x32_bf16(Bt[n][k], At[m][k], acc[ai][bj][m][n], 0, 0, 0); __builtin_amdgcn_s_setprio(0); } while (0)
; #define PG8_WAIT_V(n) asm volatile("s_waitcnt vmcnt(" #n ")" ::: "memory")
; #define PG8_WAIT_L(n) asm volatile("s_waitcnt lgkmcnt(" #n ")" ::: "memory")
; #define PG8_BAR __builtin_amdgcn_s_barrier()
; #define PG8_SCHED __builtin_amdgcn_sched_barrier(0)
; template <class Epi, bool ALIGN_EPI>
; __device__ __forceinline__ void gemm_phase(LAS unsigned char* lds, const Gemm g, const StaticOrder& S, const Epi& E) {
;     ...
;             PG8_WAIT_V(8); PG8_WAIT_L(0); PG8_BAR; PG8_MMA(1, 0, At, B0); PG8_MMA(1, 1, At, B1); PG8_BAR; PG8_SCHED;
;             PG8_LDB(B0, 1, 0); PG8_LDB(B1, 1, 1); PG8_SCHED; PG8_LDA(At, 1, 0); PG8_STAGE(PG8_SA(0, 1), a2 + hstepA, voffA);
;             PG8_WAIT_V(8); PG8_WAIT_L(0); PG8_BAR; PG8_MMA(0, 0, At, B0); PG8_MMA(0, 1, At, B1); PG8_BAR; PG8_SCHED;
;             PG8_LDA(At, 1, 1); PG8_STAGE(PG8_SB(1, 0), b3, voffB); PG8_STAGE(PG8_SB(1, 1), b3 + hstepB, voffB); PG8_STAGE(PG8_SA(1, 0), a3, voffA);
	v_mfma_f32_16x16x32_bf16 v[60:63], v[144:147], v[188:191], v[60:63]
	v_mfma_f32_16x16x32_bf16 v[44:47], v[144:147], v[196:199], v[44:47]
	v_mfma_f32_16x16x32_bf16 v[28:31], v[144:147], v[204:207], v[28:31]
	v_mfma_f32_16x16x32_bf16 v[12:15], v[144:147], v[212:215], v[12:15]
	v_mfma_f32_16x16x32_bf16 v[8:11], v[160:163], v[212:215], v[8:11]
	v_mfma_f32_16x16x32_bf16 v[24:27], v[160:163], v[204:207], v[24:27]
	v_mfma_f32_16x16x32_bf16 v[40:43], v[160:163], v[196:199], v[40:43]
	v_mfma_f32_16x16x32_bf16 v[56:59], v[160:163], v[188:191], v[56:59]
	v_mfma_f32_16x16x32_bf16 v[60:63], v[156:159], v[192:195], v[60:63]
	v_mfma_f32_16x16x32_bf16 v[44:47], v[156:159], v[200:203], v[44:47]
	v_mfma_f32_16x16x32_bf16 v[28:31], v[156:159], v[208:211], v[28:31]
	v_mfma_f32_16x16x32_bf16 v[12:15], v[156:159], v[216:219], v[12:15]
	v_mfma_f32_16x16x32_bf16 v[8:11], v[168:171], v[216:219], v[8:11]
	v_mfma_f32_16x16x32_bf16 v[24:27], v[168:171], v[208:211], v[24:27]
	v_mfma_f32_16x16x32_bf16 v[40:43], v[168:171], v[200:203], v[40:43]
	v_mfma_f32_16x16x32_bf16 v[56:59], v[168:171], v[192:195], v[56:59]
	s_setprio 0
	s_setprio 1
	v_mfma_f32_16x16x32_bf16 v[52:55], v[172:175], v[188:191], v[52:55]
	v_mfma_f32_16x16x32_bf16 v[36:39], v[172:175], v[196:199], v[36:39]
	v_mfma_f32_16x16x32_bf16 v[20:23], v[172:175], v[204:207], v[20:23]
	v_mfma_f32_16x16x32_bf16 v[4:7], v[172:175], v[212:215], v[4:7]
	v_mfma_f32_16x16x32_bf16 v[0:3], v[180:183], v[212:215], v[0:3]
	v_mfma_f32_16x16x32_bf16 v[16:19], v[180:183], v[204:207], v[16:19]
	v_mfma_f32_16x16x32_bf16 v[32:35], v[180:183], v[196:199], v[32:35]
	v_mfma_f32_16x16x32_bf16 v[48:51], v[180:183], v[188:191], v[48:51]
	v_mfma_f32_16x16x32_bf16 v[52:55], v[176:179], v[192:195], v[52:55]
	v_mfma_f32_16x16x32_bf16 v[36:39], v[176:179], v[200:203], v[36:39]
	v_mfma_f32_16x16x32_bf16 v[20:23], v[176:179], v[208:211], v[20:23]
	v_mfma_f32_16x16x32_bf16 v[4:7], v[176:179], v[216:219], v[4:7]
	v_mfma_f32_16x16x32_bf16 v[0:3], v[184:187], v[216:219], v[0:3]
	v_mfma_f32_16x16x32_bf16 v[16:19], v[184:187], v[208:211], v[16:19]
	v_mfma_f32_16x16x32_bf16 v[32:35], v[184:187], v[200:203], v[32:35]
	v_mfma_f32_16x16x32_bf16 v[48:51], v[184:187], v[192:195], v[48:51]
	s_barrier
	s_setprio 0
	s_add_i32 s56, 0, 0x18000
	v_add_u32_e32 v155, s56, v150
	s_add_i32 s57, 0, 0x1c000
	ds_read_b128 v[144:147], v155
	ds_read_b128 v[156:159], v155 offset:1024
	ds_read_b128 v[160:163], v155 offset:2048
	ds_read_b128 v[168:171], v155 offset:3072
	v_add_u32_e32 v155, s57, v150
	ds_read_b128 v[172:175], v155
	ds_read_b128 v[176:179], v155 offset:1024
	ds_read_b128 v[180:183], v155 offset:2048
	ds_read_b128 v[184:187], v155 offset:3072
	s_add_u32 s28, s28, 0x80000
	s_addc_u32 s29, s29, 0
	s_mov_b32 m0, s39
	v_lshl_add_u64 v[226:227], s[28:29], 0, v[134:135]
	ds_read_b128 v[188:191], v154 offset:32768
	ds_read_b128 v[192:195], v154 offset:33792
	ds_read_b128 v[196:199], v154 offset:34816
	ds_read_b128 v[200:203], v154 offset:35840
	ds_read_b128 v[204:207], v154 offset:36864
	ds_read_b128 v[208:211], v154 offset:37888
	ds_read_b128 v[212:215], v154 offset:38912
	ds_read_b128 v[216:219], v154 offset:39936
	global_load_lds_dwordx4 v[226:227], off
	v_lshl_add_u64 v[226:227], s[28:29], 0, v[130:131]
	s_mov_b32 m0, s40
	s_nop 0
	global_load_lds_dwordx4 v[226:227], off
	s_waitcnt vmcnt(8)
	s_waitcnt lgkmcnt(0)
	s_setprio 1
	s_barrier
	v_mfma_f32_16x16x32_bf16 v[124:127], v[144:147], v[188:191], v[124:127]
	v_mfma_f32_16x16x32_bf16 v[108:111], v[144:147], v[196:199], v[108:111]
	v_mfma_f32_16x16x32_bf16 v[92:95], v[144:147], v[204:207], v[92:95]
	v_mfma_f32_16x16x32_bf16 v[76:79], v[144:147], v[212:215], v[76:79]
	v_mfma_f32_16x16x32_bf16 v[72:75], v[160:163], v[212:215], v[72:75]
	v_mfma_f32_16x16x32_bf16 v[88:91], v[160:163], v[204:207], v[88:91]
	v_mfma_f32_16x16x32_bf16 v[104:107], v[160:163], v[196:199], v[104:107]
	v_mfma_f32_16x16x32_bf16 v[120:123], v[160:163], v[188:191], v[120:123]
	v_mfma_f32_16x16x32_bf16 v[124:127], v[156:159], v[192:195], v[124:127]
	v_mfma_f32_16x16x32_bf16 v[108:111], v[156:159], v[200:203], v[108:111]
	v_mfma_f32_16x16x32_bf16 v[92:95], v[156:159], v[208:211], v[92:95]
	v_mfma_f32_16x16x32_bf16 v[76:79], v[156:159], v[216:219], v[76:79]
	v_mfma_f32_16x16x32_bf16 v[72:75], v[168:171], v[216:219], v[72:75]
	v_mfma_f32_16x16x32_bf16 v[88:91], v[168:171], v[208:211], v[88:91]
	v_mfma_f32_16x16x32_bf16 v[104:107], v[168:171], v[200:203], v[104:107]
	v_mfma_f32_16x16x32_bf16 v[120:123], v[168:171], v[192:195], v[120:123]
	s_setprio 0
	s_setprio 1
	v_mfma_f32_16x16x32_bf16 v[116:119], v[172:175], v[188:191], v[116:119]
	v_mfma_f32_16x16x32_bf16 v[100:103], v[172:175], v[196:199], v[100:103]
	v_mfma_f32_16x16x32_bf16 v[84:87], v[172:175], v[204:207], v[84:87]
	v_mfma_f32_16x16x32_bf16 v[68:71], v[172:175], v[212:215], v[68:71]
	v_mfma_f32_16x16x32_bf16 v[64:67], v[180:183], v[212:215], v[64:67]
	v_mfma_f32_16x16x32_bf16 v[80:83], v[180:183], v[204:207], v[80:83]
	v_mfma_f32_16x16x32_bf16 v[96:99], v[180:183], v[196:199], v[96:99]
	v_mfma_f32_16x16x32_bf16 v[112:115], v[180:183], v[188:191], v[112:115]
	v_mfma_f32_16x16x32_bf16 v[116:119], v[176:179], v[192:195], v[116:119]
	v_mfma_f32_16x16x32_bf16 v[100:103], v[176:179], v[200:203], v[100:103]
	v_mfma_f32_16x16x32_bf16 v[84:87], v[176:179], v[208:211], v[84:87]
	v_mfma_f32_16x16x32_bf16 v[68:71], v[176:179], v[216:219], v[68:71]
	v_mfma_f32_16x16x32_bf16 v[64:67], v[184:187], v[216:219], v[64:67]
	v_mfma_f32_16x16x32_bf16 v[80:83], v[184:187], v[208:211], v[80:83]
	v_mfma_f32_16x16x32_bf16 v[96:99], v[184:187], v[200:203], v[96:99]
	v_mfma_f32_16x16x32_bf16 v[112:115], v[184:187], v[192:195], v[112:115]
	s_barrier
; #define PG8_STAGE(bufoff, gbase, voff) do { _Pragma("unroll") for (int _i = 0; _i < 2; ++_i) \
;         __builtin_amdgcn_global_load_lds((const unsigned*)((const char*)(gbase) + (voff)[_i]), (LAS unsigned*)(lds + (bufoff) + ldsw + _i * 8192), 16, 0, 0); } while (0)
; #define PG8_LDA(dst, b, h) do { _Pragma("unroll") for (int m = 0; m < 4; ++m) _Pragma("unroll") for (int k = 0; k < 2; ++k) dst[m][k] = *(const LAS bf16x8*)(lds + PG8_SA(b, h) + aoff + m * 2048 + k * 1024); } while (0)
; #define PG8_MMA(ai, bj, At, Bt) do { __builtin_amdgcn_s_setprio(1); _Pragma("unroll") for (int m = 0; m < 4; ++m) _Pragma("unroll") for (int n = 0; n < 2; ++n) _Pragma("unroll") for (int k = 0; k < 2; ++k) \
;         acc[ai][bj][m][n] = __builtin_amdgcn_mfma_f32_16x16x32_bf16(Bt[n][k], At[m][k], acc[ai][bj][m][n], 0, 0, 0); __builtin_amdgcn_s_setprio(0); } while (0)
; #define PG8_WAIT_V(n) asm volatile("s_waitcnt vmcnt(" #n ")" ::: "memory")
; #define PG8_WAIT_L(n) asm volatile("s_waitcnt lgkmcnt(" #n ")" ::: "memory")
; #define PG8_BAR __builtin_amdgcn_s_barrier()
; #define PG8_SCHED __builtin_amdgcn_sched_barrier(0)
; template <class Epi, bool ALIGN_EPI>
; __device__ __forceinline__ void gemm_phase(LAS unsigned char* lds, const Gemm g, const StaticOrder& S, const Epi& E) {
;     ...
;             PG8_LDA(At, 1, 1); PG8_STAGE(PG8_SB(1, 0), b3, voffB); PG8_STAGE(PG8_SB(1, 1), b3 + hstepB, voffB); PG8_STAGE(PG8_SA(1, 0), a3, voffA);
;             PG8_WAIT_V(8); PG8_WAIT_L(0); PG8_BAR; PG8_MMA(1, 0, At, B0); PG8_MMA(1, 1, At, B1); PG8_BAR; PG8_SCHED;
;         }
	s_setprio 0
	s_add_i32 s28, s56, s35
	v_lshl_add_u64 v[164:165], v[164:165], 0, s[10:11]
	s_mov_b32 m0, s28
	ds_read_b128 v[188:191], v154 offset:49152
	ds_read_b128 v[192:195], v154 offset:50176
	ds_read_b128 v[196:199], v154 offset:51200
	ds_read_b128 v[200:203], v154 offset:52224
	ds_read_b128 v[204:207], v154 offset:53248
	ds_read_b128 v[208:211], v154 offset:54272
	ds_read_b128 v[212:215], v154 offset:55296
	ds_read_b128 v[216:219], v154 offset:56320
	global_load_lds_dwordx4 v[164:165], off
	s_add_i32 m0, s28, 0x2000
	s_add_u32 s26, s26, 0x80080
	v_lshl_add_u64 v[164:165], v[220:221], 0, s[10:11]
	s_addc_u32 s27, s27, 0
	s_add_i32 s28, s57, s35
	global_load_lds_dwordx4 v[164:165], off
	v_lshl_add_u64 v[164:165], s[26:27], 0, v[132:133]
	s_mov_b32 m0, s28
	s_nop 0
	global_load_lds_dwordx4 v[164:165], off
	v_lshl_add_u64 v[164:165], s[26:27], 0, v[128:129]
	s_add_i32 m0, s28, 0x2000
	s_nop 0
	global_load_lds_dwordx4 v[164:165], off
	v_lshl_add_u64 v[164:165], v[222:223], 0, s[10:11]
	s_mov_b32 m0, s41
	s_nop 0
	global_load_lds_dwordx4 v[164:165], off
	v_lshl_add_u64 v[164:165], v[224:225], 0, s[10:11]
	s_mov_b32 m0, s42
	s_nop 0
	global_load_lds_dwordx4 v[164:165], off
	s_waitcnt vmcnt(8)
	s_waitcnt lgkmcnt(0)
	s_setprio 1
	s_barrier
	v_mfma_f32_16x16x32_bf16 v[60:63], v[144:147], v[188:191], v[60:63]
	v_mfma_f32_16x16x32_bf16 v[44:47], v[144:147], v[196:199], v[44:47]
	v_mfma_f32_16x16x32_bf16 v[28:31], v[144:147], v[204:207], v[28:31]
	v_mfma_f32_16x16x32_bf16 v[12:15], v[144:147], v[212:215], v[12:15]
	v_mfma_f32_16x16x32_bf16 v[8:11], v[160:163], v[212:215], v[8:11]
	v_mfma_f32_16x16x32_bf16 v[24:27], v[160:163], v[204:207], v[24:27]
	v_mfma_f32_16x16x32_bf16 v[40:43], v[160:163], v[196:199], v[40:43]
	v_mfma_f32_16x16x32_bf16 v[56:59], v[160:163], v[188:191], v[56:59]
	v_mfma_f32_16x16x32_bf16 v[60:63], v[156:159], v[192:195], v[60:63]
	v_mfma_f32_16x16x32_bf16 v[44:47], v[156:159], v[200:203], v[44:47]
	v_mfma_f32_16x16x32_bf16 v[28:31], v[156:159], v[208:211], v[28:31]
	v_mfma_f32_16x16x32_bf16 v[12:15], v[156:159], v[216:219], v[12:15]
	v_mfma_f32_16x16x32_bf16 v[8:11], v[168:171], v[216:219], v[8:11]
	v_mfma_f32_16x16x32_bf16 v[24:27], v[168:171], v[208:211], v[24:27]
	v_mfma_f32_16x16x32_bf16 v[40:43], v[168:171], v[200:203], v[40:43]
	v_mfma_f32_16x16x32_bf16 v[56:59], v[168:171], v[192:195], v[56:59]
	s_setprio 0
	s_setprio 1
	v_mfma_f32_16x16x32_bf16 v[52:55], v[172:175], v[188:191], v[52:55]
	v_mfma_f32_16x16x32_bf16 v[36:39], v[172:175], v[196:199], v[36:39]
	v_mfma_f32_16x16x32_bf16 v[20:23], v[172:175], v[204:207], v[20:23]
	v_mfma_f32_16x16x32_bf16 v[4:7], v[172:175], v[212:215], v[4:7]
	v_mfma_f32_16x16x32_bf16 v[0:3], v[180:183], v[212:215], v[0:3]
	v_mfma_f32_16x16x32_bf16 v[16:19], v[180:183], v[204:207], v[16:19]
	v_mfma_f32_16x16x32_bf16 v[32:35], v[180:183], v[196:199], v[32:35]
	v_mfma_f32_16x16x32_bf16 v[48:51], v[180:183], v[188:191], v[48:51]
	v_mfma_f32_16x16x32_bf16 v[52:55], v[176:179], v[192:195], v[52:55]
	v_mfma_f32_16x16x32_bf16 v[36:39], v[176:179], v[200:203], v[36:39]
	v_mfma_f32_16x16x32_bf16 v[20:23], v[176:179], v[208:211], v[20:23]
	v_mfma_f32_16x16x32_bf16 v[4:7], v[176:179], v[216:219], v[4:7]
	v_mfma_f32_16x16x32_bf16 v[0:3], v[184:187], v[216:219], v[0:3]
	v_mfma_f32_16x16x32_bf16 v[16:19], v[184:187], v[208:211], v[16:19]
	v_mfma_f32_16x16x32_bf16 v[32:35], v[184:187], v[200:203], v[32:35]
	v_mfma_f32_16x16x32_bf16 v[48:51], v[184:187], v[192:195], v[48:51]
	s_barrier
	s_setprio 0
	s_add_i32 s55, s55, 2
	s_add_u32 s53, s53, 0x100
	s_addc_u32 s54, s54, 0
	s_add_u32 s24, s24, 0x100
	s_addc_u32 s25, s25, 0
	s_cmp_gt_u32 s55, 29
	s_cbranch_scc0 .LBB0_121
	s_and_b64 vcc, exec, s[12:13]
	s_cbranch_vccz .LBB0_124
	s_barrier

; #define PG8_STAGE(bufoff, gbase, voff) do { _Pragma("unroll") for (int _i = 0; _i < 2; ++_i) \
;         __builtin_amdgcn_global_load_lds((const unsigned*)((const char*)(gbase) + (voff)[_i]), (LAS unsigned*)(lds + (bufoff) + ldsw + _i * 8192), 16, 0, 0); } while (0)
; #define PG8_LDA(dst, b, h) do { _Pragma("unroll") for (int m = 0; m < 4; ++m) _Pragma("unroll") for (int k = 0; k < 2; ++k) dst[m][k] = *(const LAS bf16x8*)(lds + PG8_SA(b, h) + aoff + m * 2048 + k * 1024); } while (0)
; #define PG8_LDB(dst, b, h) do { _Pragma("unroll") for (int n = 0; n < 2; ++n) _Pragma("unroll") for (int k = 0; k < 2; ++k) dst[n][k] = *(const LAS bf16x8*)(lds + PG8_SB(b, h) + boff + n * 2048 + k * 1024); } while (0)
; #define PG8_MMA(ai, bj, At, Bt) do { __builtin_amdgcn_s_setprio(1); _Pragma("unroll") for (int m = 0; m < 4; ++m) _Pragma("unroll") for (int n = 0; n < 2; ++n) _Pragma("unroll") for (int k = 0; k < 2; ++k) \
;         acc[ai][bj][m][n] = __builtin_amdgcn_mfma_f32_16x16x32_bf16(Bt[n][k], At[m][k], acc[ai][bj][m][n], 0, 0, 0); __builtin_amdgcn_s_setprio(0); } while (0)
; #define PG8_WAIT_V(n) asm volatile("s_waitcnt vmcnt(" #n ")" ::: "memory")
; #define PG8_WAIT_L(n) asm volatile("s_waitcnt lgkmcnt(" #n ")" ::: "memory")
; #define PG8_BAR __builtin_amdgcn_s_barrier()
; #define PG8_SCHED __builtin_amdgcn_sched_barrier(0)
; template <class Epi, bool ALIGN_EPI>
; __device__ __forceinline__ void gemm_phase(LAS unsigned char* lds, const Gemm g, const StaticOrder& S, const Epi& E) {
;     ...
;             const bool last = (t == nt - 2);
;             const char* a1 = cA + (size_t)(t + 1) * kstep;
;             const char* a2 = last ? nA : cA + (size_t)(t + 2) * kstep; const char* b2 = last ? nB : cB + (size_t)(t + 2) * kstep;
;             const char* a3 = a2 + kstep; const char* b3 = b2 + kstep;
;             PG8_LDB(B0, 0, 0); PG8_LDB(B1, 0, 1); PG8_SCHED; PG8_LDA(At, 0, 0); PG8_STAGE(PG8_SA(1, 1), a1 + hstepA, voffA);
;             PG8_WAIT_V(8); PG8_WAIT_L(0); PG8_BAR; PG8_MMA(0, 0, At, B0); PG8_MMA(0, 1, At, B1); PG8_BAR; PG8_SCHED;
;             PG8_LDA(At, 0, 1); PG8_STAGE(PG8_SB(0, 0), b2, voffB); PG8_STAGE(PG8_SB(0, 1), b2 + hstepB, voffB); PG8_STAGE(PG8_SA(0, 0), a2, voffA);
;             PG8_WAIT_V(8); PG8_WAIT_L(0); PG8_BAR; PG8_MMA(1, 0, At, B0); PG8_MMA(1, 1, At, B1); PG8_BAR; PG8_SCHED;
.LBB0_309:
	ds_read_b128 v[64:67], v171
	ds_read_b128 v[72:75], v171 offset:1024
	ds_read_b128 v[80:83], v171 offset:2048
	ds_read_b128 v[84:87], v171 offset:3072
	ds_read_b128 v[156:159], v172
	ds_read_b128 v[160:163], v172 offset:1024
	ds_read_b128 v[176:179], v172 offset:2048
	ds_read_b128 v[180:183], v172 offset:3072
	s_add_u32 s4, s30, 0x100
	s_addc_u32 s5, s31, 0
	s_cmpk_eq_i32 s65, 0x54
	s_cselect_b32 s37, s27, s5
	s_cselect_b32 s36, s26, s4
	s_cselect_b32 s35, s29, s64
	s_cselect_b32 s34, s28, s63
	v_lshl_add_u64 v[164:165], s[30:31], 0, v[150:151]
	s_add_i32 m0, s43, 0xc000
	ds_read_b128 v[184:187], v173
	ds_read_b128 v[188:191], v173 offset:1024
	ds_read_b128 v[192:195], v173 offset:2048
	ds_read_b128 v[196:199], v173 offset:3072
	ds_read_b128 v[200:203], v173 offset:4096
	ds_read_b128 v[204:207], v173 offset:5120
	ds_read_b128 v[208:211], v173 offset:6144
	ds_read_b128 v[212:215], v173 offset:7168
	global_load_lds_dwordx4 v[164:165], off
	v_lshl_add_u64 v[164:165], s[30:31], 0, v[148:149]
	s_add_i32 m0, s43, 0xe000
	s_nop 0
	global_load_lds_dwordx4 v[164:165], off
	s_waitcnt vmcnt(8)
	s_waitcnt lgkmcnt(0)
	s_setprio 1
	s_barrier
	v_mfma_f32_16x16x32_bf16 v[140:143], v[64:67], v[184:187], v[140:143]
	v_mfma_f32_16x16x32_bf16 v[124:127], v[64:67], v[192:195], v[124:127]
	v_mfma_f32_16x16x32_bf16 v[108:111], v[64:67], v[200:203], v[108:111]
	v_mfma_f32_16x16x32_bf16 v[92:95], v[64:67], v[208:211], v[92:95]
	v_mfma_f32_16x16x32_bf16 v[88:91], v[80:83], v[208:211], v[88:91]
	v_mfma_f32_16x16x32_bf16 v[104:107], v[80:83], v[200:203], v[104:107]
	v_mfma_f32_16x16x32_bf16 v[120:123], v[80:83], v[192:195], v[120:123]
	v_mfma_f32_16x16x32_bf16 v[136:139], v[80:83], v[184:187], v[136:139]
	v_mfma_f32_16x16x32_bf16 v[140:143], v[72:75], v[188:191], v[140:143]
	v_mfma_f32_16x16x32_bf16 v[124:127], v[72:75], v[196:199], v[124:127]
	v_mfma_f32_16x16x32_bf16 v[108:111], v[72:75], v[204:207], v[108:111]
	v_mfma_f32_16x16x32_bf16 v[92:95], v[72:75], v[212:215], v[92:95]
	v_mfma_f32_16x16x32_bf16 v[88:91], v[84:87], v[212:215], v[88:91]
	v_mfma_f32_16x16x32_bf16 v[104:107], v[84:87], v[204:207], v[104:107]
	v_mfma_f32_16x16x32_bf16 v[120:123], v[84:87], v[196:199], v[120:123]
	v_mfma_f32_16x16x32_bf16 v[136:139], v[84:87], v[188:191], v[136:139]
	s_setprio 0
	s_setprio 1
	v_mfma_f32_16x16x32_bf16 v[132:135], v[156:159], v[184:187], v[132:135]
	v_mfma_f32_16x16x32_bf16 v[116:119], v[156:159], v[192:195], v[116:119]
	v_mfma_f32_16x16x32_bf16 v[100:103], v[156:159], v[200:203], v[100:103]
	v_mfma_f32_16x16x32_bf16 v[76:79], v[156:159], v[208:211], v[76:79]
	v_mfma_f32_16x16x32_bf16 v[68:71], v[176:179], v[208:211], v[68:71]
	v_mfma_f32_16x16x32_bf16 v[96:99], v[176:179], v[200:203], v[96:99]
	v_mfma_f32_16x16x32_bf16 v[112:115], v[176:179], v[192:195], v[112:115]
	v_mfma_f32_16x16x32_bf16 v[128:131], v[176:179], v[184:187], v[128:131]
	v_mfma_f32_16x16x32_bf16 v[132:135], v[160:163], v[188:191], v[132:135]
	v_mfma_f32_16x16x32_bf16 v[116:119], v[160:163], v[196:199], v[116:119]
	v_mfma_f32_16x16x32_bf16 v[100:103], v[160:163], v[204:207], v[100:103]
	v_mfma_f32_16x16x32_bf16 v[76:79], v[160:163], v[212:215], v[76:79]
	v_mfma_f32_16x16x32_bf16 v[68:71], v[180:183], v[212:215], v[68:71]
	v_mfma_f32_16x16x32_bf16 v[96:99], v[180:183], v[204:207], v[96:99]
	v_mfma_f32_16x16x32_bf16 v[112:115], v[180:183], v[196:199], v[112:115]
	v_mfma_f32_16x16x32_bf16 v[128:131], v[180:183], v[188:191], v[128:131]
	s_barrier
	s_setprio 0
	s_add_i32 s30, s56, s42
	v_lshl_add_u64 v[164:165], s[34:35], 0, v[144:145]
	s_mov_b32 m0, s30
	ds_read_b128 v[184:187], v173 offset:16384
	ds_read_b128 v[188:191], v173 offset:17408
	ds_read_b128 v[192:195], v173 offset:18432
	ds_read_b128 v[196:199], v173 offset:19456
	ds_read_b128 v[200:203], v173 offset:20480
	ds_read_b128 v[204:207], v173 offset:21504
	ds_read_b128 v[208:211], v173 offset:22528
	ds_read_b128 v[212:215], v173 offset:23552
	global_load_lds_dwordx4 v[164:165], off
	s_add_i32 m0, s30, 0x2000
	s_add_u32 s30, s34, 0x160000
	v_lshl_add_u64 v[216:217], s[34:35], 0, v[146:147]
	s_addc_u32 s31, s35, 0
	s_add_i32 s66, s57, s42
	global_load_lds_dwordx4 v[216:217], off
	v_lshl_add_u64 v[218:219], s[30:31], 0, v[144:145]
	s_mov_b32 m0, s66
	v_lshl_add_u64 v[220:221], s[36:37], 0, v[146:147]
	global_load_lds_dwordx4 v[218:219], off
	v_lshl_add_u64 v[218:219], s[30:31], 0, v[146:147]
	s_add_i32 m0, s66, 0x2000
	s_nop 0
	global_load_lds_dwordx4 v[218:219], off
	v_lshl_add_u64 v[218:219], s[36:37], 0, v[144:145]
	s_mov_b32 m0, s43
	s_nop 0
	global_load_lds_dwordx4 v[218:219], off
	s_mov_b32 m0, s44
	s_nop 0
	global_load_lds_dwordx4 v[220:221], off
	s_waitcnt vmcnt(8)
	s_waitcnt lgkmcnt(0)
	s_setprio 1
	s_barrier
; #define PG8_STAGE(bufoff, gbase, voff) do { _Pragma("unroll") for (int _i = 0; _i < 2; ++_i) \
;         __builtin_amdgcn_global_load_lds((const unsigned*)((const char*)(gbase) + (voff)[_i]), (LAS unsigned*)(lds + (bufoff) + ldsw + _i * 8192), 16, 0, 0); } while (0)
; #define PG8_LDA(dst, b, h) do { _Pragma("unroll") for (int m = 0; m < 4; ++m) _Pragma("unroll") for (int k = 0; k < 2; ++k) dst[m][k] = *(const LAS bf16x8*)(lds + PG8_SA(b, h) + aoff + m * 2048 + k * 1024); } while (0)
; #define PG8_LDB(dst, b, h) do { _Pragma("unroll") for (int n = 0; n < 2; ++n) _Pragma("unroll") for (int k = 0; k < 2; ++k) dst[n][k] = *(const LAS bf16x8*)(lds + PG8_SB(b, h) + boff + n * 2048 + k * 1024); } while (0)
; #define PG8_MMA(ai, bj, At, Bt) do { __builtin_amdgcn_s_setprio(1); _Pragma("unroll") for (int m = 0; m < 4; ++m) _Pragma("unroll") for (int n = 0; n < 2; ++n) _Pragma("unroll") for (int k = 0; k < 2; ++k) \
;         acc[ai][bj][m][n] = __builtin_amdgcn_mfma_f32_16x16x32_bf16(Bt[n][k], At[m][k], acc[ai][bj][m][n], 0, 0, 0); __builtin_amdgcn_s_setprio(0); } while (0)
; #define PG8_WAIT_V(n) asm volatile("s_waitcnt vmcnt(" #n ")" ::: "memory")
; #define PG8_WAIT_L(n) asm volatile("s_waitcnt lgkmcnt(" #n ")" ::: "memory")
; #define PG8_BAR __builtin_amdgcn_s_barrier()
; #define PG8_SCHED __builtin_amdgcn_sched_barrier(0)
; template <class Epi, bool ALIGN_EPI>
; __device__ __forceinline__ void gemm_phase(LAS unsigned char* lds, const Gemm g, const StaticOrder& S, const Epi& E) {
;     ...
;             PG8_WAIT_V(8); PG8_WAIT_L(0); PG8_BAR; PG8_MMA(1, 0, At, B0); PG8_MMA(1, 1, At, B1); PG8_BAR; PG8_SCHED;
;             PG8_LDB(B0, 1, 0); PG8_LDB(B1, 1, 1); PG8_SCHED; PG8_LDA(At, 1, 0); PG8_STAGE(PG8_SA(0, 1), a2 + hstepA, voffA);
;             PG8_WAIT_V(8); PG8_WAIT_L(0); PG8_BAR; PG8_MMA(0, 0, At, B0); PG8_MMA(0, 1, At, B1); PG8_BAR; PG8_SCHED;
;             PG8_LDA(At, 1, 1); PG8_STAGE(PG8_SB(1, 0), b3, voffB); PG8_STAGE(PG8_SB(1, 1), b3 + hstepB, voffB); PG8_STAGE(PG8_SA(1, 0), a3, voffA);
	v_mfma_f32_16x16x32_bf16 v[60:63], v[64:67], v[184:187], v[60:63]
	v_mfma_f32_16x16x32_bf16 v[44:47], v[64:67], v[192:195], v[44:47]
	v_mfma_f32_16x16x32_bf16 v[28:31], v[64:67], v[200:203], v[28:31]
	v_mfma_f32_16x16x32_bf16 v[12:15], v[64:67], v[208:211], v[12:15]
	v_mfma_f32_16x16x32_bf16 v[8:11], v[80:83], v[208:211], v[8:11]
	v_mfma_f32_16x16x32_bf16 v[24:27], v[80:83], v[200:203], v[24:27]
	v_mfma_f32_16x16x32_bf16 v[40:43], v[80:83], v[192:195], v[40:43]
	v_mfma_f32_16x16x32_bf16 v[56:59], v[80:83], v[184:187], v[56:59]
	v_mfma_f32_16x16x32_bf16 v[60:63], v[72:75], v[188:191], v[60:63]
	v_mfma_f32_16x16x32_bf16 v[44:47], v[72:75], v[196:199], v[44:47]
	v_mfma_f32_16x16x32_bf16 v[28:31], v[72:75], v[204:207], v[28:31]
	v_mfma_f32_16x16x32_bf16 v[12:15], v[72:75], v[212:215], v[12:15]
	v_mfma_f32_16x16x32_bf16 v[8:11], v[84:87], v[212:215], v[8:11]
	v_mfma_f32_16x16x32_bf16 v[24:27], v[84:87], v[204:207], v[24:27]
	v_mfma_f32_16x16x32_bf16 v[40:43], v[84:87], v[196:199], v[40:43]
	v_mfma_f32_16x16x32_bf16 v[56:59], v[84:87], v[188:191], v[56:59]
	s_setprio 0
	s_setprio 1
	v_mfma_f32_16x16x32_bf16 v[52:55], v[156:159], v[184:187], v[52:55]
	v_mfma_f32_16x16x32_bf16 v[36:39], v[156:159], v[192:195], v[36:39]
	v_mfma_f32_16x16x32_bf16 v[20:23], v[156:159], v[200:203], v[20:23]
	v_mfma_f32_16x16x32_bf16 v[4:7], v[156:159], v[208:211], v[4:7]
	v_mfma_f32_16x16x32_bf16 v[0:3], v[176:179], v[208:211], v[0:3]
	v_mfma_f32_16x16x32_bf16 v[16:19], v[176:179], v[200:203], v[16:19]
	v_mfma_f32_16x16x32_bf16 v[32:35], v[176:179], v[192:195], v[32:35]
	v_mfma_f32_16x16x32_bf16 v[48:51], v[176:179], v[184:187], v[48:51]
	v_mfma_f32_16x16x32_bf16 v[52:55], v[160:163], v[188:191], v[52:55]
	v_mfma_f32_16x16x32_bf16 v[36:39], v[160:163], v[196:199], v[36:39]
	v_mfma_f32_16x16x32_bf16 v[20:23], v[160:163], v[204:207], v[20:23]
	v_mfma_f32_16x16x32_bf16 v[4:7], v[160:163], v[212:215], v[4:7]
	v_mfma_f32_16x16x32_bf16 v[0:3], v[180:183], v[212:215], v[0:3]
	v_mfma_f32_16x16x32_bf16 v[16:19], v[180:183], v[204:207], v[16:19]
	v_mfma_f32_16x16x32_bf16 v[32:35], v[180:183], v[196:199], v[32:35]
	v_mfma_f32_16x16x32_bf16 v[48:51], v[180:183], v[188:191], v[48:51]
	s_barrier
	s_setprio 0
	s_add_i32 s66, 0, 0x18000
	s_add_i32 s67, 0, 0x1c000
	v_add_u32_e32 v84, s66, v169
	v_add_u32_e32 v175, s67, v169
	ds_read_b128 v[64:67], v84
	ds_read_b128 v[72:75], v84 offset:1024
	ds_read_b128 v[80:83], v84 offset:2048
	ds_read_b128 v[84:87], v84 offset:3072
	ds_read_b128 v[156:159], v175
	ds_read_b128 v[160:163], v175 offset:1024
	ds_read_b128 v[176:179], v175 offset:2048
	ds_read_b128 v[180:183], v175 offset:3072
	s_add_u32 s30, s36, 0x160000
	s_addc_u32 s31, s37, 0
	s_mov_b32 m0, s45
	v_lshl_add_u64 v[222:223], s[30:31], 0, v[144:145]
	ds_read_b128 v[184:187], v173 offset:32768
	ds_read_b128 v[188:191], v173 offset:33792
	ds_read_b128 v[192:195], v173 offset:34816
	ds_read_b128 v[196:199], v173 offset:35840
	ds_read_b128 v[200:203], v173 offset:36864
	ds_read_b128 v[204:207], v173 offset:37888
	ds_read_b128 v[208:211], v173 offset:38912
	ds_read_b128 v[212:215], v173 offset:39936
	global_load_lds_dwordx4 v[222:223], off
	v_lshl_add_u64 v[222:223], s[30:31], 0, v[146:147]
	s_mov_b32 m0, s46
	s_nop 0
	global_load_lds_dwordx4 v[222:223], off
	s_waitcnt vmcnt(8)
	s_waitcnt lgkmcnt(0)
	s_setprio 1
	s_barrier
	v_mfma_f32_16x16x32_bf16 v[140:143], v[64:67], v[184:187], v[140:143]
	v_mfma_f32_16x16x32_bf16 v[124:127], v[64:67], v[192:195], v[124:127]
	v_mfma_f32_16x16x32_bf16 v[108:111], v[64:67], v[200:203], v[108:111]
	v_mfma_f32_16x16x32_bf16 v[92:95], v[64:67], v[208:211], v[92:95]
	v_mfma_f32_16x16x32_bf16 v[88:91], v[80:83], v[208:211], v[88:91]
	v_mfma_f32_16x16x32_bf16 v[104:107], v[80:83], v[200:203], v[104:107]
	v_mfma_f32_16x16x32_bf16 v[120:123], v[80:83], v[192:195], v[120:123]
	v_mfma_f32_16x16x32_bf16 v[136:139], v[80:83], v[184:187], v[136:139]
	v_mfma_f32_16x16x32_bf16 v[140:143], v[72:75], v[188:191], v[140:143]
	v_mfma_f32_16x16x32_bf16 v[124:127], v[72:75], v[196:199], v[124:127]
	v_mfma_f32_16x16x32_bf16 v[108:111], v[72:75], v[204:207], v[108:111]
	v_mfma_f32_16x16x32_bf16 v[92:95], v[72:75], v[212:215], v[92:95]
	v_mfma_f32_16x16x32_bf16 v[88:91], v[84:87], v[212:215], v[88:91]
	v_mfma_f32_16x16x32_bf16 v[104:107], v[84:87], v[204:207], v[104:107]
	v_mfma_f32_16x16x32_bf16 v[120:123], v[84:87], v[196:199], v[120:123]
	v_mfma_f32_16x16x32_bf16 v[136:139], v[84:87], v[188:191], v[136:139]
	s_setprio 0
	s_setprio 1
	v_mfma_f32_16x16x32_bf16 v[132:135], v[156:159], v[184:187], v[132:135]
	v_mfma_f32_16x16x32_bf16 v[116:119], v[156:159], v[192:195], v[116:119]
	v_mfma_f32_16x16x32_bf16 v[100:103], v[156:159], v[200:203], v[100:103]
	v_mfma_f32_16x16x32_bf16 v[76:79], v[156:159], v[208:211], v[76:79]
	v_mfma_f32_16x16x32_bf16 v[68:71], v[176:179], v[208:211], v[68:71]
	v_mfma_f32_16x16x32_bf16 v[96:99], v[176:179], v[200:203], v[96:99]
	v_mfma_f32_16x16x32_bf16 v[112:115], v[176:179], v[192:195], v[112:115]
	v_mfma_f32_16x16x32_bf16 v[128:131], v[176:179], v[184:187], v[128:131]
	v_mfma_f32_16x16x32_bf16 v[132:135], v[160:163], v[188:191], v[132:135]
	v_mfma_f32_16x16x32_bf16 v[116:119], v[160:163], v[196:199], v[116:119]
	v_mfma_f32_16x16x32_bf16 v[100:103], v[160:163], v[204:207], v[100:103]
	v_mfma_f32_16x16x32_bf16 v[76:79], v[160:163], v[212:215], v[76:79]
	v_mfma_f32_16x16x32_bf16 v[68:71], v[180:183], v[212:215], v[68:71]
	v_mfma_f32_16x16x32_bf16 v[96:99], v[180:183], v[204:207], v[96:99]
	v_mfma_f32_16x16x32_bf16 v[112:115], v[180:183], v[196:199], v[112:115]
	v_mfma_f32_16x16x32_bf16 v[128:131], v[180:183], v[188:191], v[128:131]
	s_barrier
; #define PG8_STAGE(bufoff, gbase, voff) do { _Pragma("unroll") for (int _i = 0; _i < 2; ++_i) \
;         __builtin_amdgcn_global_load_lds((const unsigned*)((const char*)(gbase) + (voff)[_i]), (LAS unsigned*)(lds + (bufoff) + ldsw + _i * 8192), 16, 0, 0); } while (0)
; #define PG8_LDA(dst, b, h) do { _Pragma("unroll") for (int m = 0; m < 4; ++m) _Pragma("unroll") for (int k = 0; k < 2; ++k) dst[m][k] = *(const LAS bf16x8*)(lds + PG8_SA(b, h) + aoff + m * 2048 + k * 1024); } while (0)
; #define PG8_MMA(ai, bj, At, Bt) do { __builtin_amdgcn_s_setprio(1); _Pragma("unroll") for (int m = 0; m < 4; ++m) _Pragma("unroll") for (int n = 0; n < 2; ++n) _Pragma("unroll") for (int k = 0; k < 2; ++k) \
;         acc[ai][bj][m][n] = __builtin_amdgcn_mfma_f32_16x16x32_bf16(Bt[n][k], At[m][k], acc[ai][bj][m][n], 0, 0, 0); __builtin_amdgcn_s_setprio(0); } while (0)
; #define PG8_WAIT_V(n) asm volatile("s_waitcnt vmcnt(" #n ")" ::: "memory")
; #define PG8_WAIT_L(n) asm volatile("s_waitcnt lgkmcnt(" #n ")" ::: "memory")
; #define PG8_BAR __builtin_amdgcn_s_barrier()
; #define PG8_SCHED __builtin_amdgcn_sched_barrier(0)
; template <class Epi, bool ALIGN_EPI>
; __device__ __forceinline__ void gemm_phase(LAS unsigned char* lds, const Gemm g, const StaticOrder& S, const Epi& E) {
;     ...
;             PG8_LDA(At, 1, 1); PG8_STAGE(PG8_SB(1, 0), b3, voffB); PG8_STAGE(PG8_SB(1, 1), b3 + hstepB, voffB); PG8_STAGE(PG8_SA(1, 0), a3, voffA);
;             PG8_WAIT_V(8); PG8_WAIT_L(0); PG8_BAR; PG8_MMA(1, 0, At, B0); PG8_MMA(1, 1, At, B1); PG8_BAR; PG8_SCHED;
;         }
	s_setprio 0
	s_add_i32 s30, s66, s42
	v_lshl_add_u64 v[164:165], v[164:165], 0, s[20:21]
	s_mov_b32 m0, s30
	ds_read_b128 v[184:187], v173 offset:49152
	ds_read_b128 v[188:191], v173 offset:50176
	ds_read_b128 v[192:195], v173 offset:51200
	ds_read_b128 v[196:199], v173 offset:52224
	ds_read_b128 v[200:203], v173 offset:53248
	ds_read_b128 v[204:207], v173 offset:54272
	ds_read_b128 v[208:211], v173 offset:55296
	ds_read_b128 v[212:215], v173 offset:56320
	global_load_lds_dwordx4 v[164:165], off
	s_add_i32 m0, s30, 0x2000
	s_add_u32 s30, s34, 0x160080
	v_lshl_add_u64 v[164:165], v[216:217], 0, s[20:21]
	s_addc_u32 s31, s35, 0
	s_add_i32 s34, s67, s42
	global_load_lds_dwordx4 v[164:165], off
	v_lshl_add_u64 v[164:165], s[30:31], 0, v[144:145]
	s_mov_b32 m0, s34
	s_nop 0
	global_load_lds_dwordx4 v[164:165], off
	v_lshl_add_u64 v[164:165], s[30:31], 0, v[146:147]
	s_add_i32 m0, s34, 0x2000
	s_nop 0
	global_load_lds_dwordx4 v[164:165], off
	v_lshl_add_u64 v[164:165], v[218:219], 0, s[20:21]
	s_mov_b32 m0, s48
	s_nop 0
	global_load_lds_dwordx4 v[164:165], off
	v_lshl_add_u64 v[164:165], v[220:221], 0, s[20:21]
	s_mov_b32 m0, s49
	s_nop 0
	global_load_lds_dwordx4 v[164:165], off
	s_waitcnt vmcnt(8)
	s_waitcnt lgkmcnt(0)
	s_setprio 1
	s_barrier
	v_mfma_f32_16x16x32_bf16 v[60:63], v[64:67], v[184:187], v[60:63]
	v_mfma_f32_16x16x32_bf16 v[44:47], v[64:67], v[192:195], v[44:47]
	v_mfma_f32_16x16x32_bf16 v[28:31], v[64:67], v[200:203], v[28:31]
	v_mfma_f32_16x16x32_bf16 v[12:15], v[64:67], v[208:211], v[12:15]
	v_mfma_f32_16x16x32_bf16 v[8:11], v[80:83], v[208:211], v[8:11]
	v_mfma_f32_16x16x32_bf16 v[24:27], v[80:83], v[200:203], v[24:27]
	v_mfma_f32_16x16x32_bf16 v[40:43], v[80:83], v[192:195], v[40:43]
	v_mfma_f32_16x16x32_bf16 v[56:59], v[80:83], v[184:187], v[56:59]
	v_mfma_f32_16x16x32_bf16 v[60:63], v[72:75], v[188:191], v[60:63]
	v_mfma_f32_16x16x32_bf16 v[44:47], v[72:75], v[196:199], v[44:47]
	v_mfma_f32_16x16x32_bf16 v[28:31], v[72:75], v[204:207], v[28:31]
	v_mfma_f32_16x16x32_bf16 v[12:15], v[72:75], v[212:215], v[12:15]
	v_mfma_f32_16x16x32_bf16 v[8:11], v[84:87], v[212:215], v[8:11]
	v_mfma_f32_16x16x32_bf16 v[24:27], v[84:87], v[204:207], v[24:27]
	v_mfma_f32_16x16x32_bf16 v[40:43], v[84:87], v[196:199], v[40:43]
	v_mfma_f32_16x16x32_bf16 v[56:59], v[84:87], v[188:191], v[56:59]
	s_setprio 0
	s_setprio 1
	v_mfma_f32_16x16x32_bf16 v[52:55], v[156:159], v[184:187], v[52:55]
	v_mfma_f32_16x16x32_bf16 v[36:39], v[156:159], v[192:195], v[36:39]
	v_mfma_f32_16x16x32_bf16 v[20:23], v[156:159], v[200:203], v[20:23]
	v_mfma_f32_16x16x32_bf16 v[4:7], v[156:159], v[208:211], v[4:7]
	v_mfma_f32_16x16x32_bf16 v[0:3], v[176:179], v[208:211], v[0:3]
	v_mfma_f32_16x16x32_bf16 v[16:19], v[176:179], v[200:203], v[16:19]
	v_mfma_f32_16x16x32_bf16 v[32:35], v[176:179], v[192:195], v[32:35]
	v_mfma_f32_16x16x32_bf16 v[48:51], v[176:179], v[184:187], v[48:51]
	v_mfma_f32_16x16x32_bf16 v[52:55], v[160:163], v[188:191], v[52:55]
	v_mfma_f32_16x16x32_bf16 v[36:39], v[160:163], v[196:199], v[36:39]
	v_mfma_f32_16x16x32_bf16 v[20:23], v[160:163], v[204:207], v[20:23]
	v_mfma_f32_16x16x32_bf16 v[4:7], v[160:163], v[212:215], v[4:7]
	v_mfma_f32_16x16x32_bf16 v[0:3], v[180:183], v[212:215], v[0:3]
	v_mfma_f32_16x16x32_bf16 v[16:19], v[180:183], v[204:207], v[16:19]
	v_mfma_f32_16x16x32_bf16 v[32:35], v[180:183], v[196:199], v[32:35]
	v_mfma_f32_16x16x32_bf16 v[48:51], v[180:183], v[188:191], v[48:51]
	s_barrier
	s_setprio 0
	s_add_i32 s65, s65, 2
	s_add_u32 s63, s63, 0x100
	s_addc_u32 s64, s64, 0
	s_cmpk_gt_u32 s65, 0x55
	s_mov_b64 s[30:31], s[4:5]
	s_cbranch_scc0 .LBB0_309
	s_and_b64 vcc, exec, s[22:23]
	s_cbranch_vccz .LBB0_312
	s_barrier

; #define PG8_STAGE(bufoff, gbase, voff) do { _Pragma("unroll") for (int _i = 0; _i < 2; ++_i) \
;         __builtin_amdgcn_global_load_lds((const unsigned*)((const char*)(gbase) + (voff)[_i]), (LAS unsigned*)(lds + (bufoff) + ldsw + _i * 8192), 16, 0, 0); } while (0)
; #define PG8_LDA(dst, b, h) do { _Pragma("unroll") for (int m = 0; m < 4; ++m) _Pragma("unroll") for (int k = 0; k < 2; ++k) dst[m][k] = *(const LAS bf16x8*)(lds + PG8_SA(b, h) + aoff + m * 2048 + k * 1024); } while (0)
; #define PG8_LDB(dst, b, h) do { _Pragma("unroll") for (int n = 0; n < 2; ++n) _Pragma("unroll") for (int k = 0; k < 2; ++k) dst[n][k] = *(const LAS bf16x8*)(lds + PG8_SB(b, h) + boff + n * 2048 + k * 1024); } while (0)
; #define PG8_MMA(ai, bj, At, Bt) do { __builtin_amdgcn_s_setprio(1); _Pragma("unroll") for (int m = 0; m < 4; ++m) _Pragma("unroll") for (int n = 0; n < 2; ++n) _Pragma("unroll") for (int k = 0; k < 2; ++k) \
;         acc[ai][bj][m][n] = __builtin_amdgcn_mfma_f32_16x16x32_bf16(Bt[n][k], At[m][k], acc[ai][bj][m][n], 0, 0, 0); __builtin_amdgcn_s_setprio(0); } while (0)
; #define PG8_WAIT_V(n) asm volatile("s_waitcnt vmcnt(" #n ")" ::: "memory")
; #define PG8_WAIT_L(n) asm volatile("s_waitcnt lgkmcnt(" #n ")" ::: "memory")
; #define PG8_BAR __builtin_amdgcn_s_barrier()
; #define PG8_SCHED __builtin_amdgcn_sched_barrier(0)
; template <class Epi, bool ALIGN_EPI>
; __device__ __forceinline__ void gemm_phase(LAS unsigned char* lds, const Gemm g, const StaticOrder& S, const Epi& E) {
;     ...
;             const bool last = (t == nt - 2);
;             const char* a1 = cA + (size_t)(t + 1) * kstep;
;             const char* a2 = last ? nA : cA + (size_t)(t + 2) * kstep; const char* b2 = last ? nB : cB + (size_t)(t + 2) * kstep;
;             const char* a3 = a2 + kstep; const char* b3 = b2 + kstep;
;             PG8_LDB(B0, 0, 0); PG8_LDB(B1, 0, 1); PG8_SCHED; PG8_LDA(At, 0, 0); PG8_STAGE(PG8_SA(1, 1), a1 + hstepA, voffA);
;             PG8_WAIT_V(8); PG8_WAIT_L(0); PG8_BAR; PG8_MMA(0, 0, At, B0); PG8_MMA(0, 1, At, B1); PG8_BAR; PG8_SCHED;
;             PG8_LDA(At, 0, 1); PG8_STAGE(PG8_SB(0, 0), b2, voffB); PG8_STAGE(PG8_SB(0, 1), b2 + hstepB, voffB); PG8_STAGE(PG8_SA(0, 0), a2, voffA);
;             PG8_WAIT_V(8); PG8_WAIT_L(0); PG8_BAR; PG8_MMA(1, 0, At, B0); PG8_MMA(1, 1, At, B1); PG8_BAR; PG8_SCHED;
.LBB0_459:
	ds_read_b128 v[152:155], v165
	ds_read_b128 v[156:159], v165 offset:1024
	ds_read_b128 v[172:175], v165 offset:2048
	ds_read_b128 v[176:179], v165 offset:3072
	ds_read_b128 v[180:183], v168
	ds_read_b128 v[184:187], v168 offset:1024
	ds_read_b128 v[188:191], v168 offset:2048
	ds_read_b128 v[192:195], v168 offset:3072
	s_add_u32 s40, s8, 0xfff80080
	s_addc_u32 s41, s9, -1
	s_cmp_eq_u32 s45, 28
	s_cselect_b32 s43, s5, s41
	s_cselect_b32 s42, s7, s40
	s_cselect_b32 s41, s10, s44
	s_cselect_b32 s40, s31, s35
	v_lshl_add_u64 v[160:161], s[8:9], 0, v[146:147]
	s_add_i32 m0, s50, 0xc000
	ds_read_b128 v[196:199], v169
	ds_read_b128 v[200:203], v169 offset:1024
	ds_read_b128 v[204:207], v169 offset:2048
	ds_read_b128 v[208:211], v169 offset:3072
	ds_read_b128 v[212:215], v169 offset:4096
	ds_read_b128 v[216:219], v169 offset:5120
	ds_read_b128 v[220:223], v169 offset:6144
	ds_read_b128 v[224:227], v169 offset:7168
	global_load_lds_dwordx4 v[160:161], off
	v_lshl_add_u64 v[160:161], s[8:9], 0, v[144:145]
	s_add_i32 m0, s50, 0xe000
	s_nop 0
	global_load_lds_dwordx4 v[160:161], off
	s_waitcnt vmcnt(8)
	s_waitcnt lgkmcnt(0)
	s_setprio 1
	s_barrier
	v_mfma_f32_16x16x32_bf16 v[120:123], v[152:155], v[196:199], v[120:123]
	v_mfma_f32_16x16x32_bf16 v[104:107], v[152:155], v[204:207], v[104:107]
	v_mfma_f32_16x16x32_bf16 v[88:91], v[152:155], v[212:215], v[88:91]
	v_mfma_f32_16x16x32_bf16 v[72:75], v[152:155], v[220:223], v[72:75]
	v_mfma_f32_16x16x32_bf16 v[64:67], v[172:175], v[220:223], v[64:67]
	v_mfma_f32_16x16x32_bf16 v[80:83], v[172:175], v[212:215], v[80:83]
	v_mfma_f32_16x16x32_bf16 v[96:99], v[172:175], v[204:207], v[96:99]
	v_mfma_f32_16x16x32_bf16 v[112:115], v[172:175], v[196:199], v[112:115]
	v_mfma_f32_16x16x32_bf16 v[120:123], v[156:159], v[200:203], v[120:123]
	v_mfma_f32_16x16x32_bf16 v[104:107], v[156:159], v[208:211], v[104:107]
	v_mfma_f32_16x16x32_bf16 v[88:91], v[156:159], v[216:219], v[88:91]
	v_mfma_f32_16x16x32_bf16 v[72:75], v[156:159], v[224:227], v[72:75]
	v_mfma_f32_16x16x32_bf16 v[64:67], v[176:179], v[224:227], v[64:67]
	v_mfma_f32_16x16x32_bf16 v[80:83], v[176:179], v[216:219], v[80:83]
	v_mfma_f32_16x16x32_bf16 v[96:99], v[176:179], v[208:211], v[96:99]
	v_mfma_f32_16x16x32_bf16 v[112:115], v[176:179], v[200:203], v[112:115]
	s_setprio 0
	s_setprio 1
	v_mfma_f32_16x16x32_bf16 v[124:127], v[180:183], v[196:199], v[124:127]
	v_mfma_f32_16x16x32_bf16 v[108:111], v[180:183], v[204:207], v[108:111]
	v_mfma_f32_16x16x32_bf16 v[92:95], v[180:183], v[212:215], v[92:95]
	v_mfma_f32_16x16x32_bf16 v[76:79], v[180:183], v[220:223], v[76:79]
	v_mfma_f32_16x16x32_bf16 v[68:71], v[188:191], v[220:223], v[68:71]
	v_mfma_f32_16x16x32_bf16 v[84:87], v[188:191], v[212:215], v[84:87]
	v_mfma_f32_16x16x32_bf16 v[100:103], v[188:191], v[204:207], v[100:103]
	v_mfma_f32_16x16x32_bf16 v[116:119], v[188:191], v[196:199], v[116:119]
	v_mfma_f32_16x16x32_bf16 v[124:127], v[184:187], v[200:203], v[124:127]
	v_mfma_f32_16x16x32_bf16 v[108:111], v[184:187], v[208:211], v[108:111]
	v_mfma_f32_16x16x32_bf16 v[92:95], v[184:187], v[216:219], v[92:95]
	v_mfma_f32_16x16x32_bf16 v[76:79], v[184:187], v[224:227], v[76:79]
	v_mfma_f32_16x16x32_bf16 v[68:71], v[192:195], v[224:227], v[68:71]
	v_mfma_f32_16x16x32_bf16 v[84:87], v[192:195], v[216:219], v[84:87]
	v_mfma_f32_16x16x32_bf16 v[100:103], v[192:195], v[208:211], v[100:103]
	v_mfma_f32_16x16x32_bf16 v[116:119], v[192:195], v[200:203], v[116:119]
	s_barrier
	s_setprio 0
	s_add_i32 s71, s62, s49
	v_lshl_add_u64 v[160:161], s[40:41], 0, v[130:131]
	s_mov_b32 m0, s71
	ds_read_b128 v[196:199], v169 offset:16384
	ds_read_b128 v[200:203], v169 offset:17408
	ds_read_b128 v[204:207], v169 offset:18432
	ds_read_b128 v[208:211], v169 offset:19456
	ds_read_b128 v[212:215], v169 offset:20480
	ds_read_b128 v[216:219], v169 offset:21504
	ds_read_b128 v[220:223], v169 offset:22528
	ds_read_b128 v[224:227], v169 offset:23552
	global_load_lds_dwordx4 v[160:161], off
	s_add_i32 m0, s71, 0x2000
	s_add_u32 s78, s40, 0x80000
	v_lshl_add_u64 v[228:229], s[40:41], 0, v[134:135]
	s_addc_u32 s79, s41, 0
	s_add_i32 s71, s63, s49
	global_load_lds_dwordx4 v[228:229], off
	v_lshl_add_u64 v[230:231], s[78:79], 0, v[130:131]
	s_mov_b32 m0, s71
	v_lshl_add_u64 v[232:233], s[42:43], 0, v[132:133]
	global_load_lds_dwordx4 v[230:231], off
	v_lshl_add_u64 v[230:231], s[78:79], 0, v[134:135]
	s_add_i32 m0, s71, 0x2000
	s_nop 0
	global_load_lds_dwordx4 v[230:231], off
	v_lshl_add_u64 v[230:231], s[42:43], 0, v[128:129]
	s_mov_b32 m0, s50
	s_nop 0
	global_load_lds_dwordx4 v[230:231], off
	s_mov_b32 m0, s51
	s_nop 0
	global_load_lds_dwordx4 v[232:233], off
	s_waitcnt vmcnt(8)
	s_waitcnt lgkmcnt(0)
	s_setprio 1
	s_barrier
; #define PG8_STAGE(bufoff, gbase, voff) do { _Pragma("unroll") for (int _i = 0; _i < 2; ++_i) \
;         __builtin_amdgcn_global_load_lds((const unsigned*)((const char*)(gbase) + (voff)[_i]), (LAS unsigned*)(lds + (bufoff) + ldsw + _i * 8192), 16, 0, 0); } while (0)
; #define PG8_LDA(dst, b, h) do { _Pragma("unroll") for (int m = 0; m < 4; ++m) _Pragma("unroll") for (int k = 0; k < 2; ++k) dst[m][k] = *(const LAS bf16x8*)(lds + PG8_SA(b, h) + aoff + m * 2048 + k * 1024); } while (0)
; #define PG8_LDB(dst, b, h) do { _Pragma("unroll") for (int n = 0; n < 2; ++n) _Pragma("unroll") for (int k = 0; k < 2; ++k) dst[n][k] = *(const LAS bf16x8*)(lds + PG8_SB(b, h) + boff + n * 2048 + k * 1024); } while (0)
; #define PG8_MMA(ai, bj, At, Bt) do { __builtin_amdgcn_s_setprio(1); _Pragma("unroll") for (int m = 0; m < 4; ++m) _Pragma("unroll") for (int n = 0; n < 2; ++n) _Pragma("unroll") for (int k = 0; k < 2; ++k) \
;         acc[ai][bj][m][n] = __builtin_amdgcn_mfma_f32_16x16x32_bf16(Bt[n][k], At[m][k], acc[ai][bj][m][n], 0, 0, 0); __builtin_amdgcn_s_setprio(0); } while (0)
; #define PG8_WAIT_V(n) asm volatile("s_waitcnt vmcnt(" #n ")" ::: "memory")
; #define PG8_WAIT_L(n) asm volatile("s_waitcnt lgkmcnt(" #n ")" ::: "memory")
; #define PG8_BAR __builtin_amdgcn_s_barrier()
; #define PG8_SCHED __builtin_amdgcn_sched_barrier(0)
; template <class Epi, bool ALIGN_EPI>
; __device__ __forceinline__ void gemm_phase(LAS unsigned char* lds, const Gemm g, const StaticOrder& S, const Epi& E) {
;     ...
;             PG8_WAIT_V(8); PG8_WAIT_L(0); PG8_BAR; PG8_MMA(1, 0, At, B0); PG8_MMA(1, 1, At, B1); PG8_BAR; PG8_SCHED;
;             PG8_LDB(B0, 1, 0); PG8_LDB(B1, 1, 1); PG8_SCHED; PG8_LDA(At, 1, 0); PG8_STAGE(PG8_SA(0, 1), a2 + hstepA, voffA);
;             PG8_WAIT_V(8); PG8_WAIT_L(0); PG8_BAR; PG8_MMA(0, 0, At, B0); PG8_MMA(0, 1, At, B1); PG8_BAR; PG8_SCHED;
;             PG8_LDA(At, 1, 1); PG8_STAGE(PG8_SB(1, 0), b3, voffB); PG8_STAGE(PG8_SB(1, 1), b3 + hstepB, voffB); PG8_STAGE(PG8_SA(1, 0), a3, voffA);
	v_mfma_f32_16x16x32_bf16 v[56:59], v[152:155], v[196:199], v[56:59]
	v_mfma_f32_16x16x32_bf16 v[40:43], v[152:155], v[204:207], v[40:43]
	v_mfma_f32_16x16x32_bf16 v[24:27], v[152:155], v[212:215], v[24:27]
	v_mfma_f32_16x16x32_bf16 v[8:11], v[152:155], v[220:223], v[8:11]
	v_mfma_f32_16x16x32_bf16 v[0:3], v[172:175], v[220:223], v[0:3]
	v_mfma_f32_16x16x32_bf16 v[16:19], v[172:175], v[212:215], v[16:19]
	v_mfma_f32_16x16x32_bf16 v[32:35], v[172:175], v[204:207], v[32:35]
	v_mfma_f32_16x16x32_bf16 v[48:51], v[172:175], v[196:199], v[48:51]
	v_mfma_f32_16x16x32_bf16 v[56:59], v[156:159], v[200:203], v[56:59]
	v_mfma_f32_16x16x32_bf16 v[40:43], v[156:159], v[208:211], v[40:43]
	v_mfma_f32_16x16x32_bf16 v[24:27], v[156:159], v[216:219], v[24:27]
	v_mfma_f32_16x16x32_bf16 v[8:11], v[156:159], v[224:227], v[8:11]
	v_mfma_f32_16x16x32_bf16 v[0:3], v[176:179], v[224:227], v[0:3]
	v_mfma_f32_16x16x32_bf16 v[16:19], v[176:179], v[216:219], v[16:19]
	v_mfma_f32_16x16x32_bf16 v[32:35], v[176:179], v[208:211], v[32:35]
	v_mfma_f32_16x16x32_bf16 v[48:51], v[176:179], v[200:203], v[48:51]
	s_setprio 0
	s_setprio 1
	v_mfma_f32_16x16x32_bf16 v[60:63], v[180:183], v[196:199], v[60:63]
	v_mfma_f32_16x16x32_bf16 v[44:47], v[180:183], v[204:207], v[44:47]
	v_mfma_f32_16x16x32_bf16 v[28:31], v[180:183], v[212:215], v[28:31]
	v_mfma_f32_16x16x32_bf16 v[12:15], v[180:183], v[220:223], v[12:15]
	v_mfma_f32_16x16x32_bf16 v[4:7], v[188:191], v[220:223], v[4:7]
	v_mfma_f32_16x16x32_bf16 v[20:23], v[188:191], v[212:215], v[20:23]
	v_mfma_f32_16x16x32_bf16 v[36:39], v[188:191], v[204:207], v[36:39]
	v_mfma_f32_16x16x32_bf16 v[52:55], v[188:191], v[196:199], v[52:55]
	v_mfma_f32_16x16x32_bf16 v[60:63], v[184:187], v[200:203], v[60:63]
	v_mfma_f32_16x16x32_bf16 v[44:47], v[184:187], v[208:211], v[44:47]
	v_mfma_f32_16x16x32_bf16 v[28:31], v[184:187], v[216:219], v[28:31]
	v_mfma_f32_16x16x32_bf16 v[12:15], v[184:187], v[224:227], v[12:15]
	v_mfma_f32_16x16x32_bf16 v[4:7], v[192:195], v[224:227], v[4:7]
	v_mfma_f32_16x16x32_bf16 v[20:23], v[192:195], v[216:219], v[20:23]
	v_mfma_f32_16x16x32_bf16 v[36:39], v[192:195], v[208:211], v[36:39]
	v_mfma_f32_16x16x32_bf16 v[52:55], v[192:195], v[200:203], v[52:55]
	s_barrier
	s_setprio 0
	s_add_i32 s71, 0, 0x18000
	v_add_u32_e32 v136, s71, v162
	s_add_i32 s73, 0, 0x1c000
	ds_read_b128 v[152:155], v136
	ds_read_b128 v[156:159], v136 offset:1024
	ds_read_b128 v[172:175], v136 offset:2048
	ds_read_b128 v[176:179], v136 offset:3072
	v_add_u32_e32 v136, s73, v162
	ds_read_b128 v[180:183], v136
	ds_read_b128 v[184:187], v136 offset:1024
	ds_read_b128 v[188:191], v136 offset:2048
	ds_read_b128 v[192:195], v136 offset:3072
	s_add_u32 s42, s42, 0x80000
	s_addc_u32 s43, s43, 0
	s_mov_b32 m0, s52
	v_lshl_add_u64 v[234:235], s[42:43], 0, v[128:129]
	ds_read_b128 v[196:199], v169 offset:32768
	ds_read_b128 v[200:203], v169 offset:33792
	ds_read_b128 v[204:207], v169 offset:34816
	ds_read_b128 v[208:211], v169 offset:35840
	ds_read_b128 v[212:215], v169 offset:36864
	ds_read_b128 v[216:219], v169 offset:37888
	ds_read_b128 v[220:223], v169 offset:38912
	ds_read_b128 v[224:227], v169 offset:39936
	global_load_lds_dwordx4 v[234:235], off
	v_lshl_add_u64 v[234:235], s[42:43], 0, v[132:133]
	s_mov_b32 m0, s53
	s_nop 0
	global_load_lds_dwordx4 v[234:235], off
	s_waitcnt vmcnt(8)
	s_waitcnt lgkmcnt(0)
	s_setprio 1
	s_barrier
	v_mfma_f32_16x16x32_bf16 v[120:123], v[152:155], v[196:199], v[120:123]
	v_mfma_f32_16x16x32_bf16 v[104:107], v[152:155], v[204:207], v[104:107]
	v_mfma_f32_16x16x32_bf16 v[88:91], v[152:155], v[212:215], v[88:91]
	v_mfma_f32_16x16x32_bf16 v[72:75], v[152:155], v[220:223], v[72:75]
	v_mfma_f32_16x16x32_bf16 v[64:67], v[172:175], v[220:223], v[64:67]
	v_mfma_f32_16x16x32_bf16 v[80:83], v[172:175], v[212:215], v[80:83]
	v_mfma_f32_16x16x32_bf16 v[96:99], v[172:175], v[204:207], v[96:99]
	v_mfma_f32_16x16x32_bf16 v[112:115], v[172:175], v[196:199], v[112:115]
	v_mfma_f32_16x16x32_bf16 v[120:123], v[156:159], v[200:203], v[120:123]
	v_mfma_f32_16x16x32_bf16 v[104:107], v[156:159], v[208:211], v[104:107]
	v_mfma_f32_16x16x32_bf16 v[88:91], v[156:159], v[216:219], v[88:91]
	v_mfma_f32_16x16x32_bf16 v[72:75], v[156:159], v[224:227], v[72:75]
	v_mfma_f32_16x16x32_bf16 v[64:67], v[176:179], v[224:227], v[64:67]
	v_mfma_f32_16x16x32_bf16 v[80:83], v[176:179], v[216:219], v[80:83]
	v_mfma_f32_16x16x32_bf16 v[96:99], v[176:179], v[208:211], v[96:99]
	v_mfma_f32_16x16x32_bf16 v[112:115], v[176:179], v[200:203], v[112:115]
	s_setprio 0
	s_setprio 1
	v_mfma_f32_16x16x32_bf16 v[124:127], v[180:183], v[196:199], v[124:127]
	v_mfma_f32_16x16x32_bf16 v[108:111], v[180:183], v[204:207], v[108:111]
	v_mfma_f32_16x16x32_bf16 v[92:95], v[180:183], v[212:215], v[92:95]
	v_mfma_f32_16x16x32_bf16 v[76:79], v[180:183], v[220:223], v[76:79]
	v_mfma_f32_16x16x32_bf16 v[68:71], v[188:191], v[220:223], v[68:71]
	v_mfma_f32_16x16x32_bf16 v[84:87], v[188:191], v[212:215], v[84:87]
	v_mfma_f32_16x16x32_bf16 v[100:103], v[188:191], v[204:207], v[100:103]
	v_mfma_f32_16x16x32_bf16 v[116:119], v[188:191], v[196:199], v[116:119]
	v_mfma_f32_16x16x32_bf16 v[124:127], v[184:187], v[200:203], v[124:127]
	v_mfma_f32_16x16x32_bf16 v[108:111], v[184:187], v[208:211], v[108:111]
	v_mfma_f32_16x16x32_bf16 v[92:95], v[184:187], v[216:219], v[92:95]
	v_mfma_f32_16x16x32_bf16 v[76:79], v[184:187], v[224:227], v[76:79]
	v_mfma_f32_16x16x32_bf16 v[68:71], v[192:195], v[224:227], v[68:71]
	v_mfma_f32_16x16x32_bf16 v[84:87], v[192:195], v[216:219], v[84:87]
	v_mfma_f32_16x16x32_bf16 v[100:103], v[192:195], v[208:211], v[100:103]
	v_mfma_f32_16x16x32_bf16 v[116:119], v[192:195], v[200:203], v[116:119]
	s_barrier
; #define PG8_STAGE(bufoff, gbase, voff) do { _Pragma("unroll") for (int _i = 0; _i < 2; ++_i) \
;         __builtin_amdgcn_global_load_lds((const unsigned*)((const char*)(gbase) + (voff)[_i]), (LAS unsigned*)(lds + (bufoff) + ldsw + _i * 8192), 16, 0, 0); } while (0)
; #define PG8_LDA(dst, b, h) do { _Pragma("unroll") for (int m = 0; m < 4; ++m) _Pragma("unroll") for (int k = 0; k < 2; ++k) dst[m][k] = *(const LAS bf16x8*)(lds + PG8_SA(b, h) + aoff + m * 2048 + k * 1024); } while (0)
; #define PG8_MMA(ai, bj, At, Bt) do { __builtin_amdgcn_s_setprio(1); _Pragma("unroll") for (int m = 0; m < 4; ++m) _Pragma("unroll") for (int n = 0; n < 2; ++n) _Pragma("unroll") for (int k = 0; k < 2; ++k) \
;         acc[ai][bj][m][n] = __builtin_amdgcn_mfma_f32_16x16x32_bf16(Bt[n][k], At[m][k], acc[ai][bj][m][n], 0, 0, 0); __builtin_amdgcn_s_setprio(0); } while (0)
; #define PG8_WAIT_V(n) asm volatile("s_waitcnt vmcnt(" #n ")" ::: "memory")
; #define PG8_WAIT_L(n) asm volatile("s_waitcnt lgkmcnt(" #n ")" ::: "memory")
; #define PG8_BAR __builtin_amdgcn_s_barrier()
; #define PG8_SCHED __builtin_amdgcn_sched_barrier(0)
; template <class Epi, bool ALIGN_EPI>
; __device__ __forceinline__ void gemm_phase(LAS unsigned char* lds, const Gemm g, const StaticOrder& S, const Epi& E) {
;     ...
;             PG8_LDA(At, 1, 1); PG8_STAGE(PG8_SB(1, 0), b3, voffB); PG8_STAGE(PG8_SB(1, 1), b3 + hstepB, voffB); PG8_STAGE(PG8_SA(1, 0), a3, voffA);
;             PG8_WAIT_V(8); PG8_WAIT_L(0); PG8_BAR; PG8_MMA(1, 0, At, B0); PG8_MMA(1, 1, At, B1); PG8_BAR; PG8_SCHED;
;         }
	s_setprio 0
	s_add_i32 s42, s71, s49
	v_lshl_add_u64 v[160:161], v[160:161], 0, s[22:23]
	s_mov_b32 m0, s42
	ds_read_b128 v[196:199], v169 offset:49152
	ds_read_b128 v[200:203], v169 offset:50176
	ds_read_b128 v[204:207], v169 offset:51200
	ds_read_b128 v[208:211], v169 offset:52224
	ds_read_b128 v[212:215], v169 offset:53248
	ds_read_b128 v[216:219], v169 offset:54272
	ds_read_b128 v[220:223], v169 offset:55296
	ds_read_b128 v[224:227], v169 offset:56320
	global_load_lds_dwordx4 v[160:161], off
	s_add_i32 m0, s42, 0x2000
	s_add_u32 s40, s40, 0x80080
	v_lshl_add_u64 v[160:161], v[228:229], 0, s[22:23]
	s_addc_u32 s41, s41, 0
	s_add_i32 s42, s73, s49
	global_load_lds_dwordx4 v[160:161], off
	v_lshl_add_u64 v[160:161], s[40:41], 0, v[130:131]
	s_mov_b32 m0, s42
	s_nop 0
	global_load_lds_dwordx4 v[160:161], off
	v_lshl_add_u64 v[160:161], s[40:41], 0, v[134:135]
	s_add_i32 m0, s42, 0x2000
	s_nop 0
	global_load_lds_dwordx4 v[160:161], off
	v_lshl_add_u64 v[160:161], v[230:231], 0, s[22:23]
	s_mov_b32 m0, s56
	s_nop 0
	global_load_lds_dwordx4 v[160:161], off
	v_lshl_add_u64 v[160:161], v[232:233], 0, s[22:23]
	s_mov_b32 m0, s57
	s_nop 0
	global_load_lds_dwordx4 v[160:161], off
	s_waitcnt vmcnt(8)
	s_waitcnt lgkmcnt(0)
	s_setprio 1
	s_barrier
	v_mfma_f32_16x16x32_bf16 v[56:59], v[152:155], v[196:199], v[56:59]
	v_mfma_f32_16x16x32_bf16 v[40:43], v[152:155], v[204:207], v[40:43]
	v_mfma_f32_16x16x32_bf16 v[24:27], v[152:155], v[212:215], v[24:27]
	v_mfma_f32_16x16x32_bf16 v[8:11], v[152:155], v[220:223], v[8:11]
	v_mfma_f32_16x16x32_bf16 v[0:3], v[172:175], v[220:223], v[0:3]
	v_mfma_f32_16x16x32_bf16 v[16:19], v[172:175], v[212:215], v[16:19]
	v_mfma_f32_16x16x32_bf16 v[32:35], v[172:175], v[204:207], v[32:35]
	v_mfma_f32_16x16x32_bf16 v[48:51], v[172:175], v[196:199], v[48:51]
	v_mfma_f32_16x16x32_bf16 v[56:59], v[156:159], v[200:203], v[56:59]
	v_mfma_f32_16x16x32_bf16 v[40:43], v[156:159], v[208:211], v[40:43]
	v_mfma_f32_16x16x32_bf16 v[24:27], v[156:159], v[216:219], v[24:27]
	v_mfma_f32_16x16x32_bf16 v[8:11], v[156:159], v[224:227], v[8:11]
	v_mfma_f32_16x16x32_bf16 v[0:3], v[176:179], v[224:227], v[0:3]
	v_mfma_f32_16x16x32_bf16 v[16:19], v[176:179], v[216:219], v[16:19]
	v_mfma_f32_16x16x32_bf16 v[32:35], v[176:179], v[208:211], v[32:35]
	v_mfma_f32_16x16x32_bf16 v[48:51], v[176:179], v[200:203], v[48:51]
	s_setprio 0
	s_setprio 1
	v_mfma_f32_16x16x32_bf16 v[60:63], v[180:183], v[196:199], v[60:63]
	v_mfma_f32_16x16x32_bf16 v[44:47], v[180:183], v[204:207], v[44:47]
	v_mfma_f32_16x16x32_bf16 v[28:31], v[180:183], v[212:215], v[28:31]
	v_mfma_f32_16x16x32_bf16 v[12:15], v[180:183], v[220:223], v[12:15]
	v_mfma_f32_16x16x32_bf16 v[4:7], v[188:191], v[220:223], v[4:7]
	v_mfma_f32_16x16x32_bf16 v[20:23], v[188:191], v[212:215], v[20:23]
	v_mfma_f32_16x16x32_bf16 v[36:39], v[188:191], v[204:207], v[36:39]
	v_mfma_f32_16x16x32_bf16 v[52:55], v[188:191], v[196:199], v[52:55]
	v_mfma_f32_16x16x32_bf16 v[60:63], v[184:187], v[200:203], v[60:63]
	v_mfma_f32_16x16x32_bf16 v[44:47], v[184:187], v[208:211], v[44:47]
	v_mfma_f32_16x16x32_bf16 v[28:31], v[184:187], v[216:219], v[28:31]
	v_mfma_f32_16x16x32_bf16 v[12:15], v[184:187], v[224:227], v[12:15]
	v_mfma_f32_16x16x32_bf16 v[4:7], v[192:195], v[224:227], v[4:7]
	v_mfma_f32_16x16x32_bf16 v[20:23], v[192:195], v[216:219], v[20:23]
	v_mfma_f32_16x16x32_bf16 v[36:39], v[192:195], v[208:211], v[36:39]
	v_mfma_f32_16x16x32_bf16 v[52:55], v[192:195], v[200:203], v[52:55]
	s_barrier
	s_setprio 0
	s_add_i32 s45, s45, 2
	s_add_u32 s35, s35, 0x100
	s_addc_u32 s44, s44, 0
	s_add_u32 s8, s8, 0x100
	s_addc_u32 s9, s9, 0
	s_cmp_gt_u32 s45, 29
	s_cbranch_scc0 .LBB0_459
	s_and_b64 vcc, exec, s[24:25]
	s_cbranch_vccz .LBB0_462
	s_barrier

; #define PG8_STAGE(bufoff, gbase, voff) do { _Pragma("unroll") for (int _i = 0; _i < 2; ++_i) \
;         __builtin_amdgcn_global_load_lds((const unsigned*)((const char*)(gbase) + (voff)[_i]), (LAS unsigned*)(lds + (bufoff) + ldsw + _i * 8192), 16, 0, 0); } while (0)
; #define PG8_LDA(dst, b, h) do { _Pragma("unroll") for (int m = 0; m < 4; ++m) _Pragma("unroll") for (int k = 0; k < 2; ++k) dst[m][k] = *(const LAS bf16x8*)(lds + PG8_SA(b, h) + aoff + m * 2048 + k * 1024); } while (0)
; #define PG8_LDB(dst, b, h) do { _Pragma("unroll") for (int n = 0; n < 2; ++n) _Pragma("unroll") for (int k = 0; k < 2; ++k) dst[n][k] = *(const LAS bf16x8*)(lds + PG8_SB(b, h) + boff + n * 2048 + k * 1024); } while (0)
; #define PG8_MMA(ai, bj, At, Bt) do { __builtin_amdgcn_s_setprio(1); _Pragma("unroll") for (int m = 0; m < 4; ++m) _Pragma("unroll") for (int n = 0; n < 2; ++n) _Pragma("unroll") for (int k = 0; k < 2; ++k) \
;         acc[ai][bj][m][n] = __builtin_amdgcn_mfma_f32_16x16x32_bf16(Bt[n][k], At[m][k], acc[ai][bj][m][n], 0, 0, 0); __builtin_amdgcn_s_setprio(0); } while (0)
; #define PG8_WAIT_V(n) asm volatile("s_waitcnt vmcnt(" #n ")" ::: "memory")
; #define PG8_WAIT_L(n) asm volatile("s_waitcnt lgkmcnt(" #n ")" ::: "memory")
; #define PG8_BAR __builtin_amdgcn_s_barrier()
; #define PG8_SCHED __builtin_amdgcn_sched_barrier(0)
; template <class Epi, bool ALIGN_EPI>
; __device__ __forceinline__ void gemm_phase(LAS unsigned char* lds, const Gemm g, const StaticOrder& S, const Epi& E) {
;     ...
;             const bool last = (t == nt - 2);
;             const char* a1 = cA + (size_t)(t + 1) * kstep;
;             const char* a2 = last ? nA : cA + (size_t)(t + 2) * kstep; const char* b2 = last ? nB : cB + (size_t)(t + 2) * kstep;
;             const char* a3 = a2 + kstep; const char* b3 = b2 + kstep;
;             PG8_LDB(B0, 0, 0); PG8_LDB(B1, 0, 1); PG8_SCHED; PG8_LDA(At, 0, 0); PG8_STAGE(PG8_SA(1, 1), a1 + hstepA, voffA);
;             PG8_WAIT_V(8); PG8_WAIT_L(0); PG8_BAR; PG8_MMA(0, 0, At, B0); PG8_MMA(0, 1, At, B1); PG8_BAR; PG8_SCHED;
;             PG8_LDA(At, 0, 1); PG8_STAGE(PG8_SB(0, 0), b2, voffB); PG8_STAGE(PG8_SB(0, 1), b2 + hstepB, voffB); PG8_STAGE(PG8_SA(0, 0), a2, voffA);
;             PG8_WAIT_V(8); PG8_WAIT_L(0); PG8_BAR; PG8_MMA(1, 0, At, B0); PG8_MMA(1, 1, At, B1); PG8_BAR; PG8_SCHED;
.LBB0_817:
	ds_read_b128 v[152:155], v149
	ds_read_b128 v[156:159], v149 offset:1024
	ds_read_b128 v[160:163], v149 offset:2048
	ds_read_b128 v[168:171], v149 offset:3072
	ds_read_b128 v[172:175], v150
	ds_read_b128 v[176:179], v150 offset:1024
	ds_read_b128 v[180:183], v150 offset:2048
	ds_read_b128 v[184:187], v150 offset:3072
	s_add_u32 s24, s22, 0xfff80080
	s_addc_u32 s25, s23, -1
	s_cmp_eq_u32 s56, 12
	s_cselect_b32 s27, s15, s25
	s_cselect_b32 s26, s52, s24
	s_cselect_b32 s25, s13, s55
	s_cselect_b32 s24, s53, s54
	v_lshl_add_u64 v[144:145], s[22:23], 0, v[138:139]
	s_add_i32 m0, s21, 0xc000
	ds_read_b128 v[188:191], v151
	ds_read_b128 v[192:195], v151 offset:1024
	ds_read_b128 v[196:199], v151 offset:2048
	ds_read_b128 v[200:203], v151 offset:3072
	ds_read_b128 v[204:207], v151 offset:4096
	ds_read_b128 v[208:211], v151 offset:5120
	ds_read_b128 v[212:215], v151 offset:6144
	ds_read_b128 v[216:219], v151 offset:7168
	global_load_lds_dwordx4 v[144:145], off
	v_lshl_add_u64 v[144:145], s[22:23], 0, v[136:137]
	s_add_i32 m0, s21, 0xe000
	s_nop 0
	global_load_lds_dwordx4 v[144:145], off
	s_waitcnt vmcnt(8)
	s_waitcnt lgkmcnt(0)
	s_setprio 1
	s_barrier
	v_mfma_f32_16x16x32_bf16 v[124:127], v[152:155], v[188:191], v[124:127]
	v_mfma_f32_16x16x32_bf16 v[108:111], v[152:155], v[196:199], v[108:111]
	v_mfma_f32_16x16x32_bf16 v[92:95], v[152:155], v[204:207], v[92:95]
	v_mfma_f32_16x16x32_bf16 v[76:79], v[152:155], v[212:215], v[76:79]
	v_mfma_f32_16x16x32_bf16 v[72:75], v[160:163], v[212:215], v[72:75]
	v_mfma_f32_16x16x32_bf16 v[88:91], v[160:163], v[204:207], v[88:91]
	v_mfma_f32_16x16x32_bf16 v[104:107], v[160:163], v[196:199], v[104:107]
	v_mfma_f32_16x16x32_bf16 v[120:123], v[160:163], v[188:191], v[120:123]
	v_mfma_f32_16x16x32_bf16 v[124:127], v[156:159], v[192:195], v[124:127]
	v_mfma_f32_16x16x32_bf16 v[108:111], v[156:159], v[200:203], v[108:111]
	v_mfma_f32_16x16x32_bf16 v[92:95], v[156:159], v[208:211], v[92:95]
	v_mfma_f32_16x16x32_bf16 v[76:79], v[156:159], v[216:219], v[76:79]
	v_mfma_f32_16x16x32_bf16 v[72:75], v[168:171], v[216:219], v[72:75]
	v_mfma_f32_16x16x32_bf16 v[88:91], v[168:171], v[208:211], v[88:91]
	v_mfma_f32_16x16x32_bf16 v[104:107], v[168:171], v[200:203], v[104:107]
	v_mfma_f32_16x16x32_bf16 v[120:123], v[168:171], v[192:195], v[120:123]
	s_setprio 0
	s_setprio 1
	v_mfma_f32_16x16x32_bf16 v[116:119], v[172:175], v[188:191], v[116:119]
	v_mfma_f32_16x16x32_bf16 v[100:103], v[172:175], v[196:199], v[100:103]
	v_mfma_f32_16x16x32_bf16 v[84:87], v[172:175], v[204:207], v[84:87]
	v_mfma_f32_16x16x32_bf16 v[68:71], v[172:175], v[212:215], v[68:71]
	v_mfma_f32_16x16x32_bf16 v[64:67], v[180:183], v[212:215], v[64:67]
	v_mfma_f32_16x16x32_bf16 v[80:83], v[180:183], v[204:207], v[80:83]
	v_mfma_f32_16x16x32_bf16 v[96:99], v[180:183], v[196:199], v[96:99]
	v_mfma_f32_16x16x32_bf16 v[112:115], v[180:183], v[188:191], v[112:115]
	v_mfma_f32_16x16x32_bf16 v[116:119], v[176:179], v[192:195], v[116:119]
	v_mfma_f32_16x16x32_bf16 v[100:103], v[176:179], v[200:203], v[100:103]
	v_mfma_f32_16x16x32_bf16 v[84:87], v[176:179], v[208:211], v[84:87]
	v_mfma_f32_16x16x32_bf16 v[68:71], v[176:179], v[216:219], v[68:71]
	v_mfma_f32_16x16x32_bf16 v[64:67], v[184:187], v[216:219], v[64:67]
	v_mfma_f32_16x16x32_bf16 v[80:83], v[184:187], v[208:211], v[80:83]
	v_mfma_f32_16x16x32_bf16 v[96:99], v[184:187], v[200:203], v[96:99]
	v_mfma_f32_16x16x32_bf16 v[112:115], v[184:187], v[192:195], v[112:115]
	s_barrier
	s_setprio 0
	s_add_i32 s57, s45, s34
	v_lshl_add_u64 v[144:145], s[24:25], 0, v[132:133]
	s_mov_b32 m0, s57
	ds_read_b128 v[188:191], v151 offset:16384
	ds_read_b128 v[192:195], v151 offset:17408
	ds_read_b128 v[196:199], v151 offset:18432
	ds_read_b128 v[200:203], v151 offset:19456
	ds_read_b128 v[204:207], v151 offset:20480
	ds_read_b128 v[208:211], v151 offset:21504
	ds_read_b128 v[212:215], v151 offset:22528
	ds_read_b128 v[216:219], v151 offset:23552
	global_load_lds_dwordx4 v[144:145], off
	s_add_i32 m0, s57, 0x2000
	s_add_u32 s58, s24, 0x40000
	v_lshl_add_u64 v[164:165], s[24:25], 0, v[128:129]
	s_addc_u32 s59, s25, 0
	s_add_i32 s57, s46, s34
	global_load_lds_dwordx4 v[164:165], off
	v_lshl_add_u64 v[220:221], s[58:59], 0, v[132:133]
	s_mov_b32 m0, s57
	v_lshl_add_u64 v[222:223], s[26:27], 0, v[130:131]
	global_load_lds_dwordx4 v[220:221], off
	v_lshl_add_u64 v[220:221], s[58:59], 0, v[128:129]
	s_add_i32 m0, s57, 0x2000
	s_nop 0
	global_load_lds_dwordx4 v[220:221], off
	v_lshl_add_u64 v[220:221], s[26:27], 0, v[134:135]
	s_mov_b32 m0, s21
	s_nop 0
	global_load_lds_dwordx4 v[220:221], off
	s_mov_b32 m0, s37
	s_nop 0
	global_load_lds_dwordx4 v[222:223], off
	s_waitcnt vmcnt(8)
	s_waitcnt lgkmcnt(0)
	s_setprio 1
	s_barrier
; #define PG8_STAGE(bufoff, gbase, voff) do { _Pragma("unroll") for (int _i = 0; _i < 2; ++_i) \
;         __builtin_amdgcn_global_load_lds((const unsigned*)((const char*)(gbase) + (voff)[_i]), (LAS unsigned*)(lds + (bufoff) + ldsw + _i * 8192), 16, 0, 0); } while (0)
; #define PG8_LDA(dst, b, h) do { _Pragma("unroll") for (int m = 0; m < 4; ++m) _Pragma("unroll") for (int k = 0; k < 2; ++k) dst[m][k] = *(const LAS bf16x8*)(lds + PG8_SA(b, h) + aoff + m * 2048 + k * 1024); } while (0)
; #define PG8_LDB(dst, b, h) do { _Pragma("unroll") for (int n = 0; n < 2; ++n) _Pragma("unroll") for (int k = 0; k < 2; ++k) dst[n][k] = *(const LAS bf16x8*)(lds + PG8_SB(b, h) + boff + n * 2048 + k * 1024); } while (0)
; #define PG8_MMA(ai, bj, At, Bt) do { __builtin_amdgcn_s_setprio(1); _Pragma("unroll") for (int m = 0; m < 4; ++m) _Pragma("unroll") for (int n = 0; n < 2; ++n) _Pragma("unroll") for (int k = 0; k < 2; ++k) \
;         acc[ai][bj][m][n] = __builtin_amdgcn_mfma_f32_16x16x32_bf16(Bt[n][k], At[m][k], acc[ai][bj][m][n], 0, 0, 0); __builtin_amdgcn_s_setprio(0); } while (0)
; #define PG8_WAIT_V(n) asm volatile("s_waitcnt vmcnt(" #n ")" ::: "memory")
; #define PG8_WAIT_L(n) asm volatile("s_waitcnt lgkmcnt(" #n ")" ::: "memory")
; #define PG8_BAR __builtin_amdgcn_s_barrier()
; #define PG8_SCHED __builtin_amdgcn_sched_barrier(0)
; template <class Epi, bool ALIGN_EPI>
; __device__ __forceinline__ void gemm_phase(LAS unsigned char* lds, const Gemm g, const StaticOrder& S, const Epi& E) {
;     ...
;             PG8_WAIT_V(8); PG8_WAIT_L(0); PG8_BAR; PG8_MMA(1, 0, At, B0); PG8_MMA(1, 1, At, B1); PG8_BAR; PG8_SCHED;
;             PG8_LDB(B0, 1, 0); PG8_LDB(B1, 1, 1); PG8_SCHED; PG8_LDA(At, 1, 0); PG8_STAGE(PG8_SA(0, 1), a2 + hstepA, voffA);
;             PG8_WAIT_V(8); PG8_WAIT_L(0); PG8_BAR; PG8_MMA(0, 0, At, B0); PG8_MMA(0, 1, At, B1); PG8_BAR; PG8_SCHED;
;             PG8_LDA(At, 1, 1); PG8_STAGE(PG8_SB(1, 0), b3, voffB); PG8_STAGE(PG8_SB(1, 1), b3 + hstepB, voffB); PG8_STAGE(PG8_SA(1, 0), a3, voffA);
	v_mfma_f32_16x16x32_bf16 v[60:63], v[152:155], v[188:191], v[60:63]
	v_mfma_f32_16x16x32_bf16 v[44:47], v[152:155], v[196:199], v[44:47]
	v_mfma_f32_16x16x32_bf16 v[28:31], v[152:155], v[204:207], v[28:31]
	v_mfma_f32_16x16x32_bf16 v[12:15], v[152:155], v[212:215], v[12:15]
	v_mfma_f32_16x16x32_bf16 v[8:11], v[160:163], v[212:215], v[8:11]
	v_mfma_f32_16x16x32_bf16 v[24:27], v[160:163], v[204:207], v[24:27]
	v_mfma_f32_16x16x32_bf16 v[40:43], v[160:163], v[196:199], v[40:43]
	v_mfma_f32_16x16x32_bf16 v[56:59], v[160:163], v[188:191], v[56:59]
	v_mfma_f32_16x16x32_bf16 v[60:63], v[156:159], v[192:195], v[60:63]
	v_mfma_f32_16x16x32_bf16 v[44:47], v[156:159], v[200:203], v[44:47]
	v_mfma_f32_16x16x32_bf16 v[28:31], v[156:159], v[208:211], v[28:31]
	v_mfma_f32_16x16x32_bf16 v[12:15], v[156:159], v[216:219], v[12:15]
	v_mfma_f32_16x16x32_bf16 v[8:11], v[168:171], v[216:219], v[8:11]
	v_mfma_f32_16x16x32_bf16 v[24:27], v[168:171], v[208:211], v[24:27]
	v_mfma_f32_16x16x32_bf16 v[40:43], v[168:171], v[200:203], v[40:43]
	v_mfma_f32_16x16x32_bf16 v[56:59], v[168:171], v[192:195], v[56:59]
	s_setprio 0
	s_setprio 1
	v_mfma_f32_16x16x32_bf16 v[52:55], v[172:175], v[188:191], v[52:55]
	v_mfma_f32_16x16x32_bf16 v[36:39], v[172:175], v[196:199], v[36:39]
	v_mfma_f32_16x16x32_bf16 v[20:23], v[172:175], v[204:207], v[20:23]
	v_mfma_f32_16x16x32_bf16 v[4:7], v[172:175], v[212:215], v[4:7]
	v_mfma_f32_16x16x32_bf16 v[0:3], v[180:183], v[212:215], v[0:3]
	v_mfma_f32_16x16x32_bf16 v[16:19], v[180:183], v[204:207], v[16:19]
	v_mfma_f32_16x16x32_bf16 v[32:35], v[180:183], v[196:199], v[32:35]
	v_mfma_f32_16x16x32_bf16 v[48:51], v[180:183], v[188:191], v[48:51]
	v_mfma_f32_16x16x32_bf16 v[52:55], v[176:179], v[192:195], v[52:55]
	v_mfma_f32_16x16x32_bf16 v[36:39], v[176:179], v[200:203], v[36:39]
	v_mfma_f32_16x16x32_bf16 v[20:23], v[176:179], v[208:211], v[20:23]
	v_mfma_f32_16x16x32_bf16 v[4:7], v[176:179], v[216:219], v[4:7]
	v_mfma_f32_16x16x32_bf16 v[0:3], v[184:187], v[216:219], v[0:3]
	v_mfma_f32_16x16x32_bf16 v[16:19], v[184:187], v[208:211], v[16:19]
	v_mfma_f32_16x16x32_bf16 v[32:35], v[184:187], v[200:203], v[32:35]
	v_mfma_f32_16x16x32_bf16 v[48:51], v[184:187], v[192:195], v[48:51]
	s_barrier
	s_setprio 0
	s_add_i32 s57, 0, 0x18000
	s_add_i32 s58, 0, 0x1c000
	v_add_u32_e32 v168, s57, v147
	v_add_u32_e32 v184, s58, v147
	ds_read_b128 v[152:155], v168
	ds_read_b128 v[156:159], v168 offset:1024
	ds_read_b128 v[160:163], v168 offset:2048
	ds_read_b128 v[168:171], v168 offset:3072
	ds_read_b128 v[172:175], v184
	ds_read_b128 v[176:179], v184 offset:1024
	ds_read_b128 v[180:183], v184 offset:2048
	ds_read_b128 v[184:187], v184 offset:3072
	s_add_u32 s26, s26, 0x80000
	s_addc_u32 s27, s27, 0
	s_mov_b32 m0, s38
	v_lshl_add_u64 v[224:225], s[26:27], 0, v[134:135]
	ds_read_b128 v[188:191], v151 offset:32768
	ds_read_b128 v[192:195], v151 offset:33792
	ds_read_b128 v[196:199], v151 offset:34816
	ds_read_b128 v[200:203], v151 offset:35840
	ds_read_b128 v[204:207], v151 offset:36864
	ds_read_b128 v[208:211], v151 offset:37888
	ds_read_b128 v[212:215], v151 offset:38912
	ds_read_b128 v[216:219], v151 offset:39936
	global_load_lds_dwordx4 v[224:225], off
	v_lshl_add_u64 v[224:225], s[26:27], 0, v[130:131]
	s_mov_b32 m0, s39
	s_nop 0
	global_load_lds_dwordx4 v[224:225], off
	s_waitcnt vmcnt(8)
	s_waitcnt lgkmcnt(0)
	s_setprio 1
	s_barrier
	v_mfma_f32_16x16x32_bf16 v[124:127], v[152:155], v[188:191], v[124:127]
	v_mfma_f32_16x16x32_bf16 v[108:111], v[152:155], v[196:199], v[108:111]
	v_mfma_f32_16x16x32_bf16 v[92:95], v[152:155], v[204:207], v[92:95]
	v_mfma_f32_16x16x32_bf16 v[76:79], v[152:155], v[212:215], v[76:79]
	v_mfma_f32_16x16x32_bf16 v[72:75], v[160:163], v[212:215], v[72:75]
	v_mfma_f32_16x16x32_bf16 v[88:91], v[160:163], v[204:207], v[88:91]
	v_mfma_f32_16x16x32_bf16 v[104:107], v[160:163], v[196:199], v[104:107]
	v_mfma_f32_16x16x32_bf16 v[120:123], v[160:163], v[188:191], v[120:123]
	v_mfma_f32_16x16x32_bf16 v[124:127], v[156:159], v[192:195], v[124:127]
	v_mfma_f32_16x16x32_bf16 v[108:111], v[156:159], v[200:203], v[108:111]
	v_mfma_f32_16x16x32_bf16 v[92:95], v[156:159], v[208:211], v[92:95]
	v_mfma_f32_16x16x32_bf16 v[76:79], v[156:159], v[216:219], v[76:79]
	v_mfma_f32_16x16x32_bf16 v[72:75], v[168:171], v[216:219], v[72:75]
	v_mfma_f32_16x16x32_bf16 v[88:91], v[168:171], v[208:211], v[88:91]
	v_mfma_f32_16x16x32_bf16 v[104:107], v[168:171], v[200:203], v[104:107]
	v_mfma_f32_16x16x32_bf16 v[120:123], v[168:171], v[192:195], v[120:123]
	s_setprio 0
	s_setprio 1
	v_mfma_f32_16x16x32_bf16 v[116:119], v[172:175], v[188:191], v[116:119]
	v_mfma_f32_16x16x32_bf16 v[100:103], v[172:175], v[196:199], v[100:103]
	v_mfma_f32_16x16x32_bf16 v[84:87], v[172:175], v[204:207], v[84:87]
	v_mfma_f32_16x16x32_bf16 v[68:71], v[172:175], v[212:215], v[68:71]
	v_mfma_f32_16x16x32_bf16 v[64:67], v[180:183], v[212:215], v[64:67]
	v_mfma_f32_16x16x32_bf16 v[80:83], v[180:183], v[204:207], v[80:83]
	v_mfma_f32_16x16x32_bf16 v[96:99], v[180:183], v[196:199], v[96:99]
	v_mfma_f32_16x16x32_bf16 v[112:115], v[180:183], v[188:191], v[112:115]
	v_mfma_f32_16x16x32_bf16 v[116:119], v[176:179], v[192:195], v[116:119]
	v_mfma_f32_16x16x32_bf16 v[100:103], v[176:179], v[200:203], v[100:103]
	v_mfma_f32_16x16x32_bf16 v[84:87], v[176:179], v[208:211], v[84:87]
	v_mfma_f32_16x16x32_bf16 v[68:71], v[176:179], v[216:219], v[68:71]
	v_mfma_f32_16x16x32_bf16 v[64:67], v[184:187], v[216:219], v[64:67]
	v_mfma_f32_16x16x32_bf16 v[80:83], v[184:187], v[208:211], v[80:83]
	v_mfma_f32_16x16x32_bf16 v[96:99], v[184:187], v[200:203], v[96:99]
	v_mfma_f32_16x16x32_bf16 v[112:115], v[184:187], v[192:195], v[112:115]
	s_barrier
; #define PG8_STAGE(bufoff, gbase, voff) do { _Pragma("unroll") for (int _i = 0; _i < 2; ++_i) \
;         __builtin_amdgcn_global_load_lds((const unsigned*)((const char*)(gbase) + (voff)[_i]), (LAS unsigned*)(lds + (bufoff) + ldsw + _i * 8192), 16, 0, 0); } while (0)
; #define PG8_LDA(dst, b, h) do { _Pragma("unroll") for (int m = 0; m < 4; ++m) _Pragma("unroll") for (int k = 0; k < 2; ++k) dst[m][k] = *(const LAS bf16x8*)(lds + PG8_SA(b, h) + aoff + m * 2048 + k * 1024); } while (0)
; #define PG8_MMA(ai, bj, At, Bt) do { __builtin_amdgcn_s_setprio(1); _Pragma("unroll") for (int m = 0; m < 4; ++m) _Pragma("unroll") for (int n = 0; n < 2; ++n) _Pragma("unroll") for (int k = 0; k < 2; ++k) \
;         acc[ai][bj][m][n] = __builtin_amdgcn_mfma_f32_16x16x32_bf16(Bt[n][k], At[m][k], acc[ai][bj][m][n], 0, 0, 0); __builtin_amdgcn_s_setprio(0); } while (0)
; #define PG8_WAIT_V(n) asm volatile("s_waitcnt vmcnt(" #n ")" ::: "memory")
; #define PG8_WAIT_L(n) asm volatile("s_waitcnt lgkmcnt(" #n ")" ::: "memory")
; #define PG8_BAR __builtin_amdgcn_s_barrier()
; #define PG8_SCHED __builtin_amdgcn_sched_barrier(0)
; template <class Epi, bool ALIGN_EPI>
; __device__ __forceinline__ void gemm_phase(LAS unsigned char* lds, const Gemm g, const StaticOrder& S, const Epi& E) {
;     ...
;             PG8_LDA(At, 1, 1); PG8_STAGE(PG8_SB(1, 0), b3, voffB); PG8_STAGE(PG8_SB(1, 1), b3 + hstepB, voffB); PG8_STAGE(PG8_SA(1, 0), a3, voffA);
;             PG8_WAIT_V(8); PG8_WAIT_L(0); PG8_BAR; PG8_MMA(1, 0, At, B0); PG8_MMA(1, 1, At, B1); PG8_BAR; PG8_SCHED;
;         }
	s_setprio 0
	s_add_i32 s26, s57, s34
	v_lshl_add_u64 v[144:145], v[144:145], 0, s[8:9]
	s_mov_b32 m0, s26
	ds_read_b128 v[188:191], v151 offset:49152
	ds_read_b128 v[192:195], v151 offset:50176
	ds_read_b128 v[196:199], v151 offset:51200
	ds_read_b128 v[200:203], v151 offset:52224
	ds_read_b128 v[204:207], v151 offset:53248
	ds_read_b128 v[208:211], v151 offset:54272
	ds_read_b128 v[212:215], v151 offset:55296
	ds_read_b128 v[216:219], v151 offset:56320
	global_load_lds_dwordx4 v[144:145], off
	s_add_i32 m0, s26, 0x2000
	s_add_u32 s24, s24, 0x40080
	v_lshl_add_u64 v[144:145], v[164:165], 0, s[8:9]
	s_addc_u32 s25, s25, 0
	s_add_i32 s26, s58, s34
	global_load_lds_dwordx4 v[144:145], off
	v_lshl_add_u64 v[144:145], s[24:25], 0, v[132:133]
	s_mov_b32 m0, s26
	s_nop 0
	global_load_lds_dwordx4 v[144:145], off
	v_lshl_add_u64 v[144:145], s[24:25], 0, v[128:129]
	s_add_i32 m0, s26, 0x2000
	s_nop 0
	global_load_lds_dwordx4 v[144:145], off
	v_lshl_add_u64 v[144:145], v[220:221], 0, s[8:9]
	s_mov_b32 m0, s40
	s_nop 0
	global_load_lds_dwordx4 v[144:145], off
	v_lshl_add_u64 v[144:145], v[222:223], 0, s[8:9]
	s_mov_b32 m0, s41
	s_nop 0
	global_load_lds_dwordx4 v[144:145], off
	s_waitcnt vmcnt(8)
	s_waitcnt lgkmcnt(0)
	s_setprio 1
	s_barrier
	v_mfma_f32_16x16x32_bf16 v[60:63], v[152:155], v[188:191], v[60:63]
	v_mfma_f32_16x16x32_bf16 v[44:47], v[152:155], v[196:199], v[44:47]
	v_mfma_f32_16x16x32_bf16 v[28:31], v[152:155], v[204:207], v[28:31]
	v_mfma_f32_16x16x32_bf16 v[12:15], v[152:155], v[212:215], v[12:15]
	v_mfma_f32_16x16x32_bf16 v[8:11], v[160:163], v[212:215], v[8:11]
	v_mfma_f32_16x16x32_bf16 v[24:27], v[160:163], v[204:207], v[24:27]
	v_mfma_f32_16x16x32_bf16 v[40:43], v[160:163], v[196:199], v[40:43]
	v_mfma_f32_16x16x32_bf16 v[56:59], v[160:163], v[188:191], v[56:59]
	v_mfma_f32_16x16x32_bf16 v[60:63], v[156:159], v[192:195], v[60:63]
	v_mfma_f32_16x16x32_bf16 v[44:47], v[156:159], v[200:203], v[44:47]
	v_mfma_f32_16x16x32_bf16 v[28:31], v[156:159], v[208:211], v[28:31]
	v_mfma_f32_16x16x32_bf16 v[12:15], v[156:159], v[216:219], v[12:15]
	v_mfma_f32_16x16x32_bf16 v[8:11], v[168:171], v[216:219], v[8:11]
	v_mfma_f32_16x16x32_bf16 v[24:27], v[168:171], v[208:211], v[24:27]
	v_mfma_f32_16x16x32_bf16 v[40:43], v[168:171], v[200:203], v[40:43]
	v_mfma_f32_16x16x32_bf16 v[56:59], v[168:171], v[192:195], v[56:59]
	s_setprio 0
	s_setprio 1
	v_mfma_f32_16x16x32_bf16 v[52:55], v[172:175], v[188:191], v[52:55]
	v_mfma_f32_16x16x32_bf16 v[36:39], v[172:175], v[196:199], v[36:39]
	v_mfma_f32_16x16x32_bf16 v[20:23], v[172:175], v[204:207], v[20:23]
	v_mfma_f32_16x16x32_bf16 v[4:7], v[172:175], v[212:215], v[4:7]
	v_mfma_f32_16x16x32_bf16 v[0:3], v[180:183], v[212:215], v[0:3]
	v_mfma_f32_16x16x32_bf16 v[16:19], v[180:183], v[204:207], v[16:19]
	v_mfma_f32_16x16x32_bf16 v[32:35], v[180:183], v[196:199], v[32:35]
	v_mfma_f32_16x16x32_bf16 v[48:51], v[180:183], v[188:191], v[48:51]
	v_mfma_f32_16x16x32_bf16 v[52:55], v[176:179], v[192:195], v[52:55]
	v_mfma_f32_16x16x32_bf16 v[36:39], v[176:179], v[200:203], v[36:39]
	v_mfma_f32_16x16x32_bf16 v[20:23], v[176:179], v[208:211], v[20:23]
	v_mfma_f32_16x16x32_bf16 v[4:7], v[176:179], v[216:219], v[4:7]
	v_mfma_f32_16x16x32_bf16 v[0:3], v[184:187], v[216:219], v[0:3]
	v_mfma_f32_16x16x32_bf16 v[16:19], v[184:187], v[208:211], v[16:19]
	v_mfma_f32_16x16x32_bf16 v[32:35], v[184:187], v[200:203], v[32:35]
	v_mfma_f32_16x16x32_bf16 v[48:51], v[184:187], v[192:195], v[48:51]
	s_barrier
	s_setprio 0
	s_add_i32 s56, s56, 2
	s_add_u32 s54, s54, 0x100
	s_addc_u32 s55, s55, 0
	s_add_u32 s22, s22, 0x100
	s_addc_u32 s23, s23, 0
	s_cmp_gt_u32 s56, 13
	s_cbranch_scc0 .LBB0_817
	s_and_b64 vcc, exec, s[10:11]
	s_cbranch_vccz .LBB0_820
	s_barrier

; #define PG8_STAGE(bufoff, gbase, voff) do { _Pragma("unroll") for (int _i = 0; _i < 2; ++_i) \
;         __builtin_amdgcn_global_load_lds((const unsigned*)((const char*)(gbase) + (voff)[_i]), (LAS unsigned*)(lds + (bufoff) + ldsw + _i * 8192), 16, 0, 0); } while (0)
; #define PG8_LDA(dst, b, h) do { _Pragma("unroll") for (int m = 0; m < 4; ++m) _Pragma("unroll") for (int k = 0; k < 2; ++k) dst[m][k] = *(const LAS bf16x8*)(lds + PG8_SA(b, h) + aoff + m * 2048 + k * 1024); } while (0)
; #define PG8_LDB(dst, b, h) do { _Pragma("unroll") for (int n = 0; n < 2; ++n) _Pragma("unroll") for (int k = 0; k < 2; ++k) dst[n][k] = *(const LAS bf16x8*)(lds + PG8_SB(b, h) + boff + n * 2048 + k * 1024); } while (0)
; #define PG8_MMA(ai, bj, At, Bt) do { __builtin_amdgcn_s_setprio(1); _Pragma("unroll") for (int m = 0; m < 4; ++m) _Pragma("unroll") for (int n = 0; n < 2; ++n) _Pragma("unroll") for (int k = 0; k < 2; ++k) \
;         acc[ai][bj][m][n] = __builtin_amdgcn_mfma_f32_16x16x32_bf16(Bt[n][k], At[m][k], acc[ai][bj][m][n], 0, 0, 0); __builtin_amdgcn_s_setprio(0); } while (0)
; #define PG8_WAIT_V(n) asm volatile("s_waitcnt vmcnt(" #n ")" ::: "memory")
; #define PG8_WAIT_L(n) asm volatile("s_waitcnt lgkmcnt(" #n ")" ::: "memory")
; #define PG8_BAR __builtin_amdgcn_s_barrier()
; #define PG8_SCHED __builtin_amdgcn_sched_barrier(0)
; template <class Epi, bool ALIGN_EPI>
; __device__ __forceinline__ void gemm_phase(LAS unsigned char* lds, const Gemm g, const StaticOrder& S, const Epi& E) {
;     ...
;             const bool last = (t == nt - 2);
;             const char* a1 = cA + (size_t)(t + 1) * kstep;
;             const char* a2 = last ? nA : cA + (size_t)(t + 2) * kstep; const char* b2 = last ? nB : cB + (size_t)(t + 2) * kstep;
;             const char* a3 = a2 + kstep; const char* b3 = b2 + kstep;
;             PG8_LDB(B0, 0, 0); PG8_LDB(B1, 0, 1); PG8_SCHED; PG8_LDA(At, 0, 0); PG8_STAGE(PG8_SA(1, 1), a1 + hstepA, voffA);
;             PG8_WAIT_V(8); PG8_WAIT_L(0); PG8_BAR; PG8_MMA(0, 0, At, B0); PG8_MMA(0, 1, At, B1); PG8_BAR; PG8_SCHED;
;             PG8_LDA(At, 0, 1); PG8_STAGE(PG8_SB(0, 0), b2, voffB); PG8_STAGE(PG8_SB(0, 1), b2 + hstepB, voffB); PG8_STAGE(PG8_SA(0, 0), a2, voffA);
;             PG8_WAIT_V(8); PG8_WAIT_L(0); PG8_BAR; PG8_MMA(1, 0, At, B0); PG8_MMA(1, 1, At, B1); PG8_BAR; PG8_SCHED;
.LBB0_1082:
	ds_read_b128 v[64:67], v169
	ds_read_b128 v[72:75], v169 offset:1024
	ds_read_b128 v[76:79], v169 offset:2048
	ds_read_b128 v[84:87], v169 offset:3072
	ds_read_b128 v[156:159], v170
	ds_read_b128 v[160:163], v170 offset:1024
	ds_read_b128 v[174:177], v170 offset:2048
	ds_read_b128 v[178:181], v170 offset:3072
	s_add_u32 s38, s36, 0xfff80080
	s_addc_u32 s39, s37, -1
	s_cmp_eq_u32 s61, 28
	s_cselect_b32 s41, s5, s39
	s_cselect_b32 s40, s27, s38
	s_cselect_b32 s39, s25, s60
	s_cselect_b32 s38, s35, s59
	v_lshl_add_u64 v[214:215], s[36:37], 0, v[150:151]
	s_add_i32 m0, s45, 0xc000
	ds_read_b128 v[182:185], v171
	ds_read_b128 v[186:189], v171 offset:1024
	ds_read_b128 v[190:193], v171 offset:2048
	ds_read_b128 v[194:197], v171 offset:3072
	ds_read_b128 v[198:201], v171 offset:4096
	ds_read_b128 v[202:205], v171 offset:5120
	ds_read_b128 v[206:209], v171 offset:6144
	ds_read_b128 v[210:213], v171 offset:7168
	global_load_lds_dwordx4 v[214:215], off
	v_lshl_add_u64 v[214:215], s[36:37], 0, v[148:149]
	s_add_i32 m0, s45, 0xe000
	s_nop 0
	global_load_lds_dwordx4 v[214:215], off
	s_waitcnt vmcnt(8)
	s_waitcnt lgkmcnt(0)
	s_setprio 1
	s_barrier
	v_mfma_f32_16x16x32_bf16 v[140:143], v[64:67], v[182:185], v[140:143]
	v_mfma_f32_16x16x32_bf16 v[124:127], v[64:67], v[190:193], v[124:127]
	v_mfma_f32_16x16x32_bf16 v[108:111], v[64:67], v[198:201], v[108:111]
	v_mfma_f32_16x16x32_bf16 v[92:95], v[64:67], v[206:209], v[92:95]
	v_mfma_f32_16x16x32_bf16 v[88:91], v[76:79], v[206:209], v[88:91]
	v_mfma_f32_16x16x32_bf16 v[104:107], v[76:79], v[198:201], v[104:107]
	v_mfma_f32_16x16x32_bf16 v[120:123], v[76:79], v[190:193], v[120:123]
	v_mfma_f32_16x16x32_bf16 v[136:139], v[76:79], v[182:185], v[136:139]
	v_mfma_f32_16x16x32_bf16 v[140:143], v[72:75], v[186:189], v[140:143]
	v_mfma_f32_16x16x32_bf16 v[124:127], v[72:75], v[194:197], v[124:127]
	v_mfma_f32_16x16x32_bf16 v[108:111], v[72:75], v[202:205], v[108:111]
	v_mfma_f32_16x16x32_bf16 v[92:95], v[72:75], v[210:213], v[92:95]
	v_mfma_f32_16x16x32_bf16 v[88:91], v[84:87], v[210:213], v[88:91]
	v_mfma_f32_16x16x32_bf16 v[104:107], v[84:87], v[202:205], v[104:107]
	v_mfma_f32_16x16x32_bf16 v[120:123], v[84:87], v[194:197], v[120:123]
	v_mfma_f32_16x16x32_bf16 v[136:139], v[84:87], v[186:189], v[136:139]
	s_setprio 0
	s_setprio 1
	v_mfma_f32_16x16x32_bf16 v[132:135], v[156:159], v[182:185], v[132:135]
	v_mfma_f32_16x16x32_bf16 v[116:119], v[156:159], v[190:193], v[116:119]
	v_mfma_f32_16x16x32_bf16 v[100:103], v[156:159], v[198:201], v[100:103]
	v_mfma_f32_16x16x32_bf16 v[80:83], v[156:159], v[206:209], v[80:83]
	v_mfma_f32_16x16x32_bf16 v[68:71], v[174:177], v[206:209], v[68:71]
	v_mfma_f32_16x16x32_bf16 v[96:99], v[174:177], v[198:201], v[96:99]
	v_mfma_f32_16x16x32_bf16 v[112:115], v[174:177], v[190:193], v[112:115]
	v_mfma_f32_16x16x32_bf16 v[128:131], v[174:177], v[182:185], v[128:131]
	v_mfma_f32_16x16x32_bf16 v[132:135], v[160:163], v[186:189], v[132:135]
	v_mfma_f32_16x16x32_bf16 v[116:119], v[160:163], v[194:197], v[116:119]
	v_mfma_f32_16x16x32_bf16 v[100:103], v[160:163], v[202:205], v[100:103]
	v_mfma_f32_16x16x32_bf16 v[80:83], v[160:163], v[210:213], v[80:83]
	v_mfma_f32_16x16x32_bf16 v[68:71], v[178:181], v[210:213], v[68:71]
	v_mfma_f32_16x16x32_bf16 v[96:99], v[178:181], v[202:205], v[96:99]
	v_mfma_f32_16x16x32_bf16 v[112:115], v[178:181], v[194:197], v[112:115]
	v_mfma_f32_16x16x32_bf16 v[128:131], v[178:181], v[186:189], v[128:131]
	s_barrier
	s_setprio 0
	s_add_i32 s62, s56, s44
	v_lshl_add_u64 v[214:215], s[38:39], 0, v[144:145]
	s_mov_b32 m0, s62
	ds_read_b128 v[182:185], v171 offset:16384
	ds_read_b128 v[186:189], v171 offset:17408
	ds_read_b128 v[190:193], v171 offset:18432
	ds_read_b128 v[194:197], v171 offset:19456
	ds_read_b128 v[198:201], v171 offset:20480
	ds_read_b128 v[202:205], v171 offset:21504
	ds_read_b128 v[206:209], v171 offset:22528
	ds_read_b128 v[210:213], v171 offset:23552
	global_load_lds_dwordx4 v[214:215], off
	s_add_i32 m0, s62, 0x2000
	s_add_u32 s62, s38, 0x80000
	v_lshl_add_u64 v[216:217], s[38:39], 0, v[146:147]
	s_addc_u32 s63, s39, 0
	s_add_i32 s64, s57, s44
	global_load_lds_dwordx4 v[216:217], off
	v_lshl_add_u64 v[218:219], s[62:63], 0, v[144:145]
	s_mov_b32 m0, s64
	v_lshl_add_u64 v[220:221], s[40:41], 0, v[146:147]
	global_load_lds_dwordx4 v[218:219], off
	v_lshl_add_u64 v[218:219], s[62:63], 0, v[146:147]
	s_add_i32 m0, s64, 0x2000
	s_nop 0
	global_load_lds_dwordx4 v[218:219], off
	v_lshl_add_u64 v[218:219], s[40:41], 0, v[144:145]
	s_mov_b32 m0, s45
	s_nop 0
	global_load_lds_dwordx4 v[218:219], off
	s_mov_b32 m0, s46
	s_nop 0
	global_load_lds_dwordx4 v[220:221], off
	s_waitcnt vmcnt(8)
	s_waitcnt lgkmcnt(0)
	s_setprio 1
	s_barrier
; #define PG8_STAGE(bufoff, gbase, voff) do { _Pragma("unroll") for (int _i = 0; _i < 2; ++_i) \
;         __builtin_amdgcn_global_load_lds((const unsigned*)((const char*)(gbase) + (voff)[_i]), (LAS unsigned*)(lds + (bufoff) + ldsw + _i * 8192), 16, 0, 0); } while (0)
; #define PG8_LDA(dst, b, h) do { _Pragma("unroll") for (int m = 0; m < 4; ++m) _Pragma("unroll") for (int k = 0; k < 2; ++k) dst[m][k] = *(const LAS bf16x8*)(lds + PG8_SA(b, h) + aoff + m * 2048 + k * 1024); } while (0)
; #define PG8_LDB(dst, b, h) do { _Pragma("unroll") for (int n = 0; n < 2; ++n) _Pragma("unroll") for (int k = 0; k < 2; ++k) dst[n][k] = *(const LAS bf16x8*)(lds + PG8_SB(b, h) + boff + n * 2048 + k * 1024); } while (0)
; #define PG8_MMA(ai, bj, At, Bt) do { __builtin_amdgcn_s_setprio(1); _Pragma("unroll") for (int m = 0; m < 4; ++m) _Pragma("unroll") for (int n = 0; n < 2; ++n) _Pragma("unroll") for (int k = 0; k < 2; ++k) \
;         acc[ai][bj][m][n] = __builtin_amdgcn_mfma_f32_16x16x32_bf16(Bt[n][k], At[m][k], acc[ai][bj][m][n], 0, 0, 0); __builtin_amdgcn_s_setprio(0); } while (0)
; #define PG8_WAIT_V(n) asm volatile("s_waitcnt vmcnt(" #n ")" ::: "memory")
; #define PG8_WAIT_L(n) asm volatile("s_waitcnt lgkmcnt(" #n ")" ::: "memory")
; #define PG8_BAR __builtin_amdgcn_s_barrier()
; #define PG8_SCHED __builtin_amdgcn_sched_barrier(0)
; template <class Epi, bool ALIGN_EPI>
; __device__ __forceinline__ void gemm_phase(LAS unsigned char* lds, const Gemm g, const StaticOrder& S, const Epi& E) {
;     ...
;             PG8_WAIT_V(8); PG8_WAIT_L(0); PG8_BAR; PG8_MMA(1, 0, At, B0); PG8_MMA(1, 1, At, B1); PG8_BAR; PG8_SCHED;
;             PG8_LDB(B0, 1, 0); PG8_LDB(B1, 1, 1); PG8_SCHED; PG8_LDA(At, 1, 0); PG8_STAGE(PG8_SA(0, 1), a2 + hstepA, voffA);
;             PG8_WAIT_V(8); PG8_WAIT_L(0); PG8_BAR; PG8_MMA(0, 0, At, B0); PG8_MMA(0, 1, At, B1); PG8_BAR; PG8_SCHED;
;             PG8_LDA(At, 1, 1); PG8_STAGE(PG8_SB(1, 0), b3, voffB); PG8_STAGE(PG8_SB(1, 1), b3 + hstepB, voffB); PG8_STAGE(PG8_SA(1, 0), a3, voffA);
	v_mfma_f32_16x16x32_bf16 v[60:63], v[64:67], v[182:185], v[60:63]
	v_mfma_f32_16x16x32_bf16 v[44:47], v[64:67], v[190:193], v[44:47]
	v_mfma_f32_16x16x32_bf16 v[28:31], v[64:67], v[198:201], v[28:31]
	v_mfma_f32_16x16x32_bf16 v[12:15], v[64:67], v[206:209], v[12:15]
	v_mfma_f32_16x16x32_bf16 v[8:11], v[76:79], v[206:209], v[8:11]
	v_mfma_f32_16x16x32_bf16 v[24:27], v[76:79], v[198:201], v[24:27]
	v_mfma_f32_16x16x32_bf16 v[40:43], v[76:79], v[190:193], v[40:43]
	v_mfma_f32_16x16x32_bf16 v[56:59], v[76:79], v[182:185], v[56:59]
	v_mfma_f32_16x16x32_bf16 v[60:63], v[72:75], v[186:189], v[60:63]
	v_mfma_f32_16x16x32_bf16 v[44:47], v[72:75], v[194:197], v[44:47]
	v_mfma_f32_16x16x32_bf16 v[28:31], v[72:75], v[202:205], v[28:31]
	v_mfma_f32_16x16x32_bf16 v[12:15], v[72:75], v[210:213], v[12:15]
	v_mfma_f32_16x16x32_bf16 v[8:11], v[84:87], v[210:213], v[8:11]
	v_mfma_f32_16x16x32_bf16 v[24:27], v[84:87], v[202:205], v[24:27]
	v_mfma_f32_16x16x32_bf16 v[40:43], v[84:87], v[194:197], v[40:43]
	v_mfma_f32_16x16x32_bf16 v[56:59], v[84:87], v[186:189], v[56:59]
	s_setprio 0
	s_setprio 1
	v_mfma_f32_16x16x32_bf16 v[52:55], v[156:159], v[182:185], v[52:55]
	v_mfma_f32_16x16x32_bf16 v[36:39], v[156:159], v[190:193], v[36:39]
	v_mfma_f32_16x16x32_bf16 v[20:23], v[156:159], v[198:201], v[20:23]
	v_mfma_f32_16x16x32_bf16 v[4:7], v[156:159], v[206:209], v[4:7]
	v_mfma_f32_16x16x32_bf16 v[0:3], v[174:177], v[206:209], v[0:3]
	v_mfma_f32_16x16x32_bf16 v[16:19], v[174:177], v[198:201], v[16:19]
	v_mfma_f32_16x16x32_bf16 v[32:35], v[174:177], v[190:193], v[32:35]
	v_mfma_f32_16x16x32_bf16 v[48:51], v[174:177], v[182:185], v[48:51]
	v_mfma_f32_16x16x32_bf16 v[52:55], v[160:163], v[186:189], v[52:55]
	v_mfma_f32_16x16x32_bf16 v[36:39], v[160:163], v[194:197], v[36:39]
	v_mfma_f32_16x16x32_bf16 v[20:23], v[160:163], v[202:205], v[20:23]
	v_mfma_f32_16x16x32_bf16 v[4:7], v[160:163], v[210:213], v[4:7]
	v_mfma_f32_16x16x32_bf16 v[0:3], v[178:181], v[210:213], v[0:3]
	v_mfma_f32_16x16x32_bf16 v[16:19], v[178:181], v[202:205], v[16:19]
	v_mfma_f32_16x16x32_bf16 v[32:35], v[178:181], v[194:197], v[32:35]
	v_mfma_f32_16x16x32_bf16 v[48:51], v[178:181], v[186:189], v[48:51]
	s_barrier
	s_setprio 0
	s_add_i32 s62, 0, 0x18000
	s_add_i32 s63, 0, 0x1c000
	v_add_u32_e32 v84, s62, v165
	v_add_u32_e32 v173, s63, v165
	ds_read_b128 v[64:67], v84
	ds_read_b128 v[72:75], v84 offset:1024
	ds_read_b128 v[76:79], v84 offset:2048
	ds_read_b128 v[84:87], v84 offset:3072
	ds_read_b128 v[156:159], v173
	ds_read_b128 v[160:163], v173 offset:1024
	ds_read_b128 v[174:177], v173 offset:2048
	ds_read_b128 v[178:181], v173 offset:3072
	s_add_u32 s40, s40, 0x80000
	s_addc_u32 s41, s41, 0
	s_mov_b32 m0, s47
	v_lshl_add_u64 v[222:223], s[40:41], 0, v[144:145]
	ds_read_b128 v[182:185], v171 offset:32768
	ds_read_b128 v[186:189], v171 offset:33792
	ds_read_b128 v[190:193], v171 offset:34816
	ds_read_b128 v[194:197], v171 offset:35840
	ds_read_b128 v[198:201], v171 offset:36864
	ds_read_b128 v[202:205], v171 offset:37888
	ds_read_b128 v[206:209], v171 offset:38912
	ds_read_b128 v[210:213], v171 offset:39936
	global_load_lds_dwordx4 v[222:223], off
	v_lshl_add_u64 v[222:223], s[40:41], 0, v[146:147]
	s_mov_b32 m0, s48
	s_nop 0
	global_load_lds_dwordx4 v[222:223], off
	s_waitcnt vmcnt(8)
	s_waitcnt lgkmcnt(0)
	s_setprio 1
	s_barrier
	v_mfma_f32_16x16x32_bf16 v[140:143], v[64:67], v[182:185], v[140:143]
	v_mfma_f32_16x16x32_bf16 v[124:127], v[64:67], v[190:193], v[124:127]
	v_mfma_f32_16x16x32_bf16 v[108:111], v[64:67], v[198:201], v[108:111]
	v_mfma_f32_16x16x32_bf16 v[92:95], v[64:67], v[206:209], v[92:95]
	v_mfma_f32_16x16x32_bf16 v[88:91], v[76:79], v[206:209], v[88:91]
	v_mfma_f32_16x16x32_bf16 v[104:107], v[76:79], v[198:201], v[104:107]
	v_mfma_f32_16x16x32_bf16 v[120:123], v[76:79], v[190:193], v[120:123]
	v_mfma_f32_16x16x32_bf16 v[136:139], v[76:79], v[182:185], v[136:139]
	v_mfma_f32_16x16x32_bf16 v[140:143], v[72:75], v[186:189], v[140:143]
	v_mfma_f32_16x16x32_bf16 v[124:127], v[72:75], v[194:197], v[124:127]
	v_mfma_f32_16x16x32_bf16 v[108:111], v[72:75], v[202:205], v[108:111]
	v_mfma_f32_16x16x32_bf16 v[92:95], v[72:75], v[210:213], v[92:95]
	v_mfma_f32_16x16x32_bf16 v[88:91], v[84:87], v[210:213], v[88:91]
	v_mfma_f32_16x16x32_bf16 v[104:107], v[84:87], v[202:205], v[104:107]
	v_mfma_f32_16x16x32_bf16 v[120:123], v[84:87], v[194:197], v[120:123]
	v_mfma_f32_16x16x32_bf16 v[136:139], v[84:87], v[186:189], v[136:139]
	s_setprio 0
	s_setprio 1
	v_mfma_f32_16x16x32_bf16 v[132:135], v[156:159], v[182:185], v[132:135]
	v_mfma_f32_16x16x32_bf16 v[116:119], v[156:159], v[190:193], v[116:119]
	v_mfma_f32_16x16x32_bf16 v[100:103], v[156:159], v[198:201], v[100:103]
	v_mfma_f32_16x16x32_bf16 v[80:83], v[156:159], v[206:209], v[80:83]
	v_mfma_f32_16x16x32_bf16 v[68:71], v[174:177], v[206:209], v[68:71]
	v_mfma_f32_16x16x32_bf16 v[96:99], v[174:177], v[198:201], v[96:99]
	v_mfma_f32_16x16x32_bf16 v[112:115], v[174:177], v[190:193], v[112:115]
	v_mfma_f32_16x16x32_bf16 v[128:131], v[174:177], v[182:185], v[128:131]
	v_mfma_f32_16x16x32_bf16 v[132:135], v[160:163], v[186:189], v[132:135]
	v_mfma_f32_16x16x32_bf16 v[116:119], v[160:163], v[194:197], v[116:119]
	v_mfma_f32_16x16x32_bf16 v[100:103], v[160:163], v[202:205], v[100:103]
	v_mfma_f32_16x16x32_bf16 v[80:83], v[160:163], v[210:213], v[80:83]
	v_mfma_f32_16x16x32_bf16 v[68:71], v[178:181], v[210:213], v[68:71]
	v_mfma_f32_16x16x32_bf16 v[96:99], v[178:181], v[202:205], v[96:99]
	v_mfma_f32_16x16x32_bf16 v[112:115], v[178:181], v[194:197], v[112:115]
	v_mfma_f32_16x16x32_bf16 v[128:131], v[178:181], v[186:189], v[128:131]
	s_barrier
; #define PG8_STAGE(bufoff, gbase, voff) do { _Pragma("unroll") for (int _i = 0; _i < 2; ++_i) \
;         __builtin_amdgcn_global_load_lds((const unsigned*)((const char*)(gbase) + (voff)[_i]), (LAS unsigned*)(lds + (bufoff) + ldsw + _i * 8192), 16, 0, 0); } while (0)
; #define PG8_LDA(dst, b, h) do { _Pragma("unroll") for (int m = 0; m < 4; ++m) _Pragma("unroll") for (int k = 0; k < 2; ++k) dst[m][k] = *(const LAS bf16x8*)(lds + PG8_SA(b, h) + aoff + m * 2048 + k * 1024); } while (0)
; #define PG8_MMA(ai, bj, At, Bt) do { __builtin_amdgcn_s_setprio(1); _Pragma("unroll") for (int m = 0; m < 4; ++m) _Pragma("unroll") for (int n = 0; n < 2; ++n) _Pragma("unroll") for (int k = 0; k < 2; ++k) \
;         acc[ai][bj][m][n] = __builtin_amdgcn_mfma_f32_16x16x32_bf16(Bt[n][k], At[m][k], acc[ai][bj][m][n], 0, 0, 0); __builtin_amdgcn_s_setprio(0); } while (0)
; #define PG8_WAIT_V(n) asm volatile("s_waitcnt vmcnt(" #n ")" ::: "memory")
; #define PG8_WAIT_L(n) asm volatile("s_waitcnt lgkmcnt(" #n ")" ::: "memory")
; #define PG8_BAR __builtin_amdgcn_s_barrier()
; #define PG8_SCHED __builtin_amdgcn_sched_barrier(0)
; template <class Epi, bool ALIGN_EPI>
; __device__ __forceinline__ void gemm_phase(LAS unsigned char* lds, const Gemm g, const StaticOrder& S, const Epi& E) {
;     ...
;             PG8_LDA(At, 1, 1); PG8_STAGE(PG8_SB(1, 0), b3, voffB); PG8_STAGE(PG8_SB(1, 1), b3 + hstepB, voffB); PG8_STAGE(PG8_SA(1, 0), a3, voffA);
;             PG8_WAIT_V(8); PG8_WAIT_L(0); PG8_BAR; PG8_MMA(1, 0, At, B0); PG8_MMA(1, 1, At, B1); PG8_BAR; PG8_SCHED;
;         }
	s_setprio 0
	s_add_i32 s40, s62, s44
	v_lshl_add_u64 v[214:215], v[214:215], 0, s[18:19]
	s_mov_b32 m0, s40
	ds_read_b128 v[182:185], v171 offset:49152
	ds_read_b128 v[186:189], v171 offset:50176
	ds_read_b128 v[190:193], v171 offset:51200
	ds_read_b128 v[194:197], v171 offset:52224
	ds_read_b128 v[198:201], v171 offset:53248
	ds_read_b128 v[202:205], v171 offset:54272
	ds_read_b128 v[206:209], v171 offset:55296
	ds_read_b128 v[210:213], v171 offset:56320
	global_load_lds_dwordx4 v[214:215], off
	s_add_i32 m0, s40, 0x2000
	s_add_u32 s38, s38, 0x80080
	v_lshl_add_u64 v[214:215], v[216:217], 0, s[18:19]
	s_addc_u32 s39, s39, 0
	s_add_i32 s40, s63, s44
	global_load_lds_dwordx4 v[214:215], off
	v_lshl_add_u64 v[214:215], s[38:39], 0, v[144:145]
	s_mov_b32 m0, s40
	s_nop 0
	global_load_lds_dwordx4 v[214:215], off
	v_lshl_add_u64 v[214:215], s[38:39], 0, v[146:147]
	s_add_i32 m0, s40, 0x2000
	s_nop 0
	global_load_lds_dwordx4 v[214:215], off
	v_lshl_add_u64 v[214:215], v[218:219], 0, s[18:19]
	s_mov_b32 m0, s50
	s_nop 0
	global_load_lds_dwordx4 v[214:215], off
	v_lshl_add_u64 v[214:215], v[220:221], 0, s[18:19]
	s_mov_b32 m0, s51
	s_nop 0
	global_load_lds_dwordx4 v[214:215], off
	s_waitcnt vmcnt(8)
	s_waitcnt lgkmcnt(0)
	s_setprio 1
	s_barrier
	v_mfma_f32_16x16x32_bf16 v[60:63], v[64:67], v[182:185], v[60:63]
	v_mfma_f32_16x16x32_bf16 v[44:47], v[64:67], v[190:193], v[44:47]
	v_mfma_f32_16x16x32_bf16 v[28:31], v[64:67], v[198:201], v[28:31]
	v_mfma_f32_16x16x32_bf16 v[12:15], v[64:67], v[206:209], v[12:15]
	v_mfma_f32_16x16x32_bf16 v[8:11], v[76:79], v[206:209], v[8:11]
	v_mfma_f32_16x16x32_bf16 v[24:27], v[76:79], v[198:201], v[24:27]
	v_mfma_f32_16x16x32_bf16 v[40:43], v[76:79], v[190:193], v[40:43]
	v_mfma_f32_16x16x32_bf16 v[56:59], v[76:79], v[182:185], v[56:59]
	v_mfma_f32_16x16x32_bf16 v[60:63], v[72:75], v[186:189], v[60:63]
	v_mfma_f32_16x16x32_bf16 v[44:47], v[72:75], v[194:197], v[44:47]
	v_mfma_f32_16x16x32_bf16 v[28:31], v[72:75], v[202:205], v[28:31]
	v_mfma_f32_16x16x32_bf16 v[12:15], v[72:75], v[210:213], v[12:15]
	v_mfma_f32_16x16x32_bf16 v[8:11], v[84:87], v[210:213], v[8:11]
	v_mfma_f32_16x16x32_bf16 v[24:27], v[84:87], v[202:205], v[24:27]
	v_mfma_f32_16x16x32_bf16 v[40:43], v[84:87], v[194:197], v[40:43]
	v_mfma_f32_16x16x32_bf16 v[56:59], v[84:87], v[186:189], v[56:59]
	s_setprio 0
	s_setprio 1
	v_mfma_f32_16x16x32_bf16 v[52:55], v[156:159], v[182:185], v[52:55]
	v_mfma_f32_16x16x32_bf16 v[36:39], v[156:159], v[190:193], v[36:39]
	v_mfma_f32_16x16x32_bf16 v[20:23], v[156:159], v[198:201], v[20:23]
	v_mfma_f32_16x16x32_bf16 v[4:7], v[156:159], v[206:209], v[4:7]
	v_mfma_f32_16x16x32_bf16 v[0:3], v[174:177], v[206:209], v[0:3]
	v_mfma_f32_16x16x32_bf16 v[16:19], v[174:177], v[198:201], v[16:19]
	v_mfma_f32_16x16x32_bf16 v[32:35], v[174:177], v[190:193], v[32:35]
	v_mfma_f32_16x16x32_bf16 v[48:51], v[174:177], v[182:185], v[48:51]
	v_mfma_f32_16x16x32_bf16 v[52:55], v[160:163], v[186:189], v[52:55]
	v_mfma_f32_16x16x32_bf16 v[36:39], v[160:163], v[194:197], v[36:39]
	v_mfma_f32_16x16x32_bf16 v[20:23], v[160:163], v[202:205], v[20:23]
	v_mfma_f32_16x16x32_bf16 v[4:7], v[160:163], v[210:213], v[4:7]
	v_mfma_f32_16x16x32_bf16 v[0:3], v[178:181], v[210:213], v[0:3]
	v_mfma_f32_16x16x32_bf16 v[16:19], v[178:181], v[202:205], v[16:19]
	v_mfma_f32_16x16x32_bf16 v[32:35], v[178:181], v[194:197], v[32:35]
	v_mfma_f32_16x16x32_bf16 v[48:51], v[178:181], v[186:189], v[48:51]
	s_barrier
	s_setprio 0
	s_add_i32 s61, s61, 2
	s_add_u32 s59, s59, 0x100
	s_addc_u32 s60, s60, 0
	s_add_u32 s36, s36, 0x100
	s_addc_u32 s37, s37, 0
	s_cmp_gt_u32 s61, 29
	s_cbranch_scc0 .LBB0_1082
	s_and_b64 vcc, exec, s[20:21]
	s_cbranch_vccz .LBB0_1085
	s_barrier

; #define PG8_STAGE(bufoff, gbase, voff) do { _Pragma("unroll") for (int _i = 0; _i < 2; ++_i) \
;         __builtin_amdgcn_global_load_lds((const unsigned*)((const char*)(gbase) + (voff)[_i]), (LAS unsigned*)(lds + (bufoff) + ldsw + _i * 8192), 16, 0, 0); } while (0)
; #define PG8_LDA(dst, b, h) do { _Pragma("unroll") for (int m = 0; m < 4; ++m) _Pragma("unroll") for (int k = 0; k < 2; ++k) dst[m][k] = *(const LAS bf16x8*)(lds + PG8_SA(b, h) + aoff + m * 2048 + k * 1024); } while (0)
; #define PG8_LDB(dst, b, h) do { _Pragma("unroll") for (int n = 0; n < 2; ++n) _Pragma("unroll") for (int k = 0; k < 2; ++k) dst[n][k] = *(const LAS bf16x8*)(lds + PG8_SB(b, h) + boff + n * 2048 + k * 1024); } while (0)
; #define PG8_MMA(ai, bj, At, Bt) do { __builtin_amdgcn_s_setprio(1); _Pragma("unroll") for (int m = 0; m < 4; ++m) _Pragma("unroll") for (int n = 0; n < 2; ++n) _Pragma("unroll") for (int k = 0; k < 2; ++k) \
;         acc[ai][bj][m][n] = __builtin_amdgcn_mfma_f32_16x16x32_bf16(Bt[n][k], At[m][k], acc[ai][bj][m][n], 0, 0, 0); __builtin_amdgcn_s_setprio(0); } while (0)
; #define PG8_WAIT_V(n) asm volatile("s_waitcnt vmcnt(" #n ")" ::: "memory")
; #define PG8_WAIT_L(n) asm volatile("s_waitcnt lgkmcnt(" #n ")" ::: "memory")
; #define PG8_BAR __builtin_amdgcn_s_barrier()
; #define PG8_SCHED __builtin_amdgcn_sched_barrier(0)
; template <class Epi, bool ALIGN_EPI>
; __device__ __forceinline__ void gemm_phase(LAS unsigned char* lds, const Gemm g, const StaticOrder& S, const Epi& E) {
;     ...
;             const bool last = (t == nt - 2);
;             const char* a1 = cA + (size_t)(t + 1) * kstep;
;             const char* a2 = last ? nA : cA + (size_t)(t + 2) * kstep; const char* b2 = last ? nB : cB + (size_t)(t + 2) * kstep;
;             const char* a3 = a2 + kstep; const char* b3 = b2 + kstep;
;             PG8_LDB(B0, 0, 0); PG8_LDB(B1, 0, 1); PG8_SCHED; PG8_LDA(At, 0, 0); PG8_STAGE(PG8_SA(1, 1), a1 + hstepA, voffA);
;             PG8_WAIT_V(8); PG8_WAIT_L(0); PG8_BAR; PG8_MMA(0, 0, At, B0); PG8_MMA(0, 1, At, B1); PG8_BAR; PG8_SCHED;
;             PG8_LDA(At, 0, 1); PG8_STAGE(PG8_SB(0, 0), b2, voffB); PG8_STAGE(PG8_SB(0, 1), b2 + hstepB, voffB); PG8_STAGE(PG8_SA(0, 0), a2, voffA);
.LBB0_1293:
	ds_read_b128 v[144:147], v156
	ds_read_b128 v[148:151], v156 offset:1024
	ds_read_b128 v[160:163], v156 offset:2048
	ds_read_b128 v[168:171], v156 offset:3072
	ds_read_b128 v[172:175], v157
	ds_read_b128 v[176:179], v157 offset:1024
	ds_read_b128 v[180:183], v157 offset:2048
	ds_read_b128 v[184:187], v157 offset:3072
	s_add_u32 s26, s24, 0xfff80080
	s_addc_u32 s27, s25, -1
	s_cmp_eq_u32 s56, 28
	s_cselect_b32 s29, s19, s27
	s_cselect_b32 s28, s52, s26
	s_cselect_b32 s27, s17, s55
	s_cselect_b32 s26, s53, s54
	v_lshl_add_u64 v[164:165], s[24:25], 0, v[138:139]
	s_add_i32 m0, s38, 0xc000
	ds_read_b128 v[188:191], v158
	ds_read_b128 v[192:195], v158 offset:1024
	ds_read_b128 v[196:199], v158 offset:2048
	ds_read_b128 v[200:203], v158 offset:3072
	ds_read_b128 v[204:207], v158 offset:4096
	ds_read_b128 v[208:211], v158 offset:5120
	ds_read_b128 v[212:215], v158 offset:6144
	ds_read_b128 v[216:219], v158 offset:7168
	global_load_lds_dwordx4 v[164:165], off
	v_lshl_add_u64 v[164:165], s[24:25], 0, v[136:137]
	s_add_i32 m0, s38, 0xe000
	s_nop 0
	global_load_lds_dwordx4 v[164:165], off
	s_waitcnt vmcnt(8)
	s_waitcnt lgkmcnt(0)
	s_setprio 1
	s_barrier
	v_mfma_f32_16x16x32_bf16 v[124:127], v[144:147], v[188:191], v[124:127]
	v_mfma_f32_16x16x32_bf16 v[108:111], v[144:147], v[196:199], v[108:111]
	v_mfma_f32_16x16x32_bf16 v[92:95], v[144:147], v[204:207], v[92:95]
	v_mfma_f32_16x16x32_bf16 v[76:79], v[144:147], v[212:215], v[76:79]
	v_mfma_f32_16x16x32_bf16 v[72:75], v[160:163], v[212:215], v[72:75]
	v_mfma_f32_16x16x32_bf16 v[88:91], v[160:163], v[204:207], v[88:91]
	v_mfma_f32_16x16x32_bf16 v[104:107], v[160:163], v[196:199], v[104:107]
	v_mfma_f32_16x16x32_bf16 v[120:123], v[160:163], v[188:191], v[120:123]
	v_mfma_f32_16x16x32_bf16 v[124:127], v[148:151], v[192:195], v[124:127]
	v_mfma_f32_16x16x32_bf16 v[108:111], v[148:151], v[200:203], v[108:111]
	v_mfma_f32_16x16x32_bf16 v[92:95], v[148:151], v[208:211], v[92:95]
	v_mfma_f32_16x16x32_bf16 v[76:79], v[148:151], v[216:219], v[76:79]
	v_mfma_f32_16x16x32_bf16 v[72:75], v[168:171], v[216:219], v[72:75]
	v_mfma_f32_16x16x32_bf16 v[88:91], v[168:171], v[208:211], v[88:91]
	v_mfma_f32_16x16x32_bf16 v[104:107], v[168:171], v[200:203], v[104:107]
	v_mfma_f32_16x16x32_bf16 v[120:123], v[168:171], v[192:195], v[120:123]
	s_setprio 0
	s_setprio 1
	v_mfma_f32_16x16x32_bf16 v[116:119], v[172:175], v[188:191], v[116:119]
	v_mfma_f32_16x16x32_bf16 v[100:103], v[172:175], v[196:199], v[100:103]
	v_mfma_f32_16x16x32_bf16 v[84:87], v[172:175], v[204:207], v[84:87]
	v_mfma_f32_16x16x32_bf16 v[68:71], v[172:175], v[212:215], v[68:71]
	v_mfma_f32_16x16x32_bf16 v[64:67], v[180:183], v[212:215], v[64:67]
	v_mfma_f32_16x16x32_bf16 v[80:83], v[180:183], v[204:207], v[80:83]
	v_mfma_f32_16x16x32_bf16 v[96:99], v[180:183], v[196:199], v[96:99]
	v_mfma_f32_16x16x32_bf16 v[112:115], v[180:183], v[188:191], v[112:115]
	v_mfma_f32_16x16x32_bf16 v[116:119], v[176:179], v[192:195], v[116:119]
	v_mfma_f32_16x16x32_bf16 v[100:103], v[176:179], v[200:203], v[100:103]
	v_mfma_f32_16x16x32_bf16 v[84:87], v[176:179], v[208:211], v[84:87]
	v_mfma_f32_16x16x32_bf16 v[68:71], v[176:179], v[216:219], v[68:71]
	v_mfma_f32_16x16x32_bf16 v[64:67], v[184:187], v[216:219], v[64:67]
	v_mfma_f32_16x16x32_bf16 v[80:83], v[184:187], v[208:211], v[80:83]
	v_mfma_f32_16x16x32_bf16 v[96:99], v[184:187], v[200:203], v[96:99]
	v_mfma_f32_16x16x32_bf16 v[112:115], v[184:187], v[192:195], v[112:115]
	s_barrier
	s_setprio 0
	s_add_i32 s57, s47, s35
	v_lshl_add_u64 v[164:165], s[26:27], 0, v[132:133]
	s_mov_b32 m0, s57
	ds_read_b128 v[188:191], v158 offset:16384
	ds_read_b128 v[192:195], v158 offset:17408
	ds_read_b128 v[196:199], v158 offset:18432
	ds_read_b128 v[200:203], v158 offset:19456
	ds_read_b128 v[204:207], v158 offset:20480
	ds_read_b128 v[208:211], v158 offset:21504
	ds_read_b128 v[212:215], v158 offset:22528
	ds_read_b128 v[216:219], v158 offset:23552
	global_load_lds_dwordx4 v[164:165], off
	s_add_i32 m0, s57, 0x2000
	s_add_u32 s58, s26, 0x80000
	v_lshl_add_u64 v[220:221], s[26:27], 0, v[128:129]
	s_addc_u32 s59, s27, 0
	s_add_i32 s57, s48, s35
	global_load_lds_dwordx4 v[220:221], off
	v_lshl_add_u64 v[222:223], s[58:59], 0, v[132:133]
	s_mov_b32 m0, s57
	v_lshl_add_u64 v[224:225], s[28:29], 0, v[130:131]
	global_load_lds_dwordx4 v[222:223], off
	v_lshl_add_u64 v[222:223], s[58:59], 0, v[128:129]
	s_add_i32 m0, s57, 0x2000
	s_nop 0
	global_load_lds_dwordx4 v[222:223], off
	v_lshl_add_u64 v[222:223], s[28:29], 0, v[134:135]
	s_mov_b32 m0, s38
	s_nop 0
	global_load_lds_dwordx4 v[222:223], off
	s_mov_b32 m0, s39
	s_nop 0
	global_load_lds_dwordx4 v[224:225], off
	s_waitcnt vmcnt(8)
	s_waitcnt lgkmcnt(0)
	s_setprio 1
	s_barrier
; #define PG8_STAGE(bufoff, gbase, voff) do { _Pragma("unroll") for (int _i = 0; _i < 2; ++_i) \
;         __builtin_amdgcn_global_load_lds((const unsigned*)((const char*)(gbase) + (voff)[_i]), (LAS unsigned*)(lds + (bufoff) + ldsw + _i * 8192), 16, 0, 0); } while (0)
; #define PG8_LDA(dst, b, h) do { _Pragma("unroll") for (int m = 0; m < 4; ++m) _Pragma("unroll") for (int k = 0; k < 2; ++k) dst[m][k] = *(const LAS bf16x8*)(lds + PG8_SA(b, h) + aoff + m * 2048 + k * 1024); } while (0)
; #define PG8_LDB(dst, b, h) do { _Pragma("unroll") for (int n = 0; n < 2; ++n) _Pragma("unroll") for (int k = 0; k < 2; ++k) dst[n][k] = *(const LAS bf16x8*)(lds + PG8_SB(b, h) + boff + n * 2048 + k * 1024); } while (0)
; #define PG8_MMA(ai, bj, At, Bt) do { __builtin_amdgcn_s_setprio(1); _Pragma("unroll") for (int m = 0; m < 4; ++m) _Pragma("unroll") for (int n = 0; n < 2; ++n) _Pragma("unroll") for (int k = 0; k < 2; ++k) \
;         acc[ai][bj][m][n] = __builtin_amdgcn_mfma_f32_16x16x32_bf16(Bt[n][k], At[m][k], acc[ai][bj][m][n], 0, 0, 0); __builtin_amdgcn_s_setprio(0); } while (0)
; #define PG8_WAIT_V(n) asm volatile("s_waitcnt vmcnt(" #n ")" ::: "memory")
; #define PG8_WAIT_L(n) asm volatile("s_waitcnt lgkmcnt(" #n ")" ::: "memory")
; #define PG8_BAR __builtin_amdgcn_s_barrier()
; #define PG8_SCHED __builtin_amdgcn_sched_barrier(0)
; template <class Epi, bool ALIGN_EPI>
; __device__ __forceinline__ void gemm_phase(LAS unsigned char* lds, const Gemm g, const StaticOrder& S, const Epi& E) {
;     ...
;             PG8_WAIT_V(8); PG8_WAIT_L(0); PG8_BAR; PG8_MMA(1, 0, At, B0); PG8_MMA(1, 1, At, B1); PG8_BAR; PG8_SCHED;
;             PG8_LDB(B0, 1, 0); PG8_LDB(B1, 1, 1); PG8_SCHED; PG8_LDA(At, 1, 0); PG8_STAGE(PG8_SA(0, 1), a2 + hstepA, voffA);
;             PG8_WAIT_V(8); PG8_WAIT_L(0); PG8_BAR; PG8_MMA(0, 0, At, B0); PG8_MMA(0, 1, At, B1); PG8_BAR; PG8_SCHED;
	v_mfma_f32_16x16x32_bf16 v[60:63], v[144:147], v[188:191], v[60:63]
	v_mfma_f32_16x16x32_bf16 v[44:47], v[144:147], v[196:199], v[44:47]
	v_mfma_f32_16x16x32_bf16 v[28:31], v[144:147], v[204:207], v[28:31]
	v_mfma_f32_16x16x32_bf16 v[12:15], v[144:147], v[212:215], v[12:15]
	v_mfma_f32_16x16x32_bf16 v[8:11], v[160:163], v[212:215], v[8:11]
	v_mfma_f32_16x16x32_bf16 v[24:27], v[160:163], v[204:207], v[24:27]
	v_mfma_f32_16x16x32_bf16 v[40:43], v[160:163], v[196:199], v[40:43]
	v_mfma_f32_16x16x32_bf16 v[56:59], v[160:163], v[188:191], v[56:59]
	v_mfma_f32_16x16x32_bf16 v[60:63], v[148:151], v[192:195], v[60:63]
	v_mfma_f32_16x16x32_bf16 v[44:47], v[148:151], v[200:203], v[44:47]
	v_mfma_f32_16x16x32_bf16 v[28:31], v[148:151], v[208:211], v[28:31]
	v_mfma_f32_16x16x32_bf16 v[12:15], v[148:151], v[216:219], v[12:15]
	v_mfma_f32_16x16x32_bf16 v[8:11], v[168:171], v[216:219], v[8:11]
	v_mfma_f32_16x16x32_bf16 v[24:27], v[168:171], v[208:211], v[24:27]
	v_mfma_f32_16x16x32_bf16 v[40:43], v[168:171], v[200:203], v[40:43]
	v_mfma_f32_16x16x32_bf16 v[56:59], v[168:171], v[192:195], v[56:59]
	s_setprio 0
	s_setprio 1
	v_mfma_f32_16x16x32_bf16 v[52:55], v[172:175], v[188:191], v[52:55]
	v_mfma_f32_16x16x32_bf16 v[36:39], v[172:175], v[196:199], v[36:39]
	v_mfma_f32_16x16x32_bf16 v[20:23], v[172:175], v[204:207], v[20:23]
	v_mfma_f32_16x16x32_bf16 v[4:7], v[172:175], v[212:215], v[4:7]
	v_mfma_f32_16x16x32_bf16 v[0:3], v[180:183], v[212:215], v[0:3]
	v_mfma_f32_16x16x32_bf16 v[16:19], v[180:183], v[204:207], v[16:19]
	v_mfma_f32_16x16x32_bf16 v[32:35], v[180:183], v[196:199], v[32:35]
	v_mfma_f32_16x16x32_bf16 v[48:51], v[180:183], v[188:191], v[48:51]
	v_mfma_f32_16x16x32_bf16 v[52:55], v[176:179], v[192:195], v[52:55]
	v_mfma_f32_16x16x32_bf16 v[36:39], v[176:179], v[200:203], v[36:39]
	v_mfma_f32_16x16x32_bf16 v[20:23], v[176:179], v[208:211], v[20:23]
	v_mfma_f32_16x16x32_bf16 v[4:7], v[176:179], v[216:219], v[4:7]
	v_mfma_f32_16x16x32_bf16 v[0:3], v[184:187], v[216:219], v[0:3]
	v_mfma_f32_16x16x32_bf16 v[16:19], v[184:187], v[208:211], v[16:19]
	v_mfma_f32_16x16x32_bf16 v[32:35], v[184:187], v[200:203], v[32:35]
	v_mfma_f32_16x16x32_bf16 v[48:51], v[184:187], v[192:195], v[48:51]
	s_barrier
	s_setprio 0
	s_add_i32 s57, 0, 0x18000
	s_add_i32 s58, 0, 0x1c000
	v_add_u32_e32 v168, s57, v154
	v_add_u32_e32 v184, s58, v154
	ds_read_b128 v[144:147], v168
	ds_read_b128 v[148:151], v168 offset:1024
	ds_read_b128 v[160:163], v168 offset:2048
	ds_read_b128 v[168:171], v168 offset:3072
	ds_read_b128 v[172:175], v184
	ds_read_b128 v[176:179], v184 offset:1024
	ds_read_b128 v[180:183], v184 offset:2048
	ds_read_b128 v[184:187], v184 offset:3072
	s_add_u32 s28, s28, 0x80000
	s_addc_u32 s29, s29, 0
	s_mov_b32 m0, s40
	v_lshl_add_u64 v[226:227], s[28:29], 0, v[134:135]
	ds_read_b128 v[188:191], v158 offset:32768
	ds_read_b128 v[192:195], v158 offset:33792
	ds_read_b128 v[196:199], v158 offset:34816
	ds_read_b128 v[200:203], v158 offset:35840
	ds_read_b128 v[204:207], v158 offset:36864
	ds_read_b128 v[208:211], v158 offset:37888
	ds_read_b128 v[212:215], v158 offset:38912
	ds_read_b128 v[216:219], v158 offset:39936
	global_load_lds_dwordx4 v[226:227], off
	v_lshl_add_u64 v[226:227], s[28:29], 0, v[130:131]
	s_mov_b32 m0, s41
	s_nop 0
	global_load_lds_dwordx4 v[226:227], off
	s_waitcnt vmcnt(8)
	s_waitcnt lgkmcnt(0)
	s_setprio 1
	s_barrier
	v_mfma_f32_16x16x32_bf16 v[124:127], v[144:147], v[188:191], v[124:127]
	v_mfma_f32_16x16x32_bf16 v[108:111], v[144:147], v[196:199], v[108:111]
	v_mfma_f32_16x16x32_bf16 v[92:95], v[144:147], v[204:207], v[92:95]
	v_mfma_f32_16x16x32_bf16 v[76:79], v[144:147], v[212:215], v[76:79]
	v_mfma_f32_16x16x32_bf16 v[72:75], v[160:163], v[212:215], v[72:75]
	v_mfma_f32_16x16x32_bf16 v[88:91], v[160:163], v[204:207], v[88:91]
	v_mfma_f32_16x16x32_bf16 v[104:107], v[160:163], v[196:199], v[104:107]
	v_mfma_f32_16x16x32_bf16 v[120:123], v[160:163], v[188:191], v[120:123]
	v_mfma_f32_16x16x32_bf16 v[124:127], v[148:151], v[192:195], v[124:127]
	v_mfma_f32_16x16x32_bf16 v[108:111], v[148:151], v[200:203], v[108:111]
	v_mfma_f32_16x16x32_bf16 v[92:95], v[148:151], v[208:211], v[92:95]
	v_mfma_f32_16x16x32_bf16 v[76:79], v[148:151], v[216:219], v[76:79]
	v_mfma_f32_16x16x32_bf16 v[72:75], v[168:171], v[216:219], v[72:75]
	v_mfma_f32_16x16x32_bf16 v[88:91], v[168:171], v[208:211], v[88:91]
	v_mfma_f32_16x16x32_bf16 v[104:107], v[168:171], v[200:203], v[104:107]
	v_mfma_f32_16x16x32_bf16 v[120:123], v[168:171], v[192:195], v[120:123]
	s_setprio 0
	s_setprio 1
	v_mfma_f32_16x16x32_bf16 v[116:119], v[172:175], v[188:191], v[116:119]
	v_mfma_f32_16x16x32_bf16 v[100:103], v[172:175], v[196:199], v[100:103]
	v_mfma_f32_16x16x32_bf16 v[84:87], v[172:175], v[204:207], v[84:87]
	v_mfma_f32_16x16x32_bf16 v[68:71], v[172:175], v[212:215], v[68:71]
	v_mfma_f32_16x16x32_bf16 v[64:67], v[180:183], v[212:215], v[64:67]
	v_mfma_f32_16x16x32_bf16 v[80:83], v[180:183], v[204:207], v[80:83]
	v_mfma_f32_16x16x32_bf16 v[96:99], v[180:183], v[196:199], v[96:99]
	v_mfma_f32_16x16x32_bf16 v[112:115], v[180:183], v[188:191], v[112:115]
	v_mfma_f32_16x16x32_bf16 v[116:119], v[176:179], v[192:195], v[116:119]
	v_mfma_f32_16x16x32_bf16 v[100:103], v[176:179], v[200:203], v[100:103]
	v_mfma_f32_16x16x32_bf16 v[84:87], v[176:179], v[208:211], v[84:87]
	v_mfma_f32_16x16x32_bf16 v[68:71], v[176:179], v[216:219], v[68:71]
	v_mfma_f32_16x16x32_bf16 v[64:67], v[184:187], v[216:219], v[64:67]
	v_mfma_f32_16x16x32_bf16 v[80:83], v[184:187], v[208:211], v[80:83]
	v_mfma_f32_16x16x32_bf16 v[96:99], v[184:187], v[200:203], v[96:99]
	v_mfma_f32_16x16x32_bf16 v[112:115], v[184:187], v[192:195], v[112:115]
	s_barrier
; #define PG8_STAGE(bufoff, gbase, voff) do { _Pragma("unroll") for (int _i = 0; _i < 2; ++_i) \
;         __builtin_amdgcn_global_load_lds((const unsigned*)((const char*)(gbase) + (voff)[_i]), (LAS unsigned*)(lds + (bufoff) + ldsw + _i * 8192), 16, 0, 0); } while (0)
; #define PG8_LDA(dst, b, h) do { _Pragma("unroll") for (int m = 0; m < 4; ++m) _Pragma("unroll") for (int k = 0; k < 2; ++k) dst[m][k] = *(const LAS bf16x8*)(lds + PG8_SA(b, h) + aoff + m * 2048 + k * 1024); } while (0)
; #define PG8_MMA(ai, bj, At, Bt) do { __builtin_amdgcn_s_setprio(1); _Pragma("unroll") for (int m = 0; m < 4; ++m) _Pragma("unroll") for (int n = 0; n < 2; ++n) _Pragma("unroll") for (int k = 0; k < 2; ++k) \
;         acc[ai][bj][m][n] = __builtin_amdgcn_mfma_f32_16x16x32_bf16(Bt[n][k], At[m][k], acc[ai][bj][m][n], 0, 0, 0); __builtin_amdgcn_s_setprio(0); } while (0)
; #define PG8_WAIT_V(n) asm volatile("s_waitcnt vmcnt(" #n ")" ::: "memory")
; #define PG8_WAIT_L(n) asm volatile("s_waitcnt lgkmcnt(" #n ")" ::: "memory")
; #define PG8_BAR __builtin_amdgcn_s_barrier()
; #define PG8_SCHED __builtin_amdgcn_sched_barrier(0)
; template <class Epi, bool ALIGN_EPI>
; __device__ __forceinline__ void gemm_phase(LAS unsigned char* lds, const Gemm g, const StaticOrder& S, const Epi& E) {
;     ...
;             PG8_LDA(At, 1, 1); PG8_STAGE(PG8_SB(1, 0), b3, voffB); PG8_STAGE(PG8_SB(1, 1), b3 + hstepB, voffB); PG8_STAGE(PG8_SA(1, 0), a3, voffA);
;             PG8_WAIT_V(8); PG8_WAIT_L(0); PG8_BAR; PG8_MMA(1, 0, At, B0); PG8_MMA(1, 1, At, B1); PG8_BAR; PG8_SCHED;
;         }
;         if constexpr (ALIGN_EPI) { if (wr == 0) PG8_BAR; }
	s_setprio 0
	s_add_i32 s28, s57, s35
	v_lshl_add_u64 v[164:165], v[164:165], 0, s[12:13]
	s_mov_b32 m0, s28
	ds_read_b128 v[188:191], v158 offset:49152
	ds_read_b128 v[192:195], v158 offset:50176
	ds_read_b128 v[196:199], v158 offset:51200
	ds_read_b128 v[200:203], v158 offset:52224
	ds_read_b128 v[204:207], v158 offset:53248
	ds_read_b128 v[208:211], v158 offset:54272
	ds_read_b128 v[212:215], v158 offset:55296
	ds_read_b128 v[216:219], v158 offset:56320
	global_load_lds_dwordx4 v[164:165], off
	s_add_i32 m0, s28, 0x2000
	s_add_u32 s26, s26, 0x80080
	v_lshl_add_u64 v[164:165], v[220:221], 0, s[12:13]
	s_addc_u32 s27, s27, 0
	s_add_i32 s28, s58, s35
	global_load_lds_dwordx4 v[164:165], off
	v_lshl_add_u64 v[164:165], s[26:27], 0, v[132:133]
	s_mov_b32 m0, s28
	s_nop 0
	global_load_lds_dwordx4 v[164:165], off
	v_lshl_add_u64 v[164:165], s[26:27], 0, v[128:129]
	s_add_i32 m0, s28, 0x2000
	s_nop 0
	global_load_lds_dwordx4 v[164:165], off
	v_lshl_add_u64 v[164:165], v[222:223], 0, s[12:13]
	s_mov_b32 m0, s42
	s_nop 0
	global_load_lds_dwordx4 v[164:165], off
	v_lshl_add_u64 v[164:165], v[224:225], 0, s[12:13]
	s_mov_b32 m0, s43
	s_nop 0
	global_load_lds_dwordx4 v[164:165], off
	s_waitcnt vmcnt(8)
	s_waitcnt lgkmcnt(0)
	s_setprio 1
	s_barrier
	v_mfma_f32_16x16x32_bf16 v[60:63], v[144:147], v[188:191], v[60:63]
	v_mfma_f32_16x16x32_bf16 v[44:47], v[144:147], v[196:199], v[44:47]
	v_mfma_f32_16x16x32_bf16 v[28:31], v[144:147], v[204:207], v[28:31]
	v_mfma_f32_16x16x32_bf16 v[12:15], v[144:147], v[212:215], v[12:15]
	v_mfma_f32_16x16x32_bf16 v[8:11], v[160:163], v[212:215], v[8:11]
	v_mfma_f32_16x16x32_bf16 v[24:27], v[160:163], v[204:207], v[24:27]
	v_mfma_f32_16x16x32_bf16 v[40:43], v[160:163], v[196:199], v[40:43]
	v_mfma_f32_16x16x32_bf16 v[56:59], v[160:163], v[188:191], v[56:59]
	v_mfma_f32_16x16x32_bf16 v[60:63], v[148:151], v[192:195], v[60:63]
	v_mfma_f32_16x16x32_bf16 v[44:47], v[148:151], v[200:203], v[44:47]
	v_mfma_f32_16x16x32_bf16 v[28:31], v[148:151], v[208:211], v[28:31]
	v_mfma_f32_16x16x32_bf16 v[12:15], v[148:151], v[216:219], v[12:15]
	v_mfma_f32_16x16x32_bf16 v[8:11], v[168:171], v[216:219], v[8:11]
	v_mfma_f32_16x16x32_bf16 v[24:27], v[168:171], v[208:211], v[24:27]
	v_mfma_f32_16x16x32_bf16 v[40:43], v[168:171], v[200:203], v[40:43]
	v_mfma_f32_16x16x32_bf16 v[56:59], v[168:171], v[192:195], v[56:59]
	s_setprio 0
	s_setprio 1
	v_mfma_f32_16x16x32_bf16 v[52:55], v[172:175], v[188:191], v[52:55]
	v_mfma_f32_16x16x32_bf16 v[36:39], v[172:175], v[196:199], v[36:39]
	v_mfma_f32_16x16x32_bf16 v[20:23], v[172:175], v[204:207], v[20:23]
	v_mfma_f32_16x16x32_bf16 v[4:7], v[172:175], v[212:215], v[4:7]
	v_mfma_f32_16x16x32_bf16 v[0:3], v[180:183], v[212:215], v[0:3]
	v_mfma_f32_16x16x32_bf16 v[16:19], v[180:183], v[204:207], v[16:19]
	v_mfma_f32_16x16x32_bf16 v[32:35], v[180:183], v[196:199], v[32:35]
	v_mfma_f32_16x16x32_bf16 v[48:51], v[180:183], v[188:191], v[48:51]
	v_mfma_f32_16x16x32_bf16 v[52:55], v[176:179], v[192:195], v[52:55]
	v_mfma_f32_16x16x32_bf16 v[36:39], v[176:179], v[200:203], v[36:39]
	v_mfma_f32_16x16x32_bf16 v[20:23], v[176:179], v[208:211], v[20:23]
	v_mfma_f32_16x16x32_bf16 v[4:7], v[176:179], v[216:219], v[4:7]
	v_mfma_f32_16x16x32_bf16 v[0:3], v[184:187], v[216:219], v[0:3]
	v_mfma_f32_16x16x32_bf16 v[16:19], v[184:187], v[208:211], v[16:19]
	v_mfma_f32_16x16x32_bf16 v[32:35], v[184:187], v[200:203], v[32:35]
	v_mfma_f32_16x16x32_bf16 v[48:51], v[184:187], v[192:195], v[48:51]
	s_barrier
	s_setprio 0
	s_add_i32 s56, s56, 2
	s_add_u32 s54, s54, 0x100
	s_addc_u32 s55, s55, 0
	s_add_u32 s24, s24, 0x100
	s_addc_u32 s25, s25, 0
	s_cmp_gt_u32 s56, 29
	s_cbranch_scc0 .LBB0_1293
	s_and_b64 vcc, exec, s[14:15]
	s_cbranch_vccz .LBB0_1296
	s_barrier

; #define PG8_STAGE(bufoff, gbase, voff) do { _Pragma("unroll") for (int _i = 0; _i < 2; ++_i) \
;         __builtin_amdgcn_global_load_lds((const unsigned*)((const char*)(gbase) + (voff)[_i]), (LAS unsigned*)(lds + (bufoff) + ldsw + _i * 8192), 16, 0, 0); } while (0)
; #define PG8_LDA(dst, b, h) do { _Pragma("unroll") for (int m = 0; m < 4; ++m) _Pragma("unroll") for (int k = 0; k < 2; ++k) dst[m][k] = *(const LAS bf16x8*)(lds + PG8_SA(b, h) + aoff + m * 2048 + k * 1024); } while (0)
; #define PG8_LDB(dst, b, h) do { _Pragma("unroll") for (int n = 0; n < 2; ++n) _Pragma("unroll") for (int k = 0; k < 2; ++k) dst[n][k] = *(const LAS bf16x8*)(lds + PG8_SB(b, h) + boff + n * 2048 + k * 1024); } while (0)
; #define PG8_MMA(ai, bj, At, Bt) do { __builtin_amdgcn_s_setprio(1); _Pragma("unroll") for (int m = 0; m < 4; ++m) _Pragma("unroll") for (int n = 0; n < 2; ++n) _Pragma("unroll") for (int k = 0; k < 2; ++k) \
;         acc[ai][bj][m][n] = __builtin_amdgcn_mfma_f32_16x16x32_bf16(Bt[n][k], At[m][k], acc[ai][bj][m][n], 0, 0, 0); __builtin_amdgcn_s_setprio(0); } while (0)
; #define PG8_WAIT_V(n) asm volatile("s_waitcnt vmcnt(" #n ")" ::: "memory")
; #define PG8_WAIT_L(n) asm volatile("s_waitcnt lgkmcnt(" #n ")" ::: "memory")
; #define PG8_BAR __builtin_amdgcn_s_barrier()
; #define PG8_SCHED __builtin_amdgcn_sched_barrier(0)
; template <class Epi, bool ALIGN_EPI>
; __device__ __forceinline__ void gemm_phase(LAS unsigned char* lds, const Gemm g, const StaticOrder& S, const Epi& E) {
;     ...
;         for (int t = 0; t < nt; t += 2) {
;             const bool last = (t == nt - 2);
;             const char* a1 = cA + (size_t)(t + 1) * kstep;
;             const char* a2 = last ? nA : cA + (size_t)(t + 2) * kstep; const char* b2 = last ? nB : cB + (size_t)(t + 2) * kstep;
;             const char* a3 = a2 + kstep; const char* b3 = b2 + kstep;
;             PG8_LDB(B0, 0, 0); PG8_LDB(B1, 0, 1); PG8_SCHED; PG8_LDA(At, 0, 0); PG8_STAGE(PG8_SA(1, 1), a1 + hstepA, voffA);
;             PG8_WAIT_V(8); PG8_WAIT_L(0); PG8_BAR; PG8_MMA(0, 0, At, B0); PG8_MMA(0, 1, At, B1); PG8_BAR; PG8_SCHED;
;             PG8_LDA(At, 0, 1); PG8_STAGE(PG8_SB(0, 0), b2, voffB); PG8_STAGE(PG8_SB(0, 1), b2 + hstepB, voffB); PG8_STAGE(PG8_SA(0, 0), a2, voffA);
.LBB0_1379:
	ds_read_b128 v[72:75], v163
	ds_read_b128 v[84:87], v163 offset:1024
	ds_read_b128 v[88:91], v163 offset:2048
	ds_read_b128 v[96:99], v163 offset:3072
	ds_read_b128 v[156:159], v164
	ds_read_b128 v[168:171], v164 offset:1024
	ds_read_b128 v[172:175], v164 offset:2048
	ds_read_b128 v[176:179], v164 offset:3072
	s_add_u32 s26, s24, 0x100
	s_addc_u32 s27, s25, 0
	s_cmpk_eq_i32 s57, 0x54
	s_cselect_b32 s31, s5, s27
	s_cselect_b32 s30, s4, s26
	s_cselect_b32 s29, s23, s56
	s_cselect_b32 s28, s22, s55
	v_lshl_add_u64 v[212:213], s[24:25], 0, v[150:151]
	s_add_i32 m0, s37, 0xc000
	ds_read_b128 v[180:183], v165
	ds_read_b128 v[184:187], v165 offset:1024
	ds_read_b128 v[188:191], v165 offset:2048
	ds_read_b128 v[192:195], v165 offset:3072
	ds_read_b128 v[196:199], v165 offset:4096
	ds_read_b128 v[200:203], v165 offset:5120
	ds_read_b128 v[204:207], v165 offset:6144
	ds_read_b128 v[208:211], v165 offset:7168
	global_load_lds_dwordx4 v[212:213], off
	v_lshl_add_u64 v[212:213], s[24:25], 0, v[148:149]
	s_add_i32 m0, s37, 0xe000
	s_nop 0
	global_load_lds_dwordx4 v[212:213], off
	s_waitcnt vmcnt(8)
	s_waitcnt lgkmcnt(0)
	s_setprio 1
	s_barrier
	v_mfma_f32_16x16x32_bf16 v[140:143], v[72:75], v[180:183], v[140:143]
	v_mfma_f32_16x16x32_bf16 v[124:127], v[72:75], v[188:191], v[124:127]
	v_mfma_f32_16x16x32_bf16 v[108:111], v[72:75], v[196:199], v[108:111]
	v_mfma_f32_16x16x32_bf16 v[80:83], v[72:75], v[204:207], v[80:83]
	v_mfma_f32_16x16x32_bf16 v[76:79], v[88:91], v[204:207], v[76:79]
	v_mfma_f32_16x16x32_bf16 v[104:107], v[88:91], v[196:199], v[104:107]
	v_mfma_f32_16x16x32_bf16 v[120:123], v[88:91], v[188:191], v[120:123]
	v_mfma_f32_16x16x32_bf16 v[136:139], v[88:91], v[180:183], v[136:139]
	v_mfma_f32_16x16x32_bf16 v[140:143], v[84:87], v[184:187], v[140:143]
	v_mfma_f32_16x16x32_bf16 v[124:127], v[84:87], v[192:195], v[124:127]
	v_mfma_f32_16x16x32_bf16 v[108:111], v[84:87], v[200:203], v[108:111]
	v_mfma_f32_16x16x32_bf16 v[80:83], v[84:87], v[208:211], v[80:83]
	v_mfma_f32_16x16x32_bf16 v[76:79], v[96:99], v[208:211], v[76:79]
	v_mfma_f32_16x16x32_bf16 v[104:107], v[96:99], v[200:203], v[104:107]
	v_mfma_f32_16x16x32_bf16 v[120:123], v[96:99], v[192:195], v[120:123]
	v_mfma_f32_16x16x32_bf16 v[136:139], v[96:99], v[184:187], v[136:139]
	s_setprio 0
	s_setprio 1
	v_mfma_f32_16x16x32_bf16 v[132:135], v[156:159], v[180:183], v[132:135]
	v_mfma_f32_16x16x32_bf16 v[116:119], v[156:159], v[188:191], v[116:119]
	v_mfma_f32_16x16x32_bf16 v[100:103], v[156:159], v[196:199], v[100:103]
	v_mfma_f32_16x16x32_bf16 v[68:71], v[156:159], v[204:207], v[68:71]
	v_mfma_f32_16x16x32_bf16 v[64:67], v[172:175], v[204:207], v[64:67]
	v_mfma_f32_16x16x32_bf16 v[92:95], v[172:175], v[196:199], v[92:95]
	v_mfma_f32_16x16x32_bf16 v[112:115], v[172:175], v[188:191], v[112:115]
	v_mfma_f32_16x16x32_bf16 v[128:131], v[172:175], v[180:183], v[128:131]
	v_mfma_f32_16x16x32_bf16 v[132:135], v[168:171], v[184:187], v[132:135]
	v_mfma_f32_16x16x32_bf16 v[116:119], v[168:171], v[192:195], v[116:119]
	v_mfma_f32_16x16x32_bf16 v[100:103], v[168:171], v[200:203], v[100:103]
	v_mfma_f32_16x16x32_bf16 v[68:71], v[168:171], v[208:211], v[68:71]
	v_mfma_f32_16x16x32_bf16 v[64:67], v[176:179], v[208:211], v[64:67]
	v_mfma_f32_16x16x32_bf16 v[92:95], v[176:179], v[200:203], v[92:95]
	v_mfma_f32_16x16x32_bf16 v[112:115], v[176:179], v[192:195], v[112:115]
	v_mfma_f32_16x16x32_bf16 v[128:131], v[176:179], v[184:187], v[128:131]
	s_barrier
	s_setprio 0
	s_add_i32 s24, s48, s36
	v_lshl_add_u64 v[212:213], s[28:29], 0, v[144:145]
	s_mov_b32 m0, s24
	ds_read_b128 v[180:183], v165 offset:16384
	ds_read_b128 v[184:187], v165 offset:17408
	ds_read_b128 v[188:191], v165 offset:18432
	ds_read_b128 v[192:195], v165 offset:19456
	ds_read_b128 v[196:199], v165 offset:20480
	ds_read_b128 v[200:203], v165 offset:21504
	ds_read_b128 v[204:207], v165 offset:22528
	ds_read_b128 v[208:211], v165 offset:23552
	global_load_lds_dwordx4 v[212:213], off
	s_add_i32 m0, s24, 0x2000
	s_add_u32 s24, s28, 0x160000
	v_lshl_add_u64 v[214:215], s[28:29], 0, v[146:147]
	s_addc_u32 s25, s29, 0
	s_add_i32 s58, s49, s36
	global_load_lds_dwordx4 v[214:215], off
	v_lshl_add_u64 v[216:217], s[24:25], 0, v[144:145]
	s_mov_b32 m0, s58
	v_lshl_add_u64 v[218:219], s[30:31], 0, v[146:147]
	global_load_lds_dwordx4 v[216:217], off
	v_lshl_add_u64 v[216:217], s[24:25], 0, v[146:147]
	s_add_i32 m0, s58, 0x2000
	s_nop 0
	global_load_lds_dwordx4 v[216:217], off
	v_lshl_add_u64 v[216:217], s[30:31], 0, v[144:145]
	s_mov_b32 m0, s37
	s_nop 0
	global_load_lds_dwordx4 v[216:217], off
	s_mov_b32 m0, s38
	s_nop 0
	global_load_lds_dwordx4 v[218:219], off
	s_waitcnt vmcnt(8)
	s_waitcnt lgkmcnt(0)
	s_setprio 1
	s_barrier
; #define PG8_STAGE(bufoff, gbase, voff) do { _Pragma("unroll") for (int _i = 0; _i < 2; ++_i) \
;         __builtin_amdgcn_global_load_lds((const unsigned*)((const char*)(gbase) + (voff)[_i]), (LAS unsigned*)(lds + (bufoff) + ldsw + _i * 8192), 16, 0, 0); } while (0)
; #define PG8_LDA(dst, b, h) do { _Pragma("unroll") for (int m = 0; m < 4; ++m) _Pragma("unroll") for (int k = 0; k < 2; ++k) dst[m][k] = *(const LAS bf16x8*)(lds + PG8_SA(b, h) + aoff + m * 2048 + k * 1024); } while (0)
; #define PG8_LDB(dst, b, h) do { _Pragma("unroll") for (int n = 0; n < 2; ++n) _Pragma("unroll") for (int k = 0; k < 2; ++k) dst[n][k] = *(const LAS bf16x8*)(lds + PG8_SB(b, h) + boff + n * 2048 + k * 1024); } while (0)
; #define PG8_MMA(ai, bj, At, Bt) do { __builtin_amdgcn_s_setprio(1); _Pragma("unroll") for (int m = 0; m < 4; ++m) _Pragma("unroll") for (int n = 0; n < 2; ++n) _Pragma("unroll") for (int k = 0; k < 2; ++k) \
;         acc[ai][bj][m][n] = __builtin_amdgcn_mfma_f32_16x16x32_bf16(Bt[n][k], At[m][k], acc[ai][bj][m][n], 0, 0, 0); __builtin_amdgcn_s_setprio(0); } while (0)
; #define PG8_WAIT_V(n) asm volatile("s_waitcnt vmcnt(" #n ")" ::: "memory")
; #define PG8_WAIT_L(n) asm volatile("s_waitcnt lgkmcnt(" #n ")" ::: "memory")
; #define PG8_BAR __builtin_amdgcn_s_barrier()
; #define PG8_SCHED __builtin_amdgcn_sched_barrier(0)
; template <class Epi, bool ALIGN_EPI>
; __device__ __forceinline__ void gemm_phase(LAS unsigned char* lds, const Gemm g, const StaticOrder& S, const Epi& E) {
;     ...
;             PG8_WAIT_V(8); PG8_WAIT_L(0); PG8_BAR; PG8_MMA(1, 0, At, B0); PG8_MMA(1, 1, At, B1); PG8_BAR; PG8_SCHED;
;             PG8_LDB(B0, 1, 0); PG8_LDB(B1, 1, 1); PG8_SCHED; PG8_LDA(At, 1, 0); PG8_STAGE(PG8_SA(0, 1), a2 + hstepA, voffA);
;             PG8_WAIT_V(8); PG8_WAIT_L(0); PG8_BAR; PG8_MMA(0, 0, At, B0); PG8_MMA(0, 1, At, B1); PG8_BAR; PG8_SCHED;
	v_mfma_f32_16x16x32_bf16 v[60:63], v[72:75], v[180:183], v[60:63]
	v_mfma_f32_16x16x32_bf16 v[44:47], v[72:75], v[188:191], v[44:47]
	v_mfma_f32_16x16x32_bf16 v[28:31], v[72:75], v[196:199], v[28:31]
	v_mfma_f32_16x16x32_bf16 v[12:15], v[72:75], v[204:207], v[12:15]
	v_mfma_f32_16x16x32_bf16 v[8:11], v[88:91], v[204:207], v[8:11]
	v_mfma_f32_16x16x32_bf16 v[24:27], v[88:91], v[196:199], v[24:27]
	v_mfma_f32_16x16x32_bf16 v[40:43], v[88:91], v[188:191], v[40:43]
	v_mfma_f32_16x16x32_bf16 v[56:59], v[88:91], v[180:183], v[56:59]
	v_mfma_f32_16x16x32_bf16 v[60:63], v[84:87], v[184:187], v[60:63]
	v_mfma_f32_16x16x32_bf16 v[44:47], v[84:87], v[192:195], v[44:47]
	v_mfma_f32_16x16x32_bf16 v[28:31], v[84:87], v[200:203], v[28:31]
	v_mfma_f32_16x16x32_bf16 v[12:15], v[84:87], v[208:211], v[12:15]
	v_mfma_f32_16x16x32_bf16 v[8:11], v[96:99], v[208:211], v[8:11]
	v_mfma_f32_16x16x32_bf16 v[24:27], v[96:99], v[200:203], v[24:27]
	v_mfma_f32_16x16x32_bf16 v[40:43], v[96:99], v[192:195], v[40:43]
	v_mfma_f32_16x16x32_bf16 v[56:59], v[96:99], v[184:187], v[56:59]
	s_setprio 0
	s_setprio 1
	v_mfma_f32_16x16x32_bf16 v[52:55], v[156:159], v[180:183], v[52:55]
	v_mfma_f32_16x16x32_bf16 v[36:39], v[156:159], v[188:191], v[36:39]
	v_mfma_f32_16x16x32_bf16 v[20:23], v[156:159], v[196:199], v[20:23]
	v_mfma_f32_16x16x32_bf16 v[4:7], v[156:159], v[204:207], v[4:7]
	v_mfma_f32_16x16x32_bf16 v[0:3], v[172:175], v[204:207], v[0:3]
	v_mfma_f32_16x16x32_bf16 v[16:19], v[172:175], v[196:199], v[16:19]
	v_mfma_f32_16x16x32_bf16 v[32:35], v[172:175], v[188:191], v[32:35]
	v_mfma_f32_16x16x32_bf16 v[48:51], v[172:175], v[180:183], v[48:51]
	v_mfma_f32_16x16x32_bf16 v[52:55], v[168:171], v[184:187], v[52:55]
	v_mfma_f32_16x16x32_bf16 v[36:39], v[168:171], v[192:195], v[36:39]
	v_mfma_f32_16x16x32_bf16 v[20:23], v[168:171], v[200:203], v[20:23]
	v_mfma_f32_16x16x32_bf16 v[4:7], v[168:171], v[208:211], v[4:7]
	v_mfma_f32_16x16x32_bf16 v[0:3], v[176:179], v[208:211], v[0:3]
	v_mfma_f32_16x16x32_bf16 v[16:19], v[176:179], v[200:203], v[16:19]
	v_mfma_f32_16x16x32_bf16 v[32:35], v[176:179], v[192:195], v[32:35]
	v_mfma_f32_16x16x32_bf16 v[48:51], v[176:179], v[184:187], v[48:51]
	s_barrier
	s_setprio 0
	s_add_i32 s58, 0, 0x18000
	s_add_i32 s59, 0, 0x1c000
	v_add_u32_e32 v96, s58, v161
	v_add_u32_e32 v176, s59, v161
	ds_read_b128 v[72:75], v96
	ds_read_b128 v[84:87], v96 offset:1024
	ds_read_b128 v[88:91], v96 offset:2048
	ds_read_b128 v[96:99], v96 offset:3072
	ds_read_b128 v[156:159], v176
	ds_read_b128 v[168:171], v176 offset:1024
	ds_read_b128 v[172:175], v176 offset:2048
	ds_read_b128 v[176:179], v176 offset:3072
	s_add_u32 s24, s30, 0x160000
	s_addc_u32 s25, s31, 0
	s_mov_b32 m0, s39
	v_lshl_add_u64 v[220:221], s[24:25], 0, v[144:145]
	ds_read_b128 v[180:183], v165 offset:32768
	ds_read_b128 v[184:187], v165 offset:33792
	ds_read_b128 v[188:191], v165 offset:34816
	ds_read_b128 v[192:195], v165 offset:35840
	ds_read_b128 v[196:199], v165 offset:36864
	ds_read_b128 v[200:203], v165 offset:37888
	ds_read_b128 v[204:207], v165 offset:38912
	ds_read_b128 v[208:211], v165 offset:39936
	global_load_lds_dwordx4 v[220:221], off
	v_lshl_add_u64 v[220:221], s[24:25], 0, v[146:147]
	s_mov_b32 m0, s40
	s_nop 0
	global_load_lds_dwordx4 v[220:221], off
	s_waitcnt vmcnt(8)
	s_waitcnt lgkmcnt(0)
	s_setprio 1
	s_barrier
	v_mfma_f32_16x16x32_bf16 v[140:143], v[72:75], v[180:183], v[140:143]
	v_mfma_f32_16x16x32_bf16 v[124:127], v[72:75], v[188:191], v[124:127]
	v_mfma_f32_16x16x32_bf16 v[108:111], v[72:75], v[196:199], v[108:111]
	v_mfma_f32_16x16x32_bf16 v[80:83], v[72:75], v[204:207], v[80:83]
	v_mfma_f32_16x16x32_bf16 v[76:79], v[88:91], v[204:207], v[76:79]
	v_mfma_f32_16x16x32_bf16 v[104:107], v[88:91], v[196:199], v[104:107]
	v_mfma_f32_16x16x32_bf16 v[120:123], v[88:91], v[188:191], v[120:123]
	v_mfma_f32_16x16x32_bf16 v[136:139], v[88:91], v[180:183], v[136:139]
	v_mfma_f32_16x16x32_bf16 v[140:143], v[84:87], v[184:187], v[140:143]
	v_mfma_f32_16x16x32_bf16 v[124:127], v[84:87], v[192:195], v[124:127]
	v_mfma_f32_16x16x32_bf16 v[108:111], v[84:87], v[200:203], v[108:111]
	v_mfma_f32_16x16x32_bf16 v[80:83], v[84:87], v[208:211], v[80:83]
	v_mfma_f32_16x16x32_bf16 v[76:79], v[96:99], v[208:211], v[76:79]
	v_mfma_f32_16x16x32_bf16 v[104:107], v[96:99], v[200:203], v[104:107]
	v_mfma_f32_16x16x32_bf16 v[120:123], v[96:99], v[192:195], v[120:123]
	v_mfma_f32_16x16x32_bf16 v[136:139], v[96:99], v[184:187], v[136:139]
	s_setprio 0
	s_setprio 1
	v_mfma_f32_16x16x32_bf16 v[132:135], v[156:159], v[180:183], v[132:135]
	v_mfma_f32_16x16x32_bf16 v[116:119], v[156:159], v[188:191], v[116:119]
	v_mfma_f32_16x16x32_bf16 v[100:103], v[156:159], v[196:199], v[100:103]
	v_mfma_f32_16x16x32_bf16 v[68:71], v[156:159], v[204:207], v[68:71]
	v_mfma_f32_16x16x32_bf16 v[64:67], v[172:175], v[204:207], v[64:67]
	v_mfma_f32_16x16x32_bf16 v[92:95], v[172:175], v[196:199], v[92:95]
	v_mfma_f32_16x16x32_bf16 v[112:115], v[172:175], v[188:191], v[112:115]
	v_mfma_f32_16x16x32_bf16 v[128:131], v[172:175], v[180:183], v[128:131]
	v_mfma_f32_16x16x32_bf16 v[132:135], v[168:171], v[184:187], v[132:135]
	v_mfma_f32_16x16x32_bf16 v[116:119], v[168:171], v[192:195], v[116:119]
	v_mfma_f32_16x16x32_bf16 v[100:103], v[168:171], v[200:203], v[100:103]
	v_mfma_f32_16x16x32_bf16 v[68:71], v[168:171], v[208:211], v[68:71]
	v_mfma_f32_16x16x32_bf16 v[64:67], v[176:179], v[208:211], v[64:67]
	v_mfma_f32_16x16x32_bf16 v[92:95], v[176:179], v[200:203], v[92:95]
	v_mfma_f32_16x16x32_bf16 v[112:115], v[176:179], v[192:195], v[112:115]
	v_mfma_f32_16x16x32_bf16 v[128:131], v[176:179], v[184:187], v[128:131]
	s_barrier
; #define PG8_STAGE(bufoff, gbase, voff) do { _Pragma("unroll") for (int _i = 0; _i < 2; ++_i) \
;         __builtin_amdgcn_global_load_lds((const unsigned*)((const char*)(gbase) + (voff)[_i]), (LAS unsigned*)(lds + (bufoff) + ldsw + _i * 8192), 16, 0, 0); } while (0)
; #define PG8_LDA(dst, b, h) do { _Pragma("unroll") for (int m = 0; m < 4; ++m) _Pragma("unroll") for (int k = 0; k < 2; ++k) dst[m][k] = *(const LAS bf16x8*)(lds + PG8_SA(b, h) + aoff + m * 2048 + k * 1024); } while (0)
; #define PG8_MMA(ai, bj, At, Bt) do { __builtin_amdgcn_s_setprio(1); _Pragma("unroll") for (int m = 0; m < 4; ++m) _Pragma("unroll") for (int n = 0; n < 2; ++n) _Pragma("unroll") for (int k = 0; k < 2; ++k) \
;         acc[ai][bj][m][n] = __builtin_amdgcn_mfma_f32_16x16x32_bf16(Bt[n][k], At[m][k], acc[ai][bj][m][n], 0, 0, 0); __builtin_amdgcn_s_setprio(0); } while (0)
; #define PG8_WAIT_V(n) asm volatile("s_waitcnt vmcnt(" #n ")" ::: "memory")
; #define PG8_WAIT_L(n) asm volatile("s_waitcnt lgkmcnt(" #n ")" ::: "memory")
; #define PG8_BAR __builtin_amdgcn_s_barrier()
; #define PG8_SCHED __builtin_amdgcn_sched_barrier(0)
; template <class Epi, bool ALIGN_EPI>
; __device__ __forceinline__ void gemm_phase(LAS unsigned char* lds, const Gemm g, const StaticOrder& S, const Epi& E) {
;     ...
;             PG8_LDA(At, 1, 1); PG8_STAGE(PG8_SB(1, 0), b3, voffB); PG8_STAGE(PG8_SB(1, 1), b3 + hstepB, voffB); PG8_STAGE(PG8_SA(1, 0), a3, voffA);
;             PG8_WAIT_V(8); PG8_WAIT_L(0); PG8_BAR; PG8_MMA(1, 0, At, B0); PG8_MMA(1, 1, At, B1); PG8_BAR; PG8_SCHED;
;         }
;         if constexpr (ALIGN_EPI) { if (wr == 0) PG8_BAR; }
	s_setprio 0
	s_add_i32 s24, s58, s36
	v_lshl_add_u64 v[212:213], v[212:213], 0, s[18:19]
	s_mov_b32 m0, s24
	ds_read_b128 v[180:183], v165 offset:49152
	ds_read_b128 v[184:187], v165 offset:50176
	ds_read_b128 v[188:191], v165 offset:51200
	ds_read_b128 v[192:195], v165 offset:52224
	ds_read_b128 v[196:199], v165 offset:53248
	ds_read_b128 v[200:203], v165 offset:54272
	ds_read_b128 v[204:207], v165 offset:55296
	ds_read_b128 v[208:211], v165 offset:56320
	global_load_lds_dwordx4 v[212:213], off
	s_add_i32 m0, s24, 0x2000
	s_add_u32 s24, s28, 0x160080
	v_lshl_add_u64 v[212:213], v[214:215], 0, s[18:19]
	s_addc_u32 s25, s29, 0
	s_add_i32 s28, s59, s36
	global_load_lds_dwordx4 v[212:213], off
	v_lshl_add_u64 v[212:213], s[24:25], 0, v[144:145]
	s_mov_b32 m0, s28
	s_nop 0
	global_load_lds_dwordx4 v[212:213], off
	v_lshl_add_u64 v[212:213], s[24:25], 0, v[146:147]
	s_add_i32 m0, s28, 0x2000
	s_nop 0
	global_load_lds_dwordx4 v[212:213], off
	v_lshl_add_u64 v[212:213], v[216:217], 0, s[18:19]
	s_mov_b32 m0, s42
	s_nop 0
	global_load_lds_dwordx4 v[212:213], off
	v_lshl_add_u64 v[212:213], v[218:219], 0, s[18:19]
	s_mov_b32 m0, s43
	s_nop 0
	global_load_lds_dwordx4 v[212:213], off
	s_waitcnt vmcnt(8)
	s_waitcnt lgkmcnt(0)
	s_setprio 1
	s_barrier
	v_mfma_f32_16x16x32_bf16 v[60:63], v[72:75], v[180:183], v[60:63]
	v_mfma_f32_16x16x32_bf16 v[44:47], v[72:75], v[188:191], v[44:47]
	v_mfma_f32_16x16x32_bf16 v[28:31], v[72:75], v[196:199], v[28:31]
	v_mfma_f32_16x16x32_bf16 v[12:15], v[72:75], v[204:207], v[12:15]
	v_mfma_f32_16x16x32_bf16 v[8:11], v[88:91], v[204:207], v[8:11]
	v_mfma_f32_16x16x32_bf16 v[24:27], v[88:91], v[196:199], v[24:27]
	v_mfma_f32_16x16x32_bf16 v[40:43], v[88:91], v[188:191], v[40:43]
	v_mfma_f32_16x16x32_bf16 v[56:59], v[88:91], v[180:183], v[56:59]
	v_mfma_f32_16x16x32_bf16 v[60:63], v[84:87], v[184:187], v[60:63]
	v_mfma_f32_16x16x32_bf16 v[44:47], v[84:87], v[192:195], v[44:47]
	v_mfma_f32_16x16x32_bf16 v[28:31], v[84:87], v[200:203], v[28:31]
	v_mfma_f32_16x16x32_bf16 v[12:15], v[84:87], v[208:211], v[12:15]
	v_mfma_f32_16x16x32_bf16 v[8:11], v[96:99], v[208:211], v[8:11]
	v_mfma_f32_16x16x32_bf16 v[24:27], v[96:99], v[200:203], v[24:27]
	v_mfma_f32_16x16x32_bf16 v[40:43], v[96:99], v[192:195], v[40:43]
	v_mfma_f32_16x16x32_bf16 v[56:59], v[96:99], v[184:187], v[56:59]
	s_setprio 0
	s_setprio 1
	v_mfma_f32_16x16x32_bf16 v[52:55], v[156:159], v[180:183], v[52:55]
	v_mfma_f32_16x16x32_bf16 v[36:39], v[156:159], v[188:191], v[36:39]
	v_mfma_f32_16x16x32_bf16 v[20:23], v[156:159], v[196:199], v[20:23]
	v_mfma_f32_16x16x32_bf16 v[4:7], v[156:159], v[204:207], v[4:7]
	v_mfma_f32_16x16x32_bf16 v[0:3], v[172:175], v[204:207], v[0:3]
	v_mfma_f32_16x16x32_bf16 v[16:19], v[172:175], v[196:199], v[16:19]
	v_mfma_f32_16x16x32_bf16 v[32:35], v[172:175], v[188:191], v[32:35]
	v_mfma_f32_16x16x32_bf16 v[48:51], v[172:175], v[180:183], v[48:51]
	v_mfma_f32_16x16x32_bf16 v[52:55], v[168:171], v[184:187], v[52:55]
	v_mfma_f32_16x16x32_bf16 v[36:39], v[168:171], v[192:195], v[36:39]
	v_mfma_f32_16x16x32_bf16 v[20:23], v[168:171], v[200:203], v[20:23]
	v_mfma_f32_16x16x32_bf16 v[4:7], v[168:171], v[208:211], v[4:7]
	v_mfma_f32_16x16x32_bf16 v[0:3], v[176:179], v[208:211], v[0:3]
	v_mfma_f32_16x16x32_bf16 v[16:19], v[176:179], v[200:203], v[16:19]
	v_mfma_f32_16x16x32_bf16 v[32:35], v[176:179], v[192:195], v[32:35]
	v_mfma_f32_16x16x32_bf16 v[48:51], v[176:179], v[184:187], v[48:51]
	s_barrier
	s_setprio 0
	s_add_i32 s57, s57, 2
	s_add_u32 s55, s55, 0x100
	s_addc_u32 s56, s56, 0
	s_cmpk_gt_u32 s57, 0x55
	s_mov_b64 s[24:25], s[26:27]
	s_cbranch_scc0 .LBB0_1379
	s_and_b64 vcc, exec, s[20:21]
	s_cbranch_vccz .LBB0_1382
	s_barrier
